# strategy: code placement (asm guide 9.3) - v42 + every GEMM K-loop compute segment (first MFMA after the opening barrier, loops and peeled copies) pinned to 0 mod 8 bytes by one s_nop 0 ahead of the l
# baseline (speedup 1.0000x reference)
.LBB0_161:
	s_ashr_i32 s23, s22, 31
	s_lshl_b64 s[8:9], s[22:23], 20
	v_readlane_b32 s20, v254, 38
	v_readlane_b32 s21, v254, 39
	s_add_u32 s8, s20, s8
	s_addc_u32 s9, s21, s9
	s_and_b64 s[20:21], s[40:41], exec
	s_cselect_b32 s13, s9, s43
	s_cselect_b32 s20, s8, s42
	s_ashr_i32 s19, s18, 31
	s_lshl_b64 s[28:29], s[18:19], 20
	v_readlane_b32 s30, v254, 22
	v_readlane_b32 s31, v254, 23
	s_add_u32 s28, s30, s28
	s_addc_u32 s29, s31, s29
	s_and_b64 s[30:31], s[40:41], exec
	s_cselect_b32 s19, s29, s45
	s_cselect_b32 s21, s28, s44
	s_add_u32 s42, s42, 0x80080
	s_addc_u32 s43, s43, 0
	s_add_u32 s23, s44, 0x100
	s_addc_u32 s25, s45, 0
	s_mov_b32 s30, -2
	v_readlane_b32 s52, v255, 20
	v_readlane_b32 s53, v255, 21
	v_readlane_b32 s72, v255, 22
	v_readlane_b32 s73, v255, 23
	s_mov_b64 s[74:75], 0x80
	s_add_u32 s31, s42, 0xfff80080
	s_addc_u32 s44, s43, -1
	s_add_i32 s47, 0, 0x10000
	s_cmp_eq_u32 s30, 28
	s_cselect_b32 s49, s13, s44
	s_cselect_b32 s48, s20, s31
	ds_read_b128 v[144:147], v1
	ds_read_b128 v[148:151], v141
	s_cselect_b32 s45, s19, s25
	s_cselect_b32 s44, s21, s23
	s_add_i32 s31, 0, 0x14000
	ds_read_b128 v[152:155], v1 offset:2048
	ds_read_b128 v[156:159], v141 offset:2048
	ds_read_b128 v[160:163], v1 offset:16384
	ds_read_b128 v[164:167], v141 offset:16384
	ds_read_b128 v[168:171], v1 offset:18432
	ds_read_b128 v[172:175], v141 offset:18432
	s_add_i32 m0, s34, 0xc000
	ds_read_b128 v[176:179], v142
	ds_read_b128 v[184:187], v142 offset:2048
	ds_read_b128 v[188:191], v143
	ds_read_b128 v[192:195], v143 offset:2048
	ds_read_b128 v[196:199], v142 offset:4096
	ds_read_b128 v[200:203], v142 offset:6144
	ds_read_b128 v[204:207], v143 offset:4096
	ds_read_b128 v[208:211], v143 offset:6144
	global_load_lds_dwordx4 v138, s[42:43]
	s_add_i32 m0, s34, 0xe000
	s_nop 0
	global_load_lds_dwordx4 v134, s[42:43]
	s_nop 0
	s_waitcnt vmcnt(8)
	s_waitcnt lgkmcnt(0)
	s_barrier
	v_mfma_f32_16x16x32_bf16 v[128:131], v[144:147], v[176:179], 0
	v_mfma_f32_16x16x32_bf16 v[124:127], v[152:155], v[176:179], 0
	v_mfma_f32_16x16x32_bf16 v[112:115], v[144:147], v[184:187], 0
	v_mfma_f32_16x16x32_bf16 v[108:111], v[152:155], v[184:187], 0
	v_mfma_f32_16x16x32_bf16 v[96:99], v[144:147], v[196:199], 0
	v_mfma_f32_16x16x32_bf16 v[92:95], v[152:155], v[196:199], 0
	v_mfma_f32_16x16x32_bf16 v[80:83], v[144:147], v[200:203], 0
	v_mfma_f32_16x16x32_bf16 v[76:79], v[152:155], v[200:203], 0
	v_mfma_f32_16x16x32_bf16 v[128:131], v[148:151], v[188:191], v[128:131]
	v_mfma_f32_16x16x32_bf16 v[124:127], v[156:159], v[188:191], v[124:127]
	v_mfma_f32_16x16x32_bf16 v[112:115], v[148:151], v[192:195], v[112:115]
	v_mfma_f32_16x16x32_bf16 v[108:111], v[156:159], v[192:195], v[108:111]
	v_mfma_f32_16x16x32_bf16 v[96:99], v[148:151], v[204:207], v[96:99]
	v_mfma_f32_16x16x32_bf16 v[92:95], v[156:159], v[204:207], v[92:95]
	v_mfma_f32_16x16x32_bf16 v[80:83], v[148:151], v[208:211], v[80:83]
	v_mfma_f32_16x16x32_bf16 v[76:79], v[156:159], v[208:211], v[76:79]
	v_mfma_f32_16x16x32_bf16 v[120:123], v[160:163], v[176:179], 0
	v_mfma_f32_16x16x32_bf16 v[116:119], v[168:171], v[176:179], 0
	v_mfma_f32_16x16x32_bf16 v[104:107], v[160:163], v[184:187], 0
	v_mfma_f32_16x16x32_bf16 v[100:103], v[168:171], v[184:187], 0
	v_mfma_f32_16x16x32_bf16 v[88:91], v[160:163], v[196:199], 0
	v_mfma_f32_16x16x32_bf16 v[84:87], v[168:171], v[196:199], 0
	v_mfma_f32_16x16x32_bf16 v[72:75], v[160:163], v[200:203], 0
	v_mfma_f32_16x16x32_bf16 v[68:71], v[168:171], v[200:203], 0
	v_mfma_f32_16x16x32_bf16 v[120:123], v[164:167], v[188:191], v[120:123]
	v_mfma_f32_16x16x32_bf16 v[116:119], v[172:175], v[188:191], v[116:119]
	v_mfma_f32_16x16x32_bf16 v[104:107], v[164:167], v[192:195], v[104:107]
	v_mfma_f32_16x16x32_bf16 v[100:103], v[172:175], v[192:195], v[100:103]
	v_mfma_f32_16x16x32_bf16 v[88:91], v[164:167], v[204:207], v[88:91]
	v_mfma_f32_16x16x32_bf16 v[84:87], v[172:175], v[204:207], v[84:87]
	v_mfma_f32_16x16x32_bf16 v[72:75], v[164:167], v[208:211], v[72:75]
	v_mfma_f32_16x16x32_bf16 v[68:71], v[172:175], v[208:211], v[68:71]
	s_barrier
	s_add_i32 s47, s47, s33
	s_mov_b32 m0, s47
	ds_read_b128 v[176:179], v142 offset:16384
	ds_read_b128 v[184:187], v142 offset:18432
	ds_read_b128 v[188:191], v143 offset:16384
	ds_read_b128 v[192:195], v143 offset:18432
	ds_read_b128 v[196:199], v142 offset:20480
	ds_read_b128 v[200:203], v142 offset:22528
	ds_read_b128 v[204:207], v143 offset:20480
	ds_read_b128 v[208:211], v143 offset:22528
	global_load_lds_dwordx4 v136, s[44:45]
	s_add_i32 m0, s47, 0x2000
	s_add_u32 s50, s44, 0x80000
	s_addc_u32 s51, s45, 0
	s_add_i32 s31, s31, s33
	global_load_lds_dwordx4 v132, s[44:45]
	s_mov_b32 m0, s31
	s_nop 0
	global_load_lds_dwordx4 v136, s[50:51]
	s_add_i32 m0, s31, 0x2000
	s_nop 0
	global_load_lds_dwordx4 v132, s[50:51]
	s_mov_b32 m0, s34
	s_nop 0
	global_load_lds_dwordx4 v138, s[48:49]
	s_mov_b32 m0, s35
	s_nop 0
	global_load_lds_dwordx4 v134, s[48:49]
	s_nop 0
	s_waitcnt vmcnt(8)
	s_waitcnt lgkmcnt(0)
	s_barrier
	v_mfma_f32_16x16x32_bf16 v[64:67], v[144:147], v[176:179], 0
	v_mfma_f32_16x16x32_bf16 v[60:63], v[152:155], v[176:179], 0
	v_mfma_f32_16x16x32_bf16 v[48:51], v[144:147], v[184:187], 0
	v_mfma_f32_16x16x32_bf16 v[44:47], v[152:155], v[184:187], 0
	v_mfma_f32_16x16x32_bf16 v[30:33], v[144:147], v[196:199], 0
	v_mfma_f32_16x16x32_bf16 v[26:29], v[152:155], v[196:199], 0
	v_mfma_f32_16x16x32_bf16 v[14:17], v[144:147], v[200:203], 0
	v_mfma_f32_16x16x32_bf16 v[10:13], v[152:155], v[200:203], 0
	v_mfma_f32_16x16x32_bf16 v[64:67], v[148:151], v[188:191], v[64:67]
	v_mfma_f32_16x16x32_bf16 v[60:63], v[156:159], v[188:191], v[60:63]
	v_mfma_f32_16x16x32_bf16 v[48:51], v[148:151], v[192:195], v[48:51]
	v_mfma_f32_16x16x32_bf16 v[44:47], v[156:159], v[192:195], v[44:47]
	v_mfma_f32_16x16x32_bf16 v[30:33], v[148:151], v[204:207], v[30:33]
	v_mfma_f32_16x16x32_bf16 v[26:29], v[156:159], v[204:207], v[26:29]
	v_mfma_f32_16x16x32_bf16 v[14:17], v[148:151], v[208:211], v[14:17]
	v_mfma_f32_16x16x32_bf16 v[10:13], v[156:159], v[208:211], v[10:13]
	v_mfma_f32_16x16x32_bf16 v[56:59], v[160:163], v[176:179], 0
	v_mfma_f32_16x16x32_bf16 v[52:55], v[168:171], v[176:179], 0
	v_mfma_f32_16x16x32_bf16 v[40:43], v[160:163], v[184:187], 0
	v_mfma_f32_16x16x32_bf16 v[36:39], v[168:171], v[184:187], 0
	v_mfma_f32_16x16x32_bf16 v[22:25], v[160:163], v[196:199], 0
	v_mfma_f32_16x16x32_bf16 v[18:21], v[168:171], v[196:199], 0
	v_mfma_f32_16x16x32_bf16 v[6:9], v[160:163], v[200:203], 0
	v_mfma_f32_16x16x32_bf16 v[2:5], v[168:171], v[200:203], 0
	v_mfma_f32_16x16x32_bf16 v[56:59], v[164:167], v[188:191], v[56:59]
	v_mfma_f32_16x16x32_bf16 v[52:55], v[172:175], v[188:191], v[52:55]
	v_mfma_f32_16x16x32_bf16 v[40:43], v[164:167], v[192:195], v[40:43]
	v_mfma_f32_16x16x32_bf16 v[36:39], v[172:175], v[192:195], v[36:39]
	v_mfma_f32_16x16x32_bf16 v[22:25], v[164:167], v[204:207], v[22:25]
	v_mfma_f32_16x16x32_bf16 v[18:21], v[172:175], v[204:207], v[18:21]
	v_mfma_f32_16x16x32_bf16 v[6:9], v[164:167], v[208:211], v[6:9]
	v_mfma_f32_16x16x32_bf16 v[2:5], v[172:175], v[208:211], v[2:5]
	s_barrier
	s_add_i32 s31, 0, 0x18000
	ds_read_b128 v[144:147], v1 offset:32768
	ds_read_b128 v[148:151], v141 offset:32768
	s_add_i32 s47, 0, 0x1c000
	ds_read_b128 v[152:155], v1 offset:34816
	ds_read_b128 v[156:159], v141 offset:34816
	ds_read_b128 v[160:163], v1 offset:49152
	ds_read_b128 v[164:167], v141 offset:49152
	ds_read_b128 v[168:171], v1 offset:51200
	ds_read_b128 v[172:175], v141 offset:51200
	s_mov_b64 s[100:101], s[48:49]
	s_add_u32 s48, s48, 0x80000
	s_addc_u32 s49, s49, 0
	s_mov_b32 m0, s54
	ds_read_b128 v[176:179], v142 offset:32768
	ds_read_b128 v[184:187], v142 offset:34816
	ds_read_b128 v[188:191], v143 offset:32768
	ds_read_b128 v[192:195], v143 offset:34816
	ds_read_b128 v[196:199], v142 offset:36864
	ds_read_b128 v[200:203], v142 offset:38912
	ds_read_b128 v[204:207], v143 offset:36864
	ds_read_b128 v[208:211], v143 offset:38912
	global_load_lds_dwordx4 v138, s[48:49]
	s_mov_b32 m0, s55
	s_nop 0
	global_load_lds_dwordx4 v134, s[48:49]
	s_nop 0
	s_waitcnt vmcnt(8)
	s_waitcnt lgkmcnt(0)
	s_barrier
	v_mfma_f32_16x16x32_bf16 v[128:131], v[144:147], v[176:179], v[128:131]
	v_mfma_f32_16x16x32_bf16 v[124:127], v[152:155], v[176:179], v[124:127]
	v_mfma_f32_16x16x32_bf16 v[112:115], v[144:147], v[184:187], v[112:115]
	v_mfma_f32_16x16x32_bf16 v[108:111], v[152:155], v[184:187], v[108:111]
	v_mfma_f32_16x16x32_bf16 v[96:99], v[144:147], v[196:199], v[96:99]
	v_mfma_f32_16x16x32_bf16 v[92:95], v[152:155], v[196:199], v[92:95]
	v_mfma_f32_16x16x32_bf16 v[80:83], v[144:147], v[200:203], v[80:83]
	v_mfma_f32_16x16x32_bf16 v[76:79], v[152:155], v[200:203], v[76:79]
	v_mfma_f32_16x16x32_bf16 v[128:131], v[148:151], v[188:191], v[128:131]
	v_mfma_f32_16x16x32_bf16 v[124:127], v[156:159], v[188:191], v[124:127]
	v_mfma_f32_16x16x32_bf16 v[112:115], v[148:151], v[192:195], v[112:115]
	v_mfma_f32_16x16x32_bf16 v[108:111], v[156:159], v[192:195], v[108:111]
	v_mfma_f32_16x16x32_bf16 v[96:99], v[148:151], v[204:207], v[96:99]
	v_mfma_f32_16x16x32_bf16 v[92:95], v[156:159], v[204:207], v[92:95]
	v_mfma_f32_16x16x32_bf16 v[80:83], v[148:151], v[208:211], v[80:83]
	v_mfma_f32_16x16x32_bf16 v[76:79], v[156:159], v[208:211], v[76:79]
	v_mfma_f32_16x16x32_bf16 v[120:123], v[160:163], v[176:179], v[120:123]
	v_mfma_f32_16x16x32_bf16 v[116:119], v[168:171], v[176:179], v[116:119]
	v_mfma_f32_16x16x32_bf16 v[104:107], v[160:163], v[184:187], v[104:107]
	v_mfma_f32_16x16x32_bf16 v[100:103], v[168:171], v[184:187], v[100:103]
	v_mfma_f32_16x16x32_bf16 v[88:91], v[160:163], v[196:199], v[88:91]
	v_mfma_f32_16x16x32_bf16 v[84:87], v[168:171], v[196:199], v[84:87]
	v_mfma_f32_16x16x32_bf16 v[72:75], v[160:163], v[200:203], v[72:75]
	v_mfma_f32_16x16x32_bf16 v[68:71], v[168:171], v[200:203], v[68:71]
	v_mfma_f32_16x16x32_bf16 v[120:123], v[164:167], v[188:191], v[120:123]
	v_mfma_f32_16x16x32_bf16 v[116:119], v[172:175], v[188:191], v[116:119]
	v_mfma_f32_16x16x32_bf16 v[104:107], v[164:167], v[192:195], v[104:107]
	v_mfma_f32_16x16x32_bf16 v[100:103], v[172:175], v[192:195], v[100:103]
	v_mfma_f32_16x16x32_bf16 v[88:91], v[164:167], v[204:207], v[88:91]
	v_mfma_f32_16x16x32_bf16 v[84:87], v[172:175], v[204:207], v[84:87]
	v_mfma_f32_16x16x32_bf16 v[72:75], v[164:167], v[208:211], v[72:75]
	v_mfma_f32_16x16x32_bf16 v[68:71], v[172:175], v[208:211], v[68:71]
	s_barrier
	s_add_i32 s31, s31, s33
	s_add_i32 m0, s31, 0xffffff80
	ds_read_b128 v[176:179], v142 offset:49152
	ds_read_b128 v[184:187], v142 offset:51200
	ds_read_b128 v[188:191], v143 offset:49152
	ds_read_b128 v[192:195], v143 offset:51200
	ds_read_b128 v[196:199], v142 offset:53248
	ds_read_b128 v[200:203], v142 offset:55296
	ds_read_b128 v[204:207], v143 offset:53248
	ds_read_b128 v[208:211], v143 offset:55296
	global_load_lds_dwordx4 v136, s[44:45] offset:128
	s_add_i32 m0, s31, 0x1f80
	s_mov_b64 s[98:99], s[44:45]
	s_add_u32 s44, s44, 0x80080
	s_addc_u32 s45, s45, 0
	s_add_i32 s31, s47, s33
	global_load_lds_dwordx4 v132, s[98:99] offset:128
	s_mov_b32 m0, s31
	s_nop 0
	global_load_lds_dwordx4 v136, s[44:45]
	s_add_i32 m0, s31, 0x2000
	s_nop 0
	global_load_lds_dwordx4 v132, s[44:45]
	s_add_i32 m0, s56, 0xffffff80
	s_nop 0
	global_load_lds_dwordx4 v138, s[100:101] offset:128
	s_add_i32 m0, s57, 0xffffff80
	s_nop 0
	global_load_lds_dwordx4 v134, s[100:101] offset:128
	s_nop 0
	s_waitcnt vmcnt(8)
	s_waitcnt lgkmcnt(0)
	s_barrier
	v_mfma_f32_16x16x32_bf16 v[64:67], v[144:147], v[176:179], v[64:67]
	v_mfma_f32_16x16x32_bf16 v[60:63], v[152:155], v[176:179], v[60:63]
	v_mfma_f32_16x16x32_bf16 v[48:51], v[144:147], v[184:187], v[48:51]
	v_mfma_f32_16x16x32_bf16 v[44:47], v[152:155], v[184:187], v[44:47]
	v_mfma_f32_16x16x32_bf16 v[30:33], v[144:147], v[196:199], v[30:33]
	v_mfma_f32_16x16x32_bf16 v[26:29], v[152:155], v[196:199], v[26:29]
	v_mfma_f32_16x16x32_bf16 v[14:17], v[144:147], v[200:203], v[14:17]
	v_mfma_f32_16x16x32_bf16 v[10:13], v[152:155], v[200:203], v[10:13]
	v_mfma_f32_16x16x32_bf16 v[64:67], v[148:151], v[188:191], v[64:67]
	v_mfma_f32_16x16x32_bf16 v[60:63], v[156:159], v[188:191], v[60:63]
	v_mfma_f32_16x16x32_bf16 v[48:51], v[148:151], v[192:195], v[48:51]
	v_mfma_f32_16x16x32_bf16 v[44:47], v[156:159], v[192:195], v[44:47]
	v_mfma_f32_16x16x32_bf16 v[30:33], v[148:151], v[204:207], v[30:33]
	v_mfma_f32_16x16x32_bf16 v[26:29], v[156:159], v[204:207], v[26:29]
	v_mfma_f32_16x16x32_bf16 v[14:17], v[148:151], v[208:211], v[14:17]
	v_mfma_f32_16x16x32_bf16 v[10:13], v[156:159], v[208:211], v[10:13]
	v_mfma_f32_16x16x32_bf16 v[56:59], v[160:163], v[176:179], v[56:59]
	v_mfma_f32_16x16x32_bf16 v[52:55], v[168:171], v[176:179], v[52:55]
	v_mfma_f32_16x16x32_bf16 v[40:43], v[160:163], v[184:187], v[40:43]
	v_mfma_f32_16x16x32_bf16 v[36:39], v[168:171], v[184:187], v[36:39]
	v_mfma_f32_16x16x32_bf16 v[22:25], v[160:163], v[196:199], v[22:25]
	v_mfma_f32_16x16x32_bf16 v[18:21], v[168:171], v[196:199], v[18:21]
	v_mfma_f32_16x16x32_bf16 v[6:9], v[160:163], v[200:203], v[6:9]
	v_mfma_f32_16x16x32_bf16 v[2:5], v[168:171], v[200:203], v[2:5]
	v_mfma_f32_16x16x32_bf16 v[56:59], v[164:167], v[188:191], v[56:59]
	v_mfma_f32_16x16x32_bf16 v[52:55], v[172:175], v[188:191], v[52:55]
	v_mfma_f32_16x16x32_bf16 v[40:43], v[164:167], v[192:195], v[40:43]
	v_mfma_f32_16x16x32_bf16 v[36:39], v[172:175], v[192:195], v[36:39]
	v_mfma_f32_16x16x32_bf16 v[22:25], v[164:167], v[204:207], v[22:25]
	v_mfma_f32_16x16x32_bf16 v[18:21], v[172:175], v[204:207], v[18:21]
	v_mfma_f32_16x16x32_bf16 v[6:9], v[164:167], v[208:211], v[6:9]
	v_mfma_f32_16x16x32_bf16 v[2:5], v[172:175], v[208:211], v[2:5]
	s_barrier
	s_add_i32 s30, s30, 2
	s_add_u32 s42, s42, 0x100
	s_addc_u32 s43, s43, 0
	s_add_u32 s23, s23, 0x100
	s_addc_u32 s25, s25, 0
	s_cmp_gt_u32 s30, 29
	s_cbranch_scc1 .Lpeel_done_P1
.LBB0_162:
	s_add_u32 s31, s42, 0xfff80080
	s_addc_u32 s44, s43, -1
	s_add_i32 s47, 0, 0x10000
	s_cmp_eq_u32 s30, 28
	s_cselect_b32 s49, s13, s44
	s_cselect_b32 s48, s20, s31
	ds_read_b128 v[144:147], v1
	ds_read_b128 v[148:151], v141
	s_cselect_b32 s45, s19, s25
	s_cselect_b32 s44, s21, s23
	s_add_i32 s31, 0, 0x14000
	ds_read_b128 v[152:155], v1 offset:2048
	ds_read_b128 v[156:159], v141 offset:2048
	ds_read_b128 v[160:163], v1 offset:16384
	ds_read_b128 v[164:167], v141 offset:16384
	ds_read_b128 v[168:171], v1 offset:18432
	ds_read_b128 v[172:175], v141 offset:18432
	s_add_i32 m0, s34, 0xc000
	ds_read_b128 v[176:179], v142
	ds_read_b128 v[184:187], v142 offset:2048
	ds_read_b128 v[188:191], v143
	ds_read_b128 v[192:195], v143 offset:2048
	ds_read_b128 v[196:199], v142 offset:4096
	ds_read_b128 v[200:203], v142 offset:6144
	ds_read_b128 v[204:207], v143 offset:4096
	ds_read_b128 v[208:211], v143 offset:6144
	global_load_lds_dwordx4 v138, s[42:43]
	s_add_i32 m0, s34, 0xe000
	s_nop 0
	global_load_lds_dwordx4 v134, s[42:43]
	s_waitcnt vmcnt(8)
	s_waitcnt lgkmcnt(0)
	s_barrier
	v_mfma_f32_16x16x32_bf16 v[128:131], v[144:147], v[176:179], v[128:131]
	v_mfma_f32_16x16x32_bf16 v[124:127], v[152:155], v[176:179], v[124:127]
	v_mfma_f32_16x16x32_bf16 v[112:115], v[144:147], v[184:187], v[112:115]
	v_mfma_f32_16x16x32_bf16 v[108:111], v[152:155], v[184:187], v[108:111]
	v_mfma_f32_16x16x32_bf16 v[96:99], v[144:147], v[196:199], v[96:99]
	v_mfma_f32_16x16x32_bf16 v[92:95], v[152:155], v[196:199], v[92:95]
	v_mfma_f32_16x16x32_bf16 v[80:83], v[144:147], v[200:203], v[80:83]
	v_mfma_f32_16x16x32_bf16 v[76:79], v[152:155], v[200:203], v[76:79]
	v_mfma_f32_16x16x32_bf16 v[128:131], v[148:151], v[188:191], v[128:131]
	v_mfma_f32_16x16x32_bf16 v[124:127], v[156:159], v[188:191], v[124:127]
	v_mfma_f32_16x16x32_bf16 v[112:115], v[148:151], v[192:195], v[112:115]
	v_mfma_f32_16x16x32_bf16 v[108:111], v[156:159], v[192:195], v[108:111]
	v_mfma_f32_16x16x32_bf16 v[96:99], v[148:151], v[204:207], v[96:99]
	v_mfma_f32_16x16x32_bf16 v[92:95], v[156:159], v[204:207], v[92:95]
	v_mfma_f32_16x16x32_bf16 v[80:83], v[148:151], v[208:211], v[80:83]
	v_mfma_f32_16x16x32_bf16 v[76:79], v[156:159], v[208:211], v[76:79]
	v_mfma_f32_16x16x32_bf16 v[120:123], v[160:163], v[176:179], v[120:123]
	v_mfma_f32_16x16x32_bf16 v[116:119], v[168:171], v[176:179], v[116:119]
	v_mfma_f32_16x16x32_bf16 v[104:107], v[160:163], v[184:187], v[104:107]
	v_mfma_f32_16x16x32_bf16 v[100:103], v[168:171], v[184:187], v[100:103]
	v_mfma_f32_16x16x32_bf16 v[88:91], v[160:163], v[196:199], v[88:91]
	v_mfma_f32_16x16x32_bf16 v[84:87], v[168:171], v[196:199], v[84:87]
	v_mfma_f32_16x16x32_bf16 v[72:75], v[160:163], v[200:203], v[72:75]
	v_mfma_f32_16x16x32_bf16 v[68:71], v[168:171], v[200:203], v[68:71]
	v_mfma_f32_16x16x32_bf16 v[120:123], v[164:167], v[188:191], v[120:123]
	v_mfma_f32_16x16x32_bf16 v[116:119], v[172:175], v[188:191], v[116:119]
	v_mfma_f32_16x16x32_bf16 v[104:107], v[164:167], v[192:195], v[104:107]
	v_mfma_f32_16x16x32_bf16 v[100:103], v[172:175], v[192:195], v[100:103]
	v_mfma_f32_16x16x32_bf16 v[88:91], v[164:167], v[204:207], v[88:91]
	v_mfma_f32_16x16x32_bf16 v[84:87], v[172:175], v[204:207], v[84:87]
	v_mfma_f32_16x16x32_bf16 v[72:75], v[164:167], v[208:211], v[72:75]
	v_mfma_f32_16x16x32_bf16 v[68:71], v[172:175], v[208:211], v[68:71]
	s_barrier
	s_add_i32 s47, s47, s33
	s_mov_b32 m0, s47
	ds_read_b128 v[176:179], v142 offset:16384
	ds_read_b128 v[184:187], v142 offset:18432
	ds_read_b128 v[188:191], v143 offset:16384
	ds_read_b128 v[192:195], v143 offset:18432
	ds_read_b128 v[196:199], v142 offset:20480
	ds_read_b128 v[200:203], v142 offset:22528
	ds_read_b128 v[204:207], v143 offset:20480
	ds_read_b128 v[208:211], v143 offset:22528
	global_load_lds_dwordx4 v136, s[44:45]
	s_add_i32 m0, s47, 0x2000
	s_add_u32 s50, s44, 0x80000
	s_addc_u32 s51, s45, 0
	s_add_i32 s31, s31, s33
	global_load_lds_dwordx4 v132, s[44:45]
	s_mov_b32 m0, s31
	s_nop 0
	global_load_lds_dwordx4 v136, s[50:51]
	s_add_i32 m0, s31, 0x2000
	s_nop 0
	global_load_lds_dwordx4 v132, s[50:51]
	s_mov_b32 m0, s34
	s_nop 0
	global_load_lds_dwordx4 v138, s[48:49]
	s_mov_b32 m0, s35
	s_nop 0
	global_load_lds_dwordx4 v134, s[48:49]
	s_nop 0
	s_waitcnt vmcnt(8)
	s_waitcnt lgkmcnt(0)
	s_barrier
	v_mfma_f32_16x16x32_bf16 v[64:67], v[144:147], v[176:179], v[64:67]
	v_mfma_f32_16x16x32_bf16 v[60:63], v[152:155], v[176:179], v[60:63]
	v_mfma_f32_16x16x32_bf16 v[48:51], v[144:147], v[184:187], v[48:51]
	v_mfma_f32_16x16x32_bf16 v[44:47], v[152:155], v[184:187], v[44:47]
	v_mfma_f32_16x16x32_bf16 v[30:33], v[144:147], v[196:199], v[30:33]
	v_mfma_f32_16x16x32_bf16 v[26:29], v[152:155], v[196:199], v[26:29]
	v_mfma_f32_16x16x32_bf16 v[14:17], v[144:147], v[200:203], v[14:17]
	v_mfma_f32_16x16x32_bf16 v[10:13], v[152:155], v[200:203], v[10:13]
	v_mfma_f32_16x16x32_bf16 v[64:67], v[148:151], v[188:191], v[64:67]
	v_mfma_f32_16x16x32_bf16 v[60:63], v[156:159], v[188:191], v[60:63]
	v_mfma_f32_16x16x32_bf16 v[48:51], v[148:151], v[192:195], v[48:51]
	v_mfma_f32_16x16x32_bf16 v[44:47], v[156:159], v[192:195], v[44:47]
	v_mfma_f32_16x16x32_bf16 v[30:33], v[148:151], v[204:207], v[30:33]
	v_mfma_f32_16x16x32_bf16 v[26:29], v[156:159], v[204:207], v[26:29]
	v_mfma_f32_16x16x32_bf16 v[14:17], v[148:151], v[208:211], v[14:17]
	v_mfma_f32_16x16x32_bf16 v[10:13], v[156:159], v[208:211], v[10:13]
	v_mfma_f32_16x16x32_bf16 v[56:59], v[160:163], v[176:179], v[56:59]
	v_mfma_f32_16x16x32_bf16 v[52:55], v[168:171], v[176:179], v[52:55]
	v_mfma_f32_16x16x32_bf16 v[40:43], v[160:163], v[184:187], v[40:43]
	v_mfma_f32_16x16x32_bf16 v[36:39], v[168:171], v[184:187], v[36:39]
	v_mfma_f32_16x16x32_bf16 v[22:25], v[160:163], v[196:199], v[22:25]
	v_mfma_f32_16x16x32_bf16 v[18:21], v[168:171], v[196:199], v[18:21]
	v_mfma_f32_16x16x32_bf16 v[6:9], v[160:163], v[200:203], v[6:9]
	v_mfma_f32_16x16x32_bf16 v[2:5], v[168:171], v[200:203], v[2:5]
	v_mfma_f32_16x16x32_bf16 v[56:59], v[164:167], v[188:191], v[56:59]
	v_mfma_f32_16x16x32_bf16 v[52:55], v[172:175], v[188:191], v[52:55]
	v_mfma_f32_16x16x32_bf16 v[40:43], v[164:167], v[192:195], v[40:43]
	v_mfma_f32_16x16x32_bf16 v[36:39], v[172:175], v[192:195], v[36:39]
	v_mfma_f32_16x16x32_bf16 v[22:25], v[164:167], v[204:207], v[22:25]
	v_mfma_f32_16x16x32_bf16 v[18:21], v[172:175], v[204:207], v[18:21]
	v_mfma_f32_16x16x32_bf16 v[6:9], v[164:167], v[208:211], v[6:9]
	v_mfma_f32_16x16x32_bf16 v[2:5], v[172:175], v[208:211], v[2:5]
	s_barrier
	s_add_i32 s31, 0, 0x18000
	ds_read_b128 v[144:147], v1 offset:32768
	ds_read_b128 v[148:151], v141 offset:32768
	s_add_i32 s47, 0, 0x1c000
	ds_read_b128 v[152:155], v1 offset:34816
	ds_read_b128 v[156:159], v141 offset:34816
	ds_read_b128 v[160:163], v1 offset:49152
	ds_read_b128 v[164:167], v141 offset:49152
	ds_read_b128 v[168:171], v1 offset:51200
	ds_read_b128 v[172:175], v141 offset:51200
	s_mov_b64 s[100:101], s[48:49]
	s_add_u32 s48, s48, 0x80000
	s_addc_u32 s49, s49, 0
	s_mov_b32 m0, s54
	ds_read_b128 v[176:179], v142 offset:32768
	ds_read_b128 v[184:187], v142 offset:34816
	ds_read_b128 v[188:191], v143 offset:32768
	ds_read_b128 v[192:195], v143 offset:34816
	ds_read_b128 v[196:199], v142 offset:36864
	ds_read_b128 v[200:203], v142 offset:38912
	ds_read_b128 v[204:207], v143 offset:36864
	ds_read_b128 v[208:211], v143 offset:38912
	global_load_lds_dwordx4 v138, s[48:49]
	s_mov_b32 m0, s55
	s_nop 0
	global_load_lds_dwordx4 v134, s[48:49]
	s_nop 0
	s_waitcnt vmcnt(8)
	s_waitcnt lgkmcnt(0)
	s_barrier
	v_mfma_f32_16x16x32_bf16 v[128:131], v[144:147], v[176:179], v[128:131]
	v_mfma_f32_16x16x32_bf16 v[124:127], v[152:155], v[176:179], v[124:127]
	v_mfma_f32_16x16x32_bf16 v[112:115], v[144:147], v[184:187], v[112:115]
	v_mfma_f32_16x16x32_bf16 v[108:111], v[152:155], v[184:187], v[108:111]
	v_mfma_f32_16x16x32_bf16 v[96:99], v[144:147], v[196:199], v[96:99]
	v_mfma_f32_16x16x32_bf16 v[92:95], v[152:155], v[196:199], v[92:95]
	v_mfma_f32_16x16x32_bf16 v[80:83], v[144:147], v[200:203], v[80:83]
	v_mfma_f32_16x16x32_bf16 v[76:79], v[152:155], v[200:203], v[76:79]
	v_mfma_f32_16x16x32_bf16 v[128:131], v[148:151], v[188:191], v[128:131]
	v_mfma_f32_16x16x32_bf16 v[124:127], v[156:159], v[188:191], v[124:127]
	v_mfma_f32_16x16x32_bf16 v[112:115], v[148:151], v[192:195], v[112:115]
	v_mfma_f32_16x16x32_bf16 v[108:111], v[156:159], v[192:195], v[108:111]
	v_mfma_f32_16x16x32_bf16 v[96:99], v[148:151], v[204:207], v[96:99]
	v_mfma_f32_16x16x32_bf16 v[92:95], v[156:159], v[204:207], v[92:95]
	v_mfma_f32_16x16x32_bf16 v[80:83], v[148:151], v[208:211], v[80:83]
	v_mfma_f32_16x16x32_bf16 v[76:79], v[156:159], v[208:211], v[76:79]
	v_mfma_f32_16x16x32_bf16 v[120:123], v[160:163], v[176:179], v[120:123]
	v_mfma_f32_16x16x32_bf16 v[116:119], v[168:171], v[176:179], v[116:119]
	v_mfma_f32_16x16x32_bf16 v[104:107], v[160:163], v[184:187], v[104:107]
	v_mfma_f32_16x16x32_bf16 v[100:103], v[168:171], v[184:187], v[100:103]
	v_mfma_f32_16x16x32_bf16 v[88:91], v[160:163], v[196:199], v[88:91]
	v_mfma_f32_16x16x32_bf16 v[84:87], v[168:171], v[196:199], v[84:87]
	v_mfma_f32_16x16x32_bf16 v[72:75], v[160:163], v[200:203], v[72:75]
	v_mfma_f32_16x16x32_bf16 v[68:71], v[168:171], v[200:203], v[68:71]
	v_mfma_f32_16x16x32_bf16 v[120:123], v[164:167], v[188:191], v[120:123]
	v_mfma_f32_16x16x32_bf16 v[116:119], v[172:175], v[188:191], v[116:119]
	v_mfma_f32_16x16x32_bf16 v[104:107], v[164:167], v[192:195], v[104:107]
	v_mfma_f32_16x16x32_bf16 v[100:103], v[172:175], v[192:195], v[100:103]
	v_mfma_f32_16x16x32_bf16 v[88:91], v[164:167], v[204:207], v[88:91]
	v_mfma_f32_16x16x32_bf16 v[84:87], v[172:175], v[204:207], v[84:87]
	v_mfma_f32_16x16x32_bf16 v[72:75], v[164:167], v[208:211], v[72:75]
	v_mfma_f32_16x16x32_bf16 v[68:71], v[172:175], v[208:211], v[68:71]
	s_barrier
	s_add_i32 s31, s31, s33
	s_add_i32 m0, s31, 0xffffff80
	ds_read_b128 v[176:179], v142 offset:49152
	ds_read_b128 v[184:187], v142 offset:51200
	ds_read_b128 v[188:191], v143 offset:49152
	ds_read_b128 v[192:195], v143 offset:51200
	ds_read_b128 v[196:199], v142 offset:53248
	ds_read_b128 v[200:203], v142 offset:55296
	ds_read_b128 v[204:207], v143 offset:53248
	ds_read_b128 v[208:211], v143 offset:55296
	global_load_lds_dwordx4 v136, s[44:45] offset:128
	s_add_i32 m0, s31, 0x1f80
	s_mov_b64 s[98:99], s[44:45]
	s_add_u32 s44, s44, 0x80080
	s_addc_u32 s45, s45, 0
	s_add_i32 s31, s47, s33
	global_load_lds_dwordx4 v132, s[98:99] offset:128
	s_mov_b32 m0, s31
	s_nop 0
	global_load_lds_dwordx4 v136, s[44:45]
	s_add_i32 m0, s31, 0x2000
	s_nop 0
	global_load_lds_dwordx4 v132, s[44:45]
	s_add_i32 m0, s56, 0xffffff80
	s_nop 0
	global_load_lds_dwordx4 v138, s[100:101] offset:128
	s_add_i32 m0, s57, 0xffffff80
	s_nop 0
	global_load_lds_dwordx4 v134, s[100:101] offset:128
	s_nop 0
	s_waitcnt vmcnt(8)
	s_waitcnt lgkmcnt(0)
	s_barrier
	v_mfma_f32_16x16x32_bf16 v[64:67], v[144:147], v[176:179], v[64:67]
	v_mfma_f32_16x16x32_bf16 v[60:63], v[152:155], v[176:179], v[60:63]
	v_mfma_f32_16x16x32_bf16 v[48:51], v[144:147], v[184:187], v[48:51]
	v_mfma_f32_16x16x32_bf16 v[44:47], v[152:155], v[184:187], v[44:47]
	v_mfma_f32_16x16x32_bf16 v[30:33], v[144:147], v[196:199], v[30:33]
	v_mfma_f32_16x16x32_bf16 v[26:29], v[152:155], v[196:199], v[26:29]
	v_mfma_f32_16x16x32_bf16 v[14:17], v[144:147], v[200:203], v[14:17]
	v_mfma_f32_16x16x32_bf16 v[10:13], v[152:155], v[200:203], v[10:13]
	v_mfma_f32_16x16x32_bf16 v[64:67], v[148:151], v[188:191], v[64:67]
	v_mfma_f32_16x16x32_bf16 v[60:63], v[156:159], v[188:191], v[60:63]
	v_mfma_f32_16x16x32_bf16 v[48:51], v[148:151], v[192:195], v[48:51]
	v_mfma_f32_16x16x32_bf16 v[44:47], v[156:159], v[192:195], v[44:47]
	v_mfma_f32_16x16x32_bf16 v[30:33], v[148:151], v[204:207], v[30:33]
	v_mfma_f32_16x16x32_bf16 v[26:29], v[156:159], v[204:207], v[26:29]
	v_mfma_f32_16x16x32_bf16 v[14:17], v[148:151], v[208:211], v[14:17]
	v_mfma_f32_16x16x32_bf16 v[10:13], v[156:159], v[208:211], v[10:13]
	v_mfma_f32_16x16x32_bf16 v[56:59], v[160:163], v[176:179], v[56:59]
	v_mfma_f32_16x16x32_bf16 v[52:55], v[168:171], v[176:179], v[52:55]
	v_mfma_f32_16x16x32_bf16 v[40:43], v[160:163], v[184:187], v[40:43]
	v_mfma_f32_16x16x32_bf16 v[36:39], v[168:171], v[184:187], v[36:39]
	v_mfma_f32_16x16x32_bf16 v[22:25], v[160:163], v[196:199], v[22:25]
	v_mfma_f32_16x16x32_bf16 v[18:21], v[168:171], v[196:199], v[18:21]
	v_mfma_f32_16x16x32_bf16 v[6:9], v[160:163], v[200:203], v[6:9]
	v_mfma_f32_16x16x32_bf16 v[2:5], v[168:171], v[200:203], v[2:5]
	v_mfma_f32_16x16x32_bf16 v[56:59], v[164:167], v[188:191], v[56:59]
	v_mfma_f32_16x16x32_bf16 v[52:55], v[172:175], v[188:191], v[52:55]
	v_mfma_f32_16x16x32_bf16 v[40:43], v[164:167], v[192:195], v[40:43]
	v_mfma_f32_16x16x32_bf16 v[36:39], v[172:175], v[192:195], v[36:39]
	v_mfma_f32_16x16x32_bf16 v[22:25], v[164:167], v[204:207], v[22:25]
	v_mfma_f32_16x16x32_bf16 v[18:21], v[172:175], v[204:207], v[18:21]
	v_mfma_f32_16x16x32_bf16 v[6:9], v[164:167], v[208:211], v[6:9]
	v_mfma_f32_16x16x32_bf16 v[2:5], v[172:175], v[208:211], v[2:5]
	s_barrier
	s_add_i32 s30, s30, 2
	s_add_u32 s42, s42, 0x100
	s_addc_u32 s43, s43, 0
	s_add_u32 s23, s23, 0x100
	s_addc_u32 s25, s25, 0
	s_cmp_gt_u32 s30, 29
	s_cbranch_scc0 .LBB0_162

.LBB0_907:
	s_and_b32 s9, 1, s12
	s_cmp_gt_i32 s12, 1
	s_cselect_b32 s24, 10, 12
	s_cmp_eq_u32 s9, 1
	s_cselect_b64 s[18:19], -1, 0
	s_and_b64 s[20:21], s[18:19], exec
	s_cselect_b32 s9, s24, 32
	s_add_i32 s20, s9, -2
	s_add_u32 s22, s22, 0x80080
	s_addc_u32 s23, s23, 0
	s_add_u32 s21, s28, 0x100
	s_addc_u32 s24, s29, 0
	s_mov_b32 s25, 0
	s_waitcnt vmcnt(0)
	v_readlane_b32 s43, v255, 20
	v_readlane_b32 s45, v255, 21
	v_readlane_b32 s66, v255, 22
	v_readlane_b32 s67, v255, 23
	s_mov_b64 s[68:69], 0x80
	s_add_i32 s30, s25, 2
	s_add_u32 s28, s22, 0xfff80080
	s_addc_u32 s29, s23, -1
	s_add_i32 s31, 0, 0x10000
	s_cmp_eq_u32 s20, s25
	s_cselect_b32 s41, s47, s29
	s_cselect_b32 s40, s46, s28
	s_cselect_b32 s29, s49, s24
	s_cselect_b32 s28, s48, s21
	s_add_i32 s25, 0, 0x14000
	ds_read_b128 v[132:135], v1
	ds_read_b128 v[136:139], v204
	ds_read_b128 v[140:143], v1 offset:2048
	ds_read_b128 v[144:147], v204 offset:2048
	ds_read_b128 v[148:151], v1 offset:16384
	ds_read_b128 v[152:155], v204 offset:16384
	ds_read_b128 v[156:159], v1 offset:18432
	ds_read_b128 v[160:163], v204 offset:18432
	s_add_i32 m0, s50, 0xc000
	ds_read_b128 v[164:167], v205
	ds_read_b128 v[168:171], v205 offset:2048
	ds_read_b128 v[172:175], v206
	ds_read_b128 v[176:179], v206 offset:2048
	ds_read_b128 v[190:193], v205 offset:4096
	ds_read_b128 v[194:197], v205 offset:6144
	ds_read_b128 v[198:201], v206 offset:4096
	ds_read_b128 v[232:235], v206 offset:6144
	global_load_lds_dwordx4 v188, s[22:23]
	s_add_i32 m0, s50, 0xe000
	s_nop 0
	global_load_lds_dwordx4 v186, s[22:23]
	s_waitcnt vmcnt(8)
	s_waitcnt lgkmcnt(0)
	s_barrier
	v_mfma_f32_16x16x32_bf16 v[68:71], v[132:135], v[164:167], 0
	v_mfma_f32_16x16x32_bf16 v[72:75], v[140:143], v[164:167], 0
	v_mfma_f32_16x16x32_bf16 v[84:87], v[132:135], v[168:171], 0
	v_mfma_f32_16x16x32_bf16 v[88:91], v[140:143], v[168:171], 0
	v_mfma_f32_16x16x32_bf16 v[100:103], v[132:135], v[190:193], 0
	v_mfma_f32_16x16x32_bf16 v[104:107], v[140:143], v[190:193], 0
	v_mfma_f32_16x16x32_bf16 v[116:119], v[132:135], v[194:197], 0
	v_mfma_f32_16x16x32_bf16 v[120:123], v[140:143], v[194:197], 0
	v_mfma_f32_16x16x32_bf16 v[68:71], v[136:139], v[172:175], v[68:71]
	v_mfma_f32_16x16x32_bf16 v[72:75], v[144:147], v[172:175], v[72:75]
	v_mfma_f32_16x16x32_bf16 v[84:87], v[136:139], v[176:179], v[84:87]
	v_mfma_f32_16x16x32_bf16 v[88:91], v[144:147], v[176:179], v[88:91]
	v_mfma_f32_16x16x32_bf16 v[100:103], v[136:139], v[198:201], v[100:103]
	v_mfma_f32_16x16x32_bf16 v[104:107], v[144:147], v[198:201], v[104:107]
	v_mfma_f32_16x16x32_bf16 v[116:119], v[136:139], v[232:235], v[116:119]
	v_mfma_f32_16x16x32_bf16 v[120:123], v[144:147], v[232:235], v[120:123]
	v_mfma_f32_16x16x32_bf16 v[76:79], v[148:151], v[164:167], 0
	v_mfma_f32_16x16x32_bf16 v[80:83], v[156:159], v[164:167], 0
	v_mfma_f32_16x16x32_bf16 v[92:95], v[148:151], v[168:171], 0
	v_mfma_f32_16x16x32_bf16 v[96:99], v[156:159], v[168:171], 0
	v_mfma_f32_16x16x32_bf16 v[108:111], v[148:151], v[190:193], 0
	v_mfma_f32_16x16x32_bf16 v[112:115], v[156:159], v[190:193], 0
	v_mfma_f32_16x16x32_bf16 v[124:127], v[148:151], v[194:197], 0
	v_mfma_f32_16x16x32_bf16 v[128:131], v[156:159], v[194:197], 0
	v_mfma_f32_16x16x32_bf16 v[76:79], v[152:155], v[172:175], v[76:79]
	v_mfma_f32_16x16x32_bf16 v[80:83], v[160:163], v[172:175], v[80:83]
	v_mfma_f32_16x16x32_bf16 v[92:95], v[152:155], v[176:179], v[92:95]
	v_mfma_f32_16x16x32_bf16 v[96:99], v[160:163], v[176:179], v[96:99]
	v_mfma_f32_16x16x32_bf16 v[108:111], v[152:155], v[198:201], v[108:111]
	v_mfma_f32_16x16x32_bf16 v[112:115], v[160:163], v[198:201], v[112:115]
	v_mfma_f32_16x16x32_bf16 v[124:127], v[152:155], v[232:235], v[124:127]
	v_mfma_f32_16x16x32_bf16 v[128:131], v[160:163], v[232:235], v[128:131]
	s_barrier
	s_add_i32 s31, s31, s33
	s_mov_b32 m0, s31
	ds_read_b128 v[164:167], v205 offset:16384
	ds_read_b128 v[168:171], v205 offset:18432
	ds_read_b128 v[172:175], v206 offset:16384
	ds_read_b128 v[176:179], v206 offset:18432
	ds_read_b128 v[190:193], v205 offset:20480
	ds_read_b128 v[194:197], v205 offset:22528
	ds_read_b128 v[198:201], v206 offset:20480
	ds_read_b128 v[232:235], v206 offset:22528
	global_load_lds_dwordx4 v34, s[28:29]
	s_add_i32 m0, s31, 0x2000
	s_add_u32 s34, s28, 0x80000
	s_addc_u32 s35, s29, 0
	s_add_i32 s25, s25, s33
	global_load_lds_dwordx4 v184, s[28:29]
	s_mov_b32 m0, s25
	s_nop 0
	global_load_lds_dwordx4 v34, s[34:35]
	s_add_i32 m0, s25, 0x2000
	s_nop 0
	global_load_lds_dwordx4 v184, s[34:35]
	s_mov_b32 m0, s50
	s_nop 0
	global_load_lds_dwordx4 v188, s[40:41]
	s_mov_b32 m0, s51
	s_nop 0
	global_load_lds_dwordx4 v186, s[40:41]
	s_nop 0
	s_waitcnt vmcnt(8)
	s_waitcnt lgkmcnt(0)
	s_barrier
	v_mfma_f32_16x16x32_bf16 v[2:5], v[132:135], v[164:167], 0
	v_mfma_f32_16x16x32_bf16 v[6:9], v[140:143], v[164:167], 0
	v_mfma_f32_16x16x32_bf16 v[18:21], v[132:135], v[168:171], 0
	v_mfma_f32_16x16x32_bf16 v[22:25], v[140:143], v[168:171], 0
	v_mfma_f32_16x16x32_bf16 v[36:39], v[132:135], v[190:193], 0
	v_mfma_f32_16x16x32_bf16 v[40:43], v[140:143], v[190:193], 0
	v_mfma_f32_16x16x32_bf16 v[52:55], v[132:135], v[194:197], 0
	v_mfma_f32_16x16x32_bf16 v[56:59], v[140:143], v[194:197], 0
	v_mfma_f32_16x16x32_bf16 v[2:5], v[136:139], v[172:175], v[2:5]
	v_mfma_f32_16x16x32_bf16 v[6:9], v[144:147], v[172:175], v[6:9]
	v_mfma_f32_16x16x32_bf16 v[18:21], v[136:139], v[176:179], v[18:21]
	v_mfma_f32_16x16x32_bf16 v[22:25], v[144:147], v[176:179], v[22:25]
	v_mfma_f32_16x16x32_bf16 v[36:39], v[136:139], v[198:201], v[36:39]
	v_mfma_f32_16x16x32_bf16 v[40:43], v[144:147], v[198:201], v[40:43]
	v_mfma_f32_16x16x32_bf16 v[52:55], v[136:139], v[232:235], v[52:55]
	v_mfma_f32_16x16x32_bf16 v[56:59], v[144:147], v[232:235], v[56:59]
	v_mfma_f32_16x16x32_bf16 v[10:13], v[148:151], v[164:167], 0
	v_mfma_f32_16x16x32_bf16 v[14:17], v[156:159], v[164:167], 0
	v_mfma_f32_16x16x32_bf16 v[26:29], v[148:151], v[168:171], 0
	v_mfma_f32_16x16x32_bf16 v[30:33], v[156:159], v[168:171], 0
	v_mfma_f32_16x16x32_bf16 v[44:47], v[148:151], v[190:193], 0
	v_mfma_f32_16x16x32_bf16 v[48:51], v[156:159], v[190:193], 0
	v_mfma_f32_16x16x32_bf16 v[60:63], v[148:151], v[194:197], 0
	v_mfma_f32_16x16x32_bf16 v[64:67], v[156:159], v[194:197], 0
	v_mfma_f32_16x16x32_bf16 v[10:13], v[152:155], v[172:175], v[10:13]
	v_mfma_f32_16x16x32_bf16 v[14:17], v[160:163], v[172:175], v[14:17]
	v_mfma_f32_16x16x32_bf16 v[26:29], v[152:155], v[176:179], v[26:29]
	v_mfma_f32_16x16x32_bf16 v[30:33], v[160:163], v[176:179], v[30:33]
	v_mfma_f32_16x16x32_bf16 v[44:47], v[152:155], v[198:201], v[44:47]
	v_mfma_f32_16x16x32_bf16 v[48:51], v[160:163], v[198:201], v[48:51]
	v_mfma_f32_16x16x32_bf16 v[60:63], v[152:155], v[232:235], v[60:63]
	v_mfma_f32_16x16x32_bf16 v[64:67], v[160:163], v[232:235], v[64:67]
	s_barrier
	s_add_i32 s25, 0, 0x18000
	s_add_i32 s31, 0, 0x1c000
	ds_read_b128 v[132:135], v1 offset:32768
	ds_read_b128 v[136:139], v204 offset:32768
	ds_read_b128 v[140:143], v1 offset:34816
	ds_read_b128 v[144:147], v204 offset:34816
	ds_read_b128 v[148:151], v1 offset:49152
	ds_read_b128 v[152:155], v204 offset:49152
	ds_read_b128 v[156:159], v1 offset:51200
	ds_read_b128 v[160:163], v204 offset:51200
	s_add_u32 s34, s40, 0x80000
	s_addc_u32 s35, s41, 0
	s_mov_b32 m0, s52
	ds_read_b128 v[164:167], v205 offset:32768
	ds_read_b128 v[168:171], v205 offset:34816
	ds_read_b128 v[172:175], v206 offset:32768
	ds_read_b128 v[176:179], v206 offset:34816
	ds_read_b128 v[190:193], v205 offset:36864
	ds_read_b128 v[194:197], v205 offset:38912
	ds_read_b128 v[198:201], v206 offset:36864
	ds_read_b128 v[232:235], v206 offset:38912
	global_load_lds_dwordx4 v188, s[34:35]
	s_mov_b32 m0, s53
	s_nop 0
	global_load_lds_dwordx4 v186, s[34:35]
	s_waitcnt vmcnt(8)
	s_waitcnt lgkmcnt(0)
	s_barrier
	v_mfma_f32_16x16x32_bf16 v[68:71], v[132:135], v[164:167], v[68:71]
	v_mfma_f32_16x16x32_bf16 v[72:75], v[140:143], v[164:167], v[72:75]
	v_mfma_f32_16x16x32_bf16 v[84:87], v[132:135], v[168:171], v[84:87]
	v_mfma_f32_16x16x32_bf16 v[88:91], v[140:143], v[168:171], v[88:91]
	v_mfma_f32_16x16x32_bf16 v[100:103], v[132:135], v[190:193], v[100:103]
	v_mfma_f32_16x16x32_bf16 v[104:107], v[140:143], v[190:193], v[104:107]
	v_mfma_f32_16x16x32_bf16 v[116:119], v[132:135], v[194:197], v[116:119]
	v_mfma_f32_16x16x32_bf16 v[120:123], v[140:143], v[194:197], v[120:123]
	v_mfma_f32_16x16x32_bf16 v[68:71], v[136:139], v[172:175], v[68:71]
	v_mfma_f32_16x16x32_bf16 v[72:75], v[144:147], v[172:175], v[72:75]
	v_mfma_f32_16x16x32_bf16 v[84:87], v[136:139], v[176:179], v[84:87]
	v_mfma_f32_16x16x32_bf16 v[88:91], v[144:147], v[176:179], v[88:91]
	v_mfma_f32_16x16x32_bf16 v[100:103], v[136:139], v[198:201], v[100:103]
	v_mfma_f32_16x16x32_bf16 v[104:107], v[144:147], v[198:201], v[104:107]
	v_mfma_f32_16x16x32_bf16 v[116:119], v[136:139], v[232:235], v[116:119]
	v_mfma_f32_16x16x32_bf16 v[120:123], v[144:147], v[232:235], v[120:123]
	v_mfma_f32_16x16x32_bf16 v[76:79], v[148:151], v[164:167], v[76:79]
	v_mfma_f32_16x16x32_bf16 v[80:83], v[156:159], v[164:167], v[80:83]
	v_mfma_f32_16x16x32_bf16 v[92:95], v[148:151], v[168:171], v[92:95]
	v_mfma_f32_16x16x32_bf16 v[96:99], v[156:159], v[168:171], v[96:99]
	v_mfma_f32_16x16x32_bf16 v[108:111], v[148:151], v[190:193], v[108:111]
	v_mfma_f32_16x16x32_bf16 v[112:115], v[156:159], v[190:193], v[112:115]
	v_mfma_f32_16x16x32_bf16 v[124:127], v[148:151], v[194:197], v[124:127]
	v_mfma_f32_16x16x32_bf16 v[128:131], v[156:159], v[194:197], v[128:131]
	v_mfma_f32_16x16x32_bf16 v[76:79], v[152:155], v[172:175], v[76:79]
	v_mfma_f32_16x16x32_bf16 v[80:83], v[160:163], v[172:175], v[80:83]
	v_mfma_f32_16x16x32_bf16 v[92:95], v[152:155], v[176:179], v[92:95]
	v_mfma_f32_16x16x32_bf16 v[96:99], v[160:163], v[176:179], v[96:99]
	v_mfma_f32_16x16x32_bf16 v[108:111], v[152:155], v[198:201], v[108:111]
	v_mfma_f32_16x16x32_bf16 v[112:115], v[160:163], v[198:201], v[112:115]
	v_mfma_f32_16x16x32_bf16 v[124:127], v[152:155], v[232:235], v[124:127]
	v_mfma_f32_16x16x32_bf16 v[128:131], v[160:163], v[232:235], v[128:131]
	s_barrier
	s_add_i32 s25, s25, s33
	s_add_i32 m0, s25, 0xffffff80
	ds_read_b128 v[164:167], v205 offset:49152
	ds_read_b128 v[168:171], v205 offset:51200
	ds_read_b128 v[172:175], v206 offset:49152
	ds_read_b128 v[176:179], v206 offset:51200
	ds_read_b128 v[190:193], v205 offset:53248
	ds_read_b128 v[194:197], v205 offset:55296
	ds_read_b128 v[198:201], v206 offset:53248
	ds_read_b128 v[232:235], v206 offset:55296
	global_load_lds_dwordx4 v34, s[28:29] offset:128
	s_add_i32 m0, s25, 0x1f80
	s_mov_b64 s[98:99], s[28:29]
	s_add_u32 s28, s28, 0x80080
	s_addc_u32 s29, s29, 0
	s_add_i32 s25, s31, s33
	global_load_lds_dwordx4 v184, s[98:99] offset:128
	s_mov_b32 m0, s25
	s_nop 0
	global_load_lds_dwordx4 v34, s[28:29]
	s_add_i32 m0, s25, 0x2000
	s_nop 0
	global_load_lds_dwordx4 v184, s[28:29]
	s_add_i32 m0, s54, 0xffffff80
	s_nop 0
	global_load_lds_dwordx4 v188, s[40:41] offset:128
	s_add_i32 m0, s55, 0xffffff80
	s_nop 0
	global_load_lds_dwordx4 v186, s[40:41] offset:128
	s_nop 0
	s_waitcnt vmcnt(8)
	s_waitcnt lgkmcnt(0)
	s_barrier
	v_mfma_f32_16x16x32_bf16 v[2:5], v[132:135], v[164:167], v[2:5]
	v_mfma_f32_16x16x32_bf16 v[6:9], v[140:143], v[164:167], v[6:9]
	v_mfma_f32_16x16x32_bf16 v[18:21], v[132:135], v[168:171], v[18:21]
	v_mfma_f32_16x16x32_bf16 v[22:25], v[140:143], v[168:171], v[22:25]
	v_mfma_f32_16x16x32_bf16 v[36:39], v[132:135], v[190:193], v[36:39]
	v_mfma_f32_16x16x32_bf16 v[40:43], v[140:143], v[190:193], v[40:43]
	v_mfma_f32_16x16x32_bf16 v[52:55], v[132:135], v[194:197], v[52:55]
	v_mfma_f32_16x16x32_bf16 v[56:59], v[140:143], v[194:197], v[56:59]
	v_mfma_f32_16x16x32_bf16 v[2:5], v[136:139], v[172:175], v[2:5]
	v_mfma_f32_16x16x32_bf16 v[6:9], v[144:147], v[172:175], v[6:9]
	v_mfma_f32_16x16x32_bf16 v[18:21], v[136:139], v[176:179], v[18:21]
	v_mfma_f32_16x16x32_bf16 v[22:25], v[144:147], v[176:179], v[22:25]
	v_mfma_f32_16x16x32_bf16 v[36:39], v[136:139], v[198:201], v[36:39]
	v_mfma_f32_16x16x32_bf16 v[40:43], v[144:147], v[198:201], v[40:43]
	v_mfma_f32_16x16x32_bf16 v[52:55], v[136:139], v[232:235], v[52:55]
	v_mfma_f32_16x16x32_bf16 v[56:59], v[144:147], v[232:235], v[56:59]
	v_mfma_f32_16x16x32_bf16 v[10:13], v[148:151], v[164:167], v[10:13]
	v_mfma_f32_16x16x32_bf16 v[14:17], v[156:159], v[164:167], v[14:17]
	v_mfma_f32_16x16x32_bf16 v[26:29], v[148:151], v[168:171], v[26:29]
	v_mfma_f32_16x16x32_bf16 v[30:33], v[156:159], v[168:171], v[30:33]
	v_mfma_f32_16x16x32_bf16 v[44:47], v[148:151], v[190:193], v[44:47]
	v_mfma_f32_16x16x32_bf16 v[48:51], v[156:159], v[190:193], v[48:51]
	v_mfma_f32_16x16x32_bf16 v[60:63], v[148:151], v[194:197], v[60:63]
	v_mfma_f32_16x16x32_bf16 v[64:67], v[156:159], v[194:197], v[64:67]
	v_mfma_f32_16x16x32_bf16 v[10:13], v[152:155], v[172:175], v[10:13]
	v_mfma_f32_16x16x32_bf16 v[14:17], v[160:163], v[172:175], v[14:17]
	v_mfma_f32_16x16x32_bf16 v[26:29], v[152:155], v[176:179], v[26:29]
	v_mfma_f32_16x16x32_bf16 v[30:33], v[160:163], v[176:179], v[30:33]
	v_mfma_f32_16x16x32_bf16 v[44:47], v[152:155], v[198:201], v[44:47]
	v_mfma_f32_16x16x32_bf16 v[48:51], v[160:163], v[198:201], v[48:51]
	v_mfma_f32_16x16x32_bf16 v[60:63], v[152:155], v[232:235], v[60:63]
	v_mfma_f32_16x16x32_bf16 v[64:67], v[160:163], v[232:235], v[64:67]
	s_barrier
	s_add_u32 s22, s22, 0x100
	s_addc_u32 s23, s23, 0
	s_add_u32 s21, s21, 0x100
	s_addc_u32 s24, s24, 0
	s_cmp_ge_u32 s30, s9
	s_mov_b32 s25, s30
	s_cbranch_scc1 .Lpeel_done_P3
.LBB0_908:
	s_add_i32 s30, s25, 2
	s_add_u32 s28, s22, 0xfff80080
	s_addc_u32 s29, s23, -1
	s_add_i32 s31, 0, 0x10000
	s_cmp_eq_u32 s20, s25
	s_cselect_b32 s41, s47, s29
	s_cselect_b32 s40, s46, s28
	s_cselect_b32 s29, s49, s24
	s_cselect_b32 s28, s48, s21
	s_add_i32 s25, 0, 0x14000
	ds_read_b128 v[132:135], v1
	ds_read_b128 v[136:139], v204
	ds_read_b128 v[140:143], v1 offset:2048
	ds_read_b128 v[144:147], v204 offset:2048
	ds_read_b128 v[148:151], v1 offset:16384
	ds_read_b128 v[152:155], v204 offset:16384
	ds_read_b128 v[156:159], v1 offset:18432
	ds_read_b128 v[160:163], v204 offset:18432
	s_add_i32 m0, s50, 0xc000
	ds_read_b128 v[164:167], v205
	ds_read_b128 v[168:171], v205 offset:2048
	ds_read_b128 v[172:175], v206
	ds_read_b128 v[176:179], v206 offset:2048
	ds_read_b128 v[190:193], v205 offset:4096
	ds_read_b128 v[194:197], v205 offset:6144
	ds_read_b128 v[198:201], v206 offset:4096
	ds_read_b128 v[232:235], v206 offset:6144
	global_load_lds_dwordx4 v188, s[22:23]
	s_add_i32 m0, s50, 0xe000
	s_nop 0
	global_load_lds_dwordx4 v186, s[22:23]
	s_nop 0
	s_waitcnt vmcnt(8)
	s_waitcnt lgkmcnt(0)
	s_barrier
	v_mfma_f32_16x16x32_bf16 v[68:71], v[132:135], v[164:167], v[68:71]
	v_mfma_f32_16x16x32_bf16 v[72:75], v[140:143], v[164:167], v[72:75]
	v_mfma_f32_16x16x32_bf16 v[84:87], v[132:135], v[168:171], v[84:87]
	v_mfma_f32_16x16x32_bf16 v[88:91], v[140:143], v[168:171], v[88:91]
	v_mfma_f32_16x16x32_bf16 v[100:103], v[132:135], v[190:193], v[100:103]
	v_mfma_f32_16x16x32_bf16 v[104:107], v[140:143], v[190:193], v[104:107]
	v_mfma_f32_16x16x32_bf16 v[116:119], v[132:135], v[194:197], v[116:119]
	v_mfma_f32_16x16x32_bf16 v[120:123], v[140:143], v[194:197], v[120:123]
	v_mfma_f32_16x16x32_bf16 v[68:71], v[136:139], v[172:175], v[68:71]
	v_mfma_f32_16x16x32_bf16 v[72:75], v[144:147], v[172:175], v[72:75]
	v_mfma_f32_16x16x32_bf16 v[84:87], v[136:139], v[176:179], v[84:87]
	v_mfma_f32_16x16x32_bf16 v[88:91], v[144:147], v[176:179], v[88:91]
	v_mfma_f32_16x16x32_bf16 v[100:103], v[136:139], v[198:201], v[100:103]
	v_mfma_f32_16x16x32_bf16 v[104:107], v[144:147], v[198:201], v[104:107]
	v_mfma_f32_16x16x32_bf16 v[116:119], v[136:139], v[232:235], v[116:119]
	v_mfma_f32_16x16x32_bf16 v[120:123], v[144:147], v[232:235], v[120:123]
	v_mfma_f32_16x16x32_bf16 v[76:79], v[148:151], v[164:167], v[76:79]
	v_mfma_f32_16x16x32_bf16 v[80:83], v[156:159], v[164:167], v[80:83]
	v_mfma_f32_16x16x32_bf16 v[92:95], v[148:151], v[168:171], v[92:95]
	v_mfma_f32_16x16x32_bf16 v[96:99], v[156:159], v[168:171], v[96:99]
	v_mfma_f32_16x16x32_bf16 v[108:111], v[148:151], v[190:193], v[108:111]
	v_mfma_f32_16x16x32_bf16 v[112:115], v[156:159], v[190:193], v[112:115]
	v_mfma_f32_16x16x32_bf16 v[124:127], v[148:151], v[194:197], v[124:127]
	v_mfma_f32_16x16x32_bf16 v[128:131], v[156:159], v[194:197], v[128:131]
	v_mfma_f32_16x16x32_bf16 v[76:79], v[152:155], v[172:175], v[76:79]
	v_mfma_f32_16x16x32_bf16 v[80:83], v[160:163], v[172:175], v[80:83]
	v_mfma_f32_16x16x32_bf16 v[92:95], v[152:155], v[176:179], v[92:95]
	v_mfma_f32_16x16x32_bf16 v[96:99], v[160:163], v[176:179], v[96:99]
	v_mfma_f32_16x16x32_bf16 v[108:111], v[152:155], v[198:201], v[108:111]
	v_mfma_f32_16x16x32_bf16 v[112:115], v[160:163], v[198:201], v[112:115]
	v_mfma_f32_16x16x32_bf16 v[124:127], v[152:155], v[232:235], v[124:127]
	v_mfma_f32_16x16x32_bf16 v[128:131], v[160:163], v[232:235], v[128:131]
	s_barrier
	s_add_i32 s31, s31, s33
	s_mov_b32 m0, s31
	ds_read_b128 v[164:167], v205 offset:16384
	ds_read_b128 v[168:171], v205 offset:18432
	ds_read_b128 v[172:175], v206 offset:16384
	ds_read_b128 v[176:179], v206 offset:18432
	ds_read_b128 v[190:193], v205 offset:20480
	ds_read_b128 v[194:197], v205 offset:22528
	ds_read_b128 v[198:201], v206 offset:20480
	ds_read_b128 v[232:235], v206 offset:22528
	global_load_lds_dwordx4 v34, s[28:29]
	s_add_i32 m0, s31, 0x2000
	s_add_u32 s34, s28, 0x80000
	s_addc_u32 s35, s29, 0
	s_add_i32 s25, s25, s33
	global_load_lds_dwordx4 v184, s[28:29]
	s_mov_b32 m0, s25
	s_nop 0
	global_load_lds_dwordx4 v34, s[34:35]
	s_add_i32 m0, s25, 0x2000
	s_nop 0
	global_load_lds_dwordx4 v184, s[34:35]
	s_mov_b32 m0, s50
	s_nop 0
	global_load_lds_dwordx4 v188, s[40:41]
	s_mov_b32 m0, s51
	s_nop 0
	global_load_lds_dwordx4 v186, s[40:41]
	s_nop 0
	s_waitcnt vmcnt(8)
	s_waitcnt lgkmcnt(0)
	s_barrier
	v_mfma_f32_16x16x32_bf16 v[2:5], v[132:135], v[164:167], v[2:5]
	v_mfma_f32_16x16x32_bf16 v[6:9], v[140:143], v[164:167], v[6:9]
	v_mfma_f32_16x16x32_bf16 v[18:21], v[132:135], v[168:171], v[18:21]
	v_mfma_f32_16x16x32_bf16 v[22:25], v[140:143], v[168:171], v[22:25]
	v_mfma_f32_16x16x32_bf16 v[36:39], v[132:135], v[190:193], v[36:39]
	v_mfma_f32_16x16x32_bf16 v[40:43], v[140:143], v[190:193], v[40:43]
	v_mfma_f32_16x16x32_bf16 v[52:55], v[132:135], v[194:197], v[52:55]
	v_mfma_f32_16x16x32_bf16 v[56:59], v[140:143], v[194:197], v[56:59]
	v_mfma_f32_16x16x32_bf16 v[2:5], v[136:139], v[172:175], v[2:5]
	v_mfma_f32_16x16x32_bf16 v[6:9], v[144:147], v[172:175], v[6:9]
	v_mfma_f32_16x16x32_bf16 v[18:21], v[136:139], v[176:179], v[18:21]
	v_mfma_f32_16x16x32_bf16 v[22:25], v[144:147], v[176:179], v[22:25]
	v_mfma_f32_16x16x32_bf16 v[36:39], v[136:139], v[198:201], v[36:39]
	v_mfma_f32_16x16x32_bf16 v[40:43], v[144:147], v[198:201], v[40:43]
	v_mfma_f32_16x16x32_bf16 v[52:55], v[136:139], v[232:235], v[52:55]
	v_mfma_f32_16x16x32_bf16 v[56:59], v[144:147], v[232:235], v[56:59]
	v_mfma_f32_16x16x32_bf16 v[10:13], v[148:151], v[164:167], v[10:13]
	v_mfma_f32_16x16x32_bf16 v[14:17], v[156:159], v[164:167], v[14:17]
	v_mfma_f32_16x16x32_bf16 v[26:29], v[148:151], v[168:171], v[26:29]
	v_mfma_f32_16x16x32_bf16 v[30:33], v[156:159], v[168:171], v[30:33]
	v_mfma_f32_16x16x32_bf16 v[44:47], v[148:151], v[190:193], v[44:47]
	v_mfma_f32_16x16x32_bf16 v[48:51], v[156:159], v[190:193], v[48:51]
	v_mfma_f32_16x16x32_bf16 v[60:63], v[148:151], v[194:197], v[60:63]
	v_mfma_f32_16x16x32_bf16 v[64:67], v[156:159], v[194:197], v[64:67]
	v_mfma_f32_16x16x32_bf16 v[10:13], v[152:155], v[172:175], v[10:13]
	v_mfma_f32_16x16x32_bf16 v[14:17], v[160:163], v[172:175], v[14:17]
	v_mfma_f32_16x16x32_bf16 v[26:29], v[152:155], v[176:179], v[26:29]
	v_mfma_f32_16x16x32_bf16 v[30:33], v[160:163], v[176:179], v[30:33]
	v_mfma_f32_16x16x32_bf16 v[44:47], v[152:155], v[198:201], v[44:47]
	v_mfma_f32_16x16x32_bf16 v[48:51], v[160:163], v[198:201], v[48:51]
	v_mfma_f32_16x16x32_bf16 v[60:63], v[152:155], v[232:235], v[60:63]
	v_mfma_f32_16x16x32_bf16 v[64:67], v[160:163], v[232:235], v[64:67]
	s_barrier
	s_add_i32 s25, 0, 0x18000
	s_add_i32 s31, 0, 0x1c000
	ds_read_b128 v[132:135], v1 offset:32768
	ds_read_b128 v[136:139], v204 offset:32768
	ds_read_b128 v[140:143], v1 offset:34816
	ds_read_b128 v[144:147], v204 offset:34816
	ds_read_b128 v[148:151], v1 offset:49152
	ds_read_b128 v[152:155], v204 offset:49152
	ds_read_b128 v[156:159], v1 offset:51200
	ds_read_b128 v[160:163], v204 offset:51200
	s_add_u32 s34, s40, 0x80000
	s_addc_u32 s35, s41, 0
	s_mov_b32 m0, s52
	ds_read_b128 v[164:167], v205 offset:32768
	ds_read_b128 v[168:171], v205 offset:34816
	ds_read_b128 v[172:175], v206 offset:32768
	ds_read_b128 v[176:179], v206 offset:34816
	ds_read_b128 v[190:193], v205 offset:36864
	ds_read_b128 v[194:197], v205 offset:38912
	ds_read_b128 v[198:201], v206 offset:36864
	ds_read_b128 v[232:235], v206 offset:38912
	global_load_lds_dwordx4 v188, s[34:35]
	s_mov_b32 m0, s53
	s_nop 0
	global_load_lds_dwordx4 v186, s[34:35]
	s_waitcnt vmcnt(8)
	s_waitcnt lgkmcnt(0)
	s_barrier
	v_mfma_f32_16x16x32_bf16 v[68:71], v[132:135], v[164:167], v[68:71]
	v_mfma_f32_16x16x32_bf16 v[72:75], v[140:143], v[164:167], v[72:75]
	v_mfma_f32_16x16x32_bf16 v[84:87], v[132:135], v[168:171], v[84:87]
	v_mfma_f32_16x16x32_bf16 v[88:91], v[140:143], v[168:171], v[88:91]
	v_mfma_f32_16x16x32_bf16 v[100:103], v[132:135], v[190:193], v[100:103]
	v_mfma_f32_16x16x32_bf16 v[104:107], v[140:143], v[190:193], v[104:107]
	v_mfma_f32_16x16x32_bf16 v[116:119], v[132:135], v[194:197], v[116:119]
	v_mfma_f32_16x16x32_bf16 v[120:123], v[140:143], v[194:197], v[120:123]
	v_mfma_f32_16x16x32_bf16 v[68:71], v[136:139], v[172:175], v[68:71]
	v_mfma_f32_16x16x32_bf16 v[72:75], v[144:147], v[172:175], v[72:75]
	v_mfma_f32_16x16x32_bf16 v[84:87], v[136:139], v[176:179], v[84:87]
	v_mfma_f32_16x16x32_bf16 v[88:91], v[144:147], v[176:179], v[88:91]
	v_mfma_f32_16x16x32_bf16 v[100:103], v[136:139], v[198:201], v[100:103]
	v_mfma_f32_16x16x32_bf16 v[104:107], v[144:147], v[198:201], v[104:107]
	v_mfma_f32_16x16x32_bf16 v[116:119], v[136:139], v[232:235], v[116:119]
	v_mfma_f32_16x16x32_bf16 v[120:123], v[144:147], v[232:235], v[120:123]
	v_mfma_f32_16x16x32_bf16 v[76:79], v[148:151], v[164:167], v[76:79]
	v_mfma_f32_16x16x32_bf16 v[80:83], v[156:159], v[164:167], v[80:83]
	v_mfma_f32_16x16x32_bf16 v[92:95], v[148:151], v[168:171], v[92:95]
	v_mfma_f32_16x16x32_bf16 v[96:99], v[156:159], v[168:171], v[96:99]
	v_mfma_f32_16x16x32_bf16 v[108:111], v[148:151], v[190:193], v[108:111]
	v_mfma_f32_16x16x32_bf16 v[112:115], v[156:159], v[190:193], v[112:115]
	v_mfma_f32_16x16x32_bf16 v[124:127], v[148:151], v[194:197], v[124:127]
	v_mfma_f32_16x16x32_bf16 v[128:131], v[156:159], v[194:197], v[128:131]
	v_mfma_f32_16x16x32_bf16 v[76:79], v[152:155], v[172:175], v[76:79]
	v_mfma_f32_16x16x32_bf16 v[80:83], v[160:163], v[172:175], v[80:83]
	v_mfma_f32_16x16x32_bf16 v[92:95], v[152:155], v[176:179], v[92:95]
	v_mfma_f32_16x16x32_bf16 v[96:99], v[160:163], v[176:179], v[96:99]
	v_mfma_f32_16x16x32_bf16 v[108:111], v[152:155], v[198:201], v[108:111]
	v_mfma_f32_16x16x32_bf16 v[112:115], v[160:163], v[198:201], v[112:115]
	v_mfma_f32_16x16x32_bf16 v[124:127], v[152:155], v[232:235], v[124:127]
	v_mfma_f32_16x16x32_bf16 v[128:131], v[160:163], v[232:235], v[128:131]
	s_barrier
	s_add_i32 s25, s25, s33
	s_add_i32 m0, s25, 0xffffff80
	ds_read_b128 v[164:167], v205 offset:49152
	ds_read_b128 v[168:171], v205 offset:51200
	ds_read_b128 v[172:175], v206 offset:49152
	ds_read_b128 v[176:179], v206 offset:51200
	ds_read_b128 v[190:193], v205 offset:53248
	ds_read_b128 v[194:197], v205 offset:55296
	ds_read_b128 v[198:201], v206 offset:53248
	ds_read_b128 v[232:235], v206 offset:55296
	global_load_lds_dwordx4 v34, s[28:29] offset:128
	s_add_i32 m0, s25, 0x1f80
	s_mov_b64 s[98:99], s[28:29]
	s_add_u32 s28, s28, 0x80080
	s_addc_u32 s29, s29, 0
	s_add_i32 s25, s31, s33
	global_load_lds_dwordx4 v184, s[98:99] offset:128
	s_mov_b32 m0, s25
	s_nop 0
	global_load_lds_dwordx4 v34, s[28:29]
	s_add_i32 m0, s25, 0x2000
	s_nop 0
	global_load_lds_dwordx4 v184, s[28:29]
	s_add_i32 m0, s54, 0xffffff80
	s_nop 0
	global_load_lds_dwordx4 v188, s[40:41] offset:128
	s_add_i32 m0, s55, 0xffffff80
	s_nop 0
	global_load_lds_dwordx4 v186, s[40:41] offset:128
	s_nop 0
	s_waitcnt vmcnt(8)
	s_waitcnt lgkmcnt(0)
	s_barrier
	v_mfma_f32_16x16x32_bf16 v[2:5], v[132:135], v[164:167], v[2:5]
	v_mfma_f32_16x16x32_bf16 v[6:9], v[140:143], v[164:167], v[6:9]
	v_mfma_f32_16x16x32_bf16 v[18:21], v[132:135], v[168:171], v[18:21]
	v_mfma_f32_16x16x32_bf16 v[22:25], v[140:143], v[168:171], v[22:25]
	v_mfma_f32_16x16x32_bf16 v[36:39], v[132:135], v[190:193], v[36:39]
	v_mfma_f32_16x16x32_bf16 v[40:43], v[140:143], v[190:193], v[40:43]
	v_mfma_f32_16x16x32_bf16 v[52:55], v[132:135], v[194:197], v[52:55]
	v_mfma_f32_16x16x32_bf16 v[56:59], v[140:143], v[194:197], v[56:59]
	v_mfma_f32_16x16x32_bf16 v[2:5], v[136:139], v[172:175], v[2:5]
	v_mfma_f32_16x16x32_bf16 v[6:9], v[144:147], v[172:175], v[6:9]
	v_mfma_f32_16x16x32_bf16 v[18:21], v[136:139], v[176:179], v[18:21]
	v_mfma_f32_16x16x32_bf16 v[22:25], v[144:147], v[176:179], v[22:25]
	v_mfma_f32_16x16x32_bf16 v[36:39], v[136:139], v[198:201], v[36:39]
	v_mfma_f32_16x16x32_bf16 v[40:43], v[144:147], v[198:201], v[40:43]
	v_mfma_f32_16x16x32_bf16 v[52:55], v[136:139], v[232:235], v[52:55]
	v_mfma_f32_16x16x32_bf16 v[56:59], v[144:147], v[232:235], v[56:59]
	v_mfma_f32_16x16x32_bf16 v[10:13], v[148:151], v[164:167], v[10:13]
	v_mfma_f32_16x16x32_bf16 v[14:17], v[156:159], v[164:167], v[14:17]
	v_mfma_f32_16x16x32_bf16 v[26:29], v[148:151], v[168:171], v[26:29]
	v_mfma_f32_16x16x32_bf16 v[30:33], v[156:159], v[168:171], v[30:33]
	v_mfma_f32_16x16x32_bf16 v[44:47], v[148:151], v[190:193], v[44:47]
	v_mfma_f32_16x16x32_bf16 v[48:51], v[156:159], v[190:193], v[48:51]
	v_mfma_f32_16x16x32_bf16 v[60:63], v[148:151], v[194:197], v[60:63]
	v_mfma_f32_16x16x32_bf16 v[64:67], v[156:159], v[194:197], v[64:67]
	v_mfma_f32_16x16x32_bf16 v[10:13], v[152:155], v[172:175], v[10:13]
	v_mfma_f32_16x16x32_bf16 v[14:17], v[160:163], v[172:175], v[14:17]
	v_mfma_f32_16x16x32_bf16 v[26:29], v[152:155], v[176:179], v[26:29]
	v_mfma_f32_16x16x32_bf16 v[30:33], v[160:163], v[176:179], v[30:33]
	v_mfma_f32_16x16x32_bf16 v[44:47], v[152:155], v[198:201], v[44:47]
	v_mfma_f32_16x16x32_bf16 v[48:51], v[160:163], v[198:201], v[48:51]
	v_mfma_f32_16x16x32_bf16 v[60:63], v[152:155], v[232:235], v[60:63]
	v_mfma_f32_16x16x32_bf16 v[64:67], v[160:163], v[232:235], v[64:67]
	s_barrier
	s_add_u32 s22, s22, 0x100
	s_addc_u32 s23, s23, 0
	s_add_u32 s21, s21, 0x100
	s_addc_u32 s24, s24, 0
	s_cmp_ge_u32 s30, s9
	s_mov_b32 s25, s30
	s_cbranch_scc0 .LBB0_908

.LBB0_1022:
	s_ashr_i32 s23, s22, 31
	s_lshl_b64 s[12:13], s[22:23], 20
	v_readlane_b32 s20, v254, 52
	v_readlane_b32 s21, v254, 53
	s_add_u32 s40, s20, s12
	s_addc_u32 s41, s21, s13
	s_and_b64 s[12:13], s[38:39], exec
	s_cselect_b32 s12, s41, s9
	s_cselect_b32 s13, s40, s8
	s_ashr_i32 s19, s18, 31
	s_lshl_b64 s[20:21], s[18:19], 20
	v_readlane_b32 s24, v254, 48
	v_readlane_b32 s25, v254, 49
	s_add_u32 s42, s24, s20
	s_addc_u32 s43, s25, s21
	s_and_b64 s[20:21], s[38:39], exec
	s_cselect_b32 s19, s43, s29
	s_cselect_b32 s20, s42, s28
	s_add_u32 s8, s8, 0x80080
	s_addc_u32 s9, s9, 0
	s_add_u32 s21, s28, 0x100
	s_addc_u32 s23, s29, 0
	s_mov_b32 s24, -2
	v_readlane_b32 s35, v255, 20
	v_readlane_b32 s57, v255, 21
	v_readlane_b32 s58, v255, 22
	v_readlane_b32 s59, v255, 23
	s_mov_b64 s[60:61], 0x80
	s_add_u32 s25, s8, 0xfff80080
	s_addc_u32 s28, s9, -1
	s_add_i32 s30, 0, 0x10000
	s_cmp_eq_u32 s24, 28
	s_cselect_b32 s45, s12, s28
	s_cselect_b32 s44, s13, s25
	s_cselect_b32 s29, s19, s23
	s_cselect_b32 s28, s20, s21
	s_add_i32 s25, 0, 0x14000
	ds_read_b128 v[138:141], v1
	ds_read_b128 v[142:145], v150
	ds_read_b128 v[146:149], v1 offset:2048
	ds_read_b128 v[154:157], v150 offset:2048
	ds_read_b128 v[158:161], v1 offset:16384
	ds_read_b128 v[162:165], v150 offset:16384
	ds_read_b128 v[166:169], v1 offset:18432
	ds_read_b128 v[170:173], v150 offset:18432
	s_add_i32 m0, s46, 0xc000
	ds_read_b128 v[174:177], v151
	ds_read_b128 v[184:187], v151 offset:2048
	ds_read_b128 v[188:191], v152
	ds_read_b128 v[192:195], v152 offset:2048
	ds_read_b128 v[196:199], v151 offset:4096
	ds_read_b128 v[200:203], v151 offset:6144
	ds_read_b128 v[204:207], v152 offset:4096
	ds_read_b128 v[208:211], v152 offset:6144
	global_load_lds_dwordx4 v136, s[8:9]
	s_add_i32 m0, s46, 0xe000
	s_nop 0
	global_load_lds_dwordx4 v134, s[8:9]
	s_nop 0
	s_waitcnt vmcnt(8)
	s_waitcnt lgkmcnt(0)
	s_barrier
	v_mfma_f32_16x16x32_bf16 v[128:131], v[138:141], v[174:177], 0
	v_mfma_f32_16x16x32_bf16 v[124:127], v[146:149], v[174:177], 0
	v_mfma_f32_16x16x32_bf16 v[112:115], v[138:141], v[184:187], 0
	v_mfma_f32_16x16x32_bf16 v[108:111], v[146:149], v[184:187], 0
	v_mfma_f32_16x16x32_bf16 v[96:99], v[138:141], v[196:199], 0
	v_mfma_f32_16x16x32_bf16 v[92:95], v[146:149], v[196:199], 0
	v_mfma_f32_16x16x32_bf16 v[80:83], v[138:141], v[200:203], 0
	v_mfma_f32_16x16x32_bf16 v[76:79], v[146:149], v[200:203], 0
	v_mfma_f32_16x16x32_bf16 v[128:131], v[142:145], v[188:191], v[128:131]
	v_mfma_f32_16x16x32_bf16 v[124:127], v[154:157], v[188:191], v[124:127]
	v_mfma_f32_16x16x32_bf16 v[112:115], v[142:145], v[192:195], v[112:115]
	v_mfma_f32_16x16x32_bf16 v[108:111], v[154:157], v[192:195], v[108:111]
	v_mfma_f32_16x16x32_bf16 v[96:99], v[142:145], v[204:207], v[96:99]
	v_mfma_f32_16x16x32_bf16 v[92:95], v[154:157], v[204:207], v[92:95]
	v_mfma_f32_16x16x32_bf16 v[80:83], v[142:145], v[208:211], v[80:83]
	v_mfma_f32_16x16x32_bf16 v[76:79], v[154:157], v[208:211], v[76:79]
	v_mfma_f32_16x16x32_bf16 v[120:123], v[158:161], v[174:177], 0
	v_mfma_f32_16x16x32_bf16 v[116:119], v[166:169], v[174:177], 0
	v_mfma_f32_16x16x32_bf16 v[104:107], v[158:161], v[184:187], 0
	v_mfma_f32_16x16x32_bf16 v[100:103], v[166:169], v[184:187], 0
	v_mfma_f32_16x16x32_bf16 v[88:91], v[158:161], v[196:199], 0
	v_mfma_f32_16x16x32_bf16 v[84:87], v[166:169], v[196:199], 0
	v_mfma_f32_16x16x32_bf16 v[72:75], v[158:161], v[200:203], 0
	v_mfma_f32_16x16x32_bf16 v[68:71], v[166:169], v[200:203], 0
	v_mfma_f32_16x16x32_bf16 v[120:123], v[162:165], v[188:191], v[120:123]
	v_mfma_f32_16x16x32_bf16 v[116:119], v[170:173], v[188:191], v[116:119]
	v_mfma_f32_16x16x32_bf16 v[104:107], v[162:165], v[192:195], v[104:107]
	v_mfma_f32_16x16x32_bf16 v[100:103], v[170:173], v[192:195], v[100:103]
	v_mfma_f32_16x16x32_bf16 v[88:91], v[162:165], v[204:207], v[88:91]
	v_mfma_f32_16x16x32_bf16 v[84:87], v[170:173], v[204:207], v[84:87]
	v_mfma_f32_16x16x32_bf16 v[72:75], v[162:165], v[208:211], v[72:75]
	v_mfma_f32_16x16x32_bf16 v[68:71], v[170:173], v[208:211], v[68:71]
	s_barrier
	s_add_i32 s30, s30, s33
	s_mov_b32 m0, s30
	ds_read_b128 v[174:177], v151 offset:16384
	ds_read_b128 v[184:187], v151 offset:18432
	ds_read_b128 v[188:191], v152 offset:16384
	ds_read_b128 v[192:195], v152 offset:18432
	ds_read_b128 v[196:199], v151 offset:20480
	ds_read_b128 v[200:203], v151 offset:22528
	ds_read_b128 v[204:207], v152 offset:20480
	ds_read_b128 v[208:211], v152 offset:22528
	global_load_lds_dwordx4 v34, s[28:29]
	s_add_i32 m0, s30, 0x2000
	s_add_u32 s30, s28, 0x80000
	s_addc_u32 s31, s29, 0
	s_add_i32 s25, s25, s33
	global_load_lds_dwordx4 v132, s[28:29]
	s_mov_b32 m0, s25
	s_nop 0
	global_load_lds_dwordx4 v34, s[30:31]
	s_add_i32 m0, s25, 0x2000
	s_nop 0
	global_load_lds_dwordx4 v132, s[30:31]
	s_mov_b32 m0, s46
	s_nop 0
	global_load_lds_dwordx4 v136, s[44:45]
	s_mov_b32 m0, s47
	s_nop 0
	global_load_lds_dwordx4 v134, s[44:45]
	s_nop 0
	s_waitcnt vmcnt(8)
	s_waitcnt lgkmcnt(0)
	s_barrier
	v_mfma_f32_16x16x32_bf16 v[64:67], v[138:141], v[174:177], 0
	v_mfma_f32_16x16x32_bf16 v[60:63], v[146:149], v[174:177], 0
	v_mfma_f32_16x16x32_bf16 v[48:51], v[138:141], v[184:187], 0
	v_mfma_f32_16x16x32_bf16 v[44:47], v[146:149], v[184:187], 0
	v_mfma_f32_16x16x32_bf16 v[30:33], v[138:141], v[196:199], 0
	v_mfma_f32_16x16x32_bf16 v[26:29], v[146:149], v[196:199], 0
	v_mfma_f32_16x16x32_bf16 v[14:17], v[138:141], v[200:203], 0
	v_mfma_f32_16x16x32_bf16 v[10:13], v[146:149], v[200:203], 0
	v_mfma_f32_16x16x32_bf16 v[64:67], v[142:145], v[188:191], v[64:67]
	v_mfma_f32_16x16x32_bf16 v[60:63], v[154:157], v[188:191], v[60:63]
	v_mfma_f32_16x16x32_bf16 v[48:51], v[142:145], v[192:195], v[48:51]
	v_mfma_f32_16x16x32_bf16 v[44:47], v[154:157], v[192:195], v[44:47]
	v_mfma_f32_16x16x32_bf16 v[30:33], v[142:145], v[204:207], v[30:33]
	v_mfma_f32_16x16x32_bf16 v[26:29], v[154:157], v[204:207], v[26:29]
	v_mfma_f32_16x16x32_bf16 v[14:17], v[142:145], v[208:211], v[14:17]
	v_mfma_f32_16x16x32_bf16 v[10:13], v[154:157], v[208:211], v[10:13]
	v_mfma_f32_16x16x32_bf16 v[56:59], v[158:161], v[174:177], 0
	v_mfma_f32_16x16x32_bf16 v[52:55], v[166:169], v[174:177], 0
	v_mfma_f32_16x16x32_bf16 v[40:43], v[158:161], v[184:187], 0
	v_mfma_f32_16x16x32_bf16 v[36:39], v[166:169], v[184:187], 0
	v_mfma_f32_16x16x32_bf16 v[22:25], v[158:161], v[196:199], 0
	v_mfma_f32_16x16x32_bf16 v[18:21], v[166:169], v[196:199], 0
	v_mfma_f32_16x16x32_bf16 v[6:9], v[158:161], v[200:203], 0
	v_mfma_f32_16x16x32_bf16 v[2:5], v[166:169], v[200:203], 0
	v_mfma_f32_16x16x32_bf16 v[56:59], v[162:165], v[188:191], v[56:59]
	v_mfma_f32_16x16x32_bf16 v[52:55], v[170:173], v[188:191], v[52:55]
	v_mfma_f32_16x16x32_bf16 v[40:43], v[162:165], v[192:195], v[40:43]
	v_mfma_f32_16x16x32_bf16 v[36:39], v[170:173], v[192:195], v[36:39]
	v_mfma_f32_16x16x32_bf16 v[22:25], v[162:165], v[204:207], v[22:25]
	v_mfma_f32_16x16x32_bf16 v[18:21], v[170:173], v[204:207], v[18:21]
	v_mfma_f32_16x16x32_bf16 v[6:9], v[162:165], v[208:211], v[6:9]
	v_mfma_f32_16x16x32_bf16 v[2:5], v[170:173], v[208:211], v[2:5]
	s_barrier
	s_add_i32 s25, 0, 0x18000
	s_add_i32 s34, 0, 0x1c000
	ds_read_b128 v[138:141], v1 offset:32768
	ds_read_b128 v[142:145], v150 offset:32768
	ds_read_b128 v[146:149], v1 offset:34816
	ds_read_b128 v[154:157], v150 offset:34816
	ds_read_b128 v[158:161], v1 offset:49152
	ds_read_b128 v[162:165], v150 offset:49152
	ds_read_b128 v[166:169], v1 offset:51200
	ds_read_b128 v[170:173], v150 offset:51200
	s_add_u32 s30, s44, 0x80000
	s_addc_u32 s31, s45, 0
	s_mov_b32 m0, s48
	ds_read_b128 v[174:177], v151 offset:32768
	ds_read_b128 v[184:187], v151 offset:34816
	ds_read_b128 v[188:191], v152 offset:32768
	ds_read_b128 v[192:195], v152 offset:34816
	ds_read_b128 v[196:199], v151 offset:36864
	ds_read_b128 v[200:203], v151 offset:38912
	ds_read_b128 v[204:207], v152 offset:36864
	ds_read_b128 v[208:211], v152 offset:38912
	global_load_lds_dwordx4 v136, s[30:31]
	s_mov_b32 m0, s49
	s_nop 0
	global_load_lds_dwordx4 v134, s[30:31]
	s_waitcnt vmcnt(8)
	s_waitcnt lgkmcnt(0)
	s_barrier
	v_mfma_f32_16x16x32_bf16 v[128:131], v[138:141], v[174:177], v[128:131]
	v_mfma_f32_16x16x32_bf16 v[124:127], v[146:149], v[174:177], v[124:127]
	v_mfma_f32_16x16x32_bf16 v[112:115], v[138:141], v[184:187], v[112:115]
	v_mfma_f32_16x16x32_bf16 v[108:111], v[146:149], v[184:187], v[108:111]
	v_mfma_f32_16x16x32_bf16 v[96:99], v[138:141], v[196:199], v[96:99]
	v_mfma_f32_16x16x32_bf16 v[92:95], v[146:149], v[196:199], v[92:95]
	v_mfma_f32_16x16x32_bf16 v[80:83], v[138:141], v[200:203], v[80:83]
	v_mfma_f32_16x16x32_bf16 v[76:79], v[146:149], v[200:203], v[76:79]
	v_mfma_f32_16x16x32_bf16 v[128:131], v[142:145], v[188:191], v[128:131]
	v_mfma_f32_16x16x32_bf16 v[124:127], v[154:157], v[188:191], v[124:127]
	v_mfma_f32_16x16x32_bf16 v[112:115], v[142:145], v[192:195], v[112:115]
	v_mfma_f32_16x16x32_bf16 v[108:111], v[154:157], v[192:195], v[108:111]
	v_mfma_f32_16x16x32_bf16 v[96:99], v[142:145], v[204:207], v[96:99]
	v_mfma_f32_16x16x32_bf16 v[92:95], v[154:157], v[204:207], v[92:95]
	v_mfma_f32_16x16x32_bf16 v[80:83], v[142:145], v[208:211], v[80:83]
	v_mfma_f32_16x16x32_bf16 v[76:79], v[154:157], v[208:211], v[76:79]
	v_mfma_f32_16x16x32_bf16 v[120:123], v[158:161], v[174:177], v[120:123]
	v_mfma_f32_16x16x32_bf16 v[116:119], v[166:169], v[174:177], v[116:119]
	v_mfma_f32_16x16x32_bf16 v[104:107], v[158:161], v[184:187], v[104:107]
	v_mfma_f32_16x16x32_bf16 v[100:103], v[166:169], v[184:187], v[100:103]
	v_mfma_f32_16x16x32_bf16 v[88:91], v[158:161], v[196:199], v[88:91]
	v_mfma_f32_16x16x32_bf16 v[84:87], v[166:169], v[196:199], v[84:87]
	v_mfma_f32_16x16x32_bf16 v[72:75], v[158:161], v[200:203], v[72:75]
	v_mfma_f32_16x16x32_bf16 v[68:71], v[166:169], v[200:203], v[68:71]
	v_mfma_f32_16x16x32_bf16 v[120:123], v[162:165], v[188:191], v[120:123]
	v_mfma_f32_16x16x32_bf16 v[116:119], v[170:173], v[188:191], v[116:119]
	v_mfma_f32_16x16x32_bf16 v[104:107], v[162:165], v[192:195], v[104:107]
	v_mfma_f32_16x16x32_bf16 v[100:103], v[170:173], v[192:195], v[100:103]
	v_mfma_f32_16x16x32_bf16 v[88:91], v[162:165], v[204:207], v[88:91]
	v_mfma_f32_16x16x32_bf16 v[84:87], v[170:173], v[204:207], v[84:87]
	v_mfma_f32_16x16x32_bf16 v[72:75], v[162:165], v[208:211], v[72:75]
	v_mfma_f32_16x16x32_bf16 v[68:71], v[170:173], v[208:211], v[68:71]
	s_barrier
	s_add_i32 s25, s25, s33
	s_add_i32 m0, s25, 0xffffff80
	ds_read_b128 v[174:177], v151 offset:49152
	ds_read_b128 v[184:187], v151 offset:51200
	ds_read_b128 v[188:191], v152 offset:49152
	ds_read_b128 v[192:195], v152 offset:51200
	ds_read_b128 v[196:199], v151 offset:53248
	ds_read_b128 v[200:203], v151 offset:55296
	ds_read_b128 v[204:207], v152 offset:53248
	ds_read_b128 v[208:211], v152 offset:55296
	global_load_lds_dwordx4 v34, s[28:29] offset:128
	s_add_i32 m0, s25, 0x1f80
	s_mov_b64 s[98:99], s[28:29]
	s_add_u32 s28, s28, 0x80080
	s_addc_u32 s29, s29, 0
	s_add_i32 s25, s34, s33
	global_load_lds_dwordx4 v132, s[98:99] offset:128
	s_mov_b32 m0, s25
	s_nop 0
	global_load_lds_dwordx4 v34, s[28:29]
	s_add_i32 m0, s25, 0x2000
	s_nop 0
	global_load_lds_dwordx4 v132, s[28:29]
	s_add_i32 m0, s52, 0xffffff80
	s_nop 0
	global_load_lds_dwordx4 v136, s[44:45] offset:128
	s_add_i32 m0, s53, 0xffffff80
	s_nop 0
	global_load_lds_dwordx4 v134, s[44:45] offset:128
	s_nop 0
	s_waitcnt vmcnt(8)
	s_waitcnt lgkmcnt(0)
	s_barrier
	v_mfma_f32_16x16x32_bf16 v[64:67], v[138:141], v[174:177], v[64:67]
	v_mfma_f32_16x16x32_bf16 v[60:63], v[146:149], v[174:177], v[60:63]
	v_mfma_f32_16x16x32_bf16 v[48:51], v[138:141], v[184:187], v[48:51]
	v_mfma_f32_16x16x32_bf16 v[44:47], v[146:149], v[184:187], v[44:47]
	v_mfma_f32_16x16x32_bf16 v[30:33], v[138:141], v[196:199], v[30:33]
	v_mfma_f32_16x16x32_bf16 v[26:29], v[146:149], v[196:199], v[26:29]
	v_mfma_f32_16x16x32_bf16 v[14:17], v[138:141], v[200:203], v[14:17]
	v_mfma_f32_16x16x32_bf16 v[10:13], v[146:149], v[200:203], v[10:13]
	v_mfma_f32_16x16x32_bf16 v[64:67], v[142:145], v[188:191], v[64:67]
	v_mfma_f32_16x16x32_bf16 v[60:63], v[154:157], v[188:191], v[60:63]
	v_mfma_f32_16x16x32_bf16 v[48:51], v[142:145], v[192:195], v[48:51]
	v_mfma_f32_16x16x32_bf16 v[44:47], v[154:157], v[192:195], v[44:47]
	v_mfma_f32_16x16x32_bf16 v[30:33], v[142:145], v[204:207], v[30:33]
	v_mfma_f32_16x16x32_bf16 v[26:29], v[154:157], v[204:207], v[26:29]
	v_mfma_f32_16x16x32_bf16 v[14:17], v[142:145], v[208:211], v[14:17]
	v_mfma_f32_16x16x32_bf16 v[10:13], v[154:157], v[208:211], v[10:13]
	v_mfma_f32_16x16x32_bf16 v[56:59], v[158:161], v[174:177], v[56:59]
	v_mfma_f32_16x16x32_bf16 v[52:55], v[166:169], v[174:177], v[52:55]
	v_mfma_f32_16x16x32_bf16 v[40:43], v[158:161], v[184:187], v[40:43]
	v_mfma_f32_16x16x32_bf16 v[36:39], v[166:169], v[184:187], v[36:39]
	v_mfma_f32_16x16x32_bf16 v[22:25], v[158:161], v[196:199], v[22:25]
	v_mfma_f32_16x16x32_bf16 v[18:21], v[166:169], v[196:199], v[18:21]
	v_mfma_f32_16x16x32_bf16 v[6:9], v[158:161], v[200:203], v[6:9]
	v_mfma_f32_16x16x32_bf16 v[2:5], v[166:169], v[200:203], v[2:5]
	v_mfma_f32_16x16x32_bf16 v[56:59], v[162:165], v[188:191], v[56:59]
	v_mfma_f32_16x16x32_bf16 v[52:55], v[170:173], v[188:191], v[52:55]
	v_mfma_f32_16x16x32_bf16 v[40:43], v[162:165], v[192:195], v[40:43]
	v_mfma_f32_16x16x32_bf16 v[36:39], v[170:173], v[192:195], v[36:39]
	v_mfma_f32_16x16x32_bf16 v[22:25], v[162:165], v[204:207], v[22:25]
	v_mfma_f32_16x16x32_bf16 v[18:21], v[170:173], v[204:207], v[18:21]
	v_mfma_f32_16x16x32_bf16 v[6:9], v[162:165], v[208:211], v[6:9]
	v_mfma_f32_16x16x32_bf16 v[2:5], v[170:173], v[208:211], v[2:5]
	s_barrier
	s_add_i32 s24, s24, 2
	s_add_u32 s8, s8, 0x100
	s_addc_u32 s9, s9, 0
	s_add_u32 s21, s21, 0x100
	s_addc_u32 s23, s23, 0
	s_cmp_gt_u32 s24, 29
	s_cbranch_scc1 .Lpeel_done_P4
.LBB0_1023:
	s_add_u32 s25, s8, 0xfff80080
	s_addc_u32 s28, s9, -1
	s_add_i32 s30, 0, 0x10000
	s_cmp_eq_u32 s24, 28
	s_cselect_b32 s45, s12, s28
	s_cselect_b32 s44, s13, s25
	s_cselect_b32 s29, s19, s23
	s_cselect_b32 s28, s20, s21
	s_add_i32 s25, 0, 0x14000
	ds_read_b128 v[138:141], v1
	ds_read_b128 v[142:145], v150
	ds_read_b128 v[146:149], v1 offset:2048
	ds_read_b128 v[154:157], v150 offset:2048
	ds_read_b128 v[158:161], v1 offset:16384
	ds_read_b128 v[162:165], v150 offset:16384
	ds_read_b128 v[166:169], v1 offset:18432
	ds_read_b128 v[170:173], v150 offset:18432
	s_add_i32 m0, s46, 0xc000
	ds_read_b128 v[174:177], v151
	ds_read_b128 v[184:187], v151 offset:2048
	ds_read_b128 v[188:191], v152
	ds_read_b128 v[192:195], v152 offset:2048
	ds_read_b128 v[196:199], v151 offset:4096
	ds_read_b128 v[200:203], v151 offset:6144
	ds_read_b128 v[204:207], v152 offset:4096
	ds_read_b128 v[208:211], v152 offset:6144
	global_load_lds_dwordx4 v136, s[8:9]
	s_add_i32 m0, s46, 0xe000
	s_nop 0
	global_load_lds_dwordx4 v134, s[8:9]
	s_waitcnt vmcnt(8)
	s_waitcnt lgkmcnt(0)
	s_barrier
	v_mfma_f32_16x16x32_bf16 v[128:131], v[138:141], v[174:177], v[128:131]
	v_mfma_f32_16x16x32_bf16 v[124:127], v[146:149], v[174:177], v[124:127]
	v_mfma_f32_16x16x32_bf16 v[112:115], v[138:141], v[184:187], v[112:115]
	v_mfma_f32_16x16x32_bf16 v[108:111], v[146:149], v[184:187], v[108:111]
	v_mfma_f32_16x16x32_bf16 v[96:99], v[138:141], v[196:199], v[96:99]
	v_mfma_f32_16x16x32_bf16 v[92:95], v[146:149], v[196:199], v[92:95]
	v_mfma_f32_16x16x32_bf16 v[80:83], v[138:141], v[200:203], v[80:83]
	v_mfma_f32_16x16x32_bf16 v[76:79], v[146:149], v[200:203], v[76:79]
	v_mfma_f32_16x16x32_bf16 v[128:131], v[142:145], v[188:191], v[128:131]
	v_mfma_f32_16x16x32_bf16 v[124:127], v[154:157], v[188:191], v[124:127]
	v_mfma_f32_16x16x32_bf16 v[112:115], v[142:145], v[192:195], v[112:115]
	v_mfma_f32_16x16x32_bf16 v[108:111], v[154:157], v[192:195], v[108:111]
	v_mfma_f32_16x16x32_bf16 v[96:99], v[142:145], v[204:207], v[96:99]
	v_mfma_f32_16x16x32_bf16 v[92:95], v[154:157], v[204:207], v[92:95]
	v_mfma_f32_16x16x32_bf16 v[80:83], v[142:145], v[208:211], v[80:83]
	v_mfma_f32_16x16x32_bf16 v[76:79], v[154:157], v[208:211], v[76:79]
	v_mfma_f32_16x16x32_bf16 v[120:123], v[158:161], v[174:177], v[120:123]
	v_mfma_f32_16x16x32_bf16 v[116:119], v[166:169], v[174:177], v[116:119]
	v_mfma_f32_16x16x32_bf16 v[104:107], v[158:161], v[184:187], v[104:107]
	v_mfma_f32_16x16x32_bf16 v[100:103], v[166:169], v[184:187], v[100:103]
	v_mfma_f32_16x16x32_bf16 v[88:91], v[158:161], v[196:199], v[88:91]
	v_mfma_f32_16x16x32_bf16 v[84:87], v[166:169], v[196:199], v[84:87]
	v_mfma_f32_16x16x32_bf16 v[72:75], v[158:161], v[200:203], v[72:75]
	v_mfma_f32_16x16x32_bf16 v[68:71], v[166:169], v[200:203], v[68:71]
	v_mfma_f32_16x16x32_bf16 v[120:123], v[162:165], v[188:191], v[120:123]
	v_mfma_f32_16x16x32_bf16 v[116:119], v[170:173], v[188:191], v[116:119]
	v_mfma_f32_16x16x32_bf16 v[104:107], v[162:165], v[192:195], v[104:107]
	v_mfma_f32_16x16x32_bf16 v[100:103], v[170:173], v[192:195], v[100:103]
	v_mfma_f32_16x16x32_bf16 v[88:91], v[162:165], v[204:207], v[88:91]
	v_mfma_f32_16x16x32_bf16 v[84:87], v[170:173], v[204:207], v[84:87]
	v_mfma_f32_16x16x32_bf16 v[72:75], v[162:165], v[208:211], v[72:75]
	v_mfma_f32_16x16x32_bf16 v[68:71], v[170:173], v[208:211], v[68:71]
	s_barrier
	s_add_i32 s30, s30, s33
	s_mov_b32 m0, s30
	ds_read_b128 v[174:177], v151 offset:16384
	ds_read_b128 v[184:187], v151 offset:18432
	ds_read_b128 v[188:191], v152 offset:16384
	ds_read_b128 v[192:195], v152 offset:18432
	ds_read_b128 v[196:199], v151 offset:20480
	ds_read_b128 v[200:203], v151 offset:22528
	ds_read_b128 v[204:207], v152 offset:20480
	ds_read_b128 v[208:211], v152 offset:22528
	global_load_lds_dwordx4 v34, s[28:29]
	s_add_i32 m0, s30, 0x2000
	s_add_u32 s30, s28, 0x80000
	s_addc_u32 s31, s29, 0
	s_add_i32 s25, s25, s33
	global_load_lds_dwordx4 v132, s[28:29]
	s_mov_b32 m0, s25
	s_nop 0
	global_load_lds_dwordx4 v34, s[30:31]
	s_add_i32 m0, s25, 0x2000
	s_nop 0
	global_load_lds_dwordx4 v132, s[30:31]
	s_mov_b32 m0, s46
	s_nop 0
	global_load_lds_dwordx4 v136, s[44:45]
	s_mov_b32 m0, s47
	s_nop 0
	global_load_lds_dwordx4 v134, s[44:45]
	s_nop 0
	s_waitcnt vmcnt(8)
	s_waitcnt lgkmcnt(0)
	s_barrier
	v_mfma_f32_16x16x32_bf16 v[64:67], v[138:141], v[174:177], v[64:67]
	v_mfma_f32_16x16x32_bf16 v[60:63], v[146:149], v[174:177], v[60:63]
	v_mfma_f32_16x16x32_bf16 v[48:51], v[138:141], v[184:187], v[48:51]
	v_mfma_f32_16x16x32_bf16 v[44:47], v[146:149], v[184:187], v[44:47]
	v_mfma_f32_16x16x32_bf16 v[30:33], v[138:141], v[196:199], v[30:33]
	v_mfma_f32_16x16x32_bf16 v[26:29], v[146:149], v[196:199], v[26:29]
	v_mfma_f32_16x16x32_bf16 v[14:17], v[138:141], v[200:203], v[14:17]
	v_mfma_f32_16x16x32_bf16 v[10:13], v[146:149], v[200:203], v[10:13]
	v_mfma_f32_16x16x32_bf16 v[64:67], v[142:145], v[188:191], v[64:67]
	v_mfma_f32_16x16x32_bf16 v[60:63], v[154:157], v[188:191], v[60:63]
	v_mfma_f32_16x16x32_bf16 v[48:51], v[142:145], v[192:195], v[48:51]
	v_mfma_f32_16x16x32_bf16 v[44:47], v[154:157], v[192:195], v[44:47]
	v_mfma_f32_16x16x32_bf16 v[30:33], v[142:145], v[204:207], v[30:33]
	v_mfma_f32_16x16x32_bf16 v[26:29], v[154:157], v[204:207], v[26:29]
	v_mfma_f32_16x16x32_bf16 v[14:17], v[142:145], v[208:211], v[14:17]
	v_mfma_f32_16x16x32_bf16 v[10:13], v[154:157], v[208:211], v[10:13]
	v_mfma_f32_16x16x32_bf16 v[56:59], v[158:161], v[174:177], v[56:59]
	v_mfma_f32_16x16x32_bf16 v[52:55], v[166:169], v[174:177], v[52:55]
	v_mfma_f32_16x16x32_bf16 v[40:43], v[158:161], v[184:187], v[40:43]
	v_mfma_f32_16x16x32_bf16 v[36:39], v[166:169], v[184:187], v[36:39]
	v_mfma_f32_16x16x32_bf16 v[22:25], v[158:161], v[196:199], v[22:25]
	v_mfma_f32_16x16x32_bf16 v[18:21], v[166:169], v[196:199], v[18:21]
	v_mfma_f32_16x16x32_bf16 v[6:9], v[158:161], v[200:203], v[6:9]
	v_mfma_f32_16x16x32_bf16 v[2:5], v[166:169], v[200:203], v[2:5]
	v_mfma_f32_16x16x32_bf16 v[56:59], v[162:165], v[188:191], v[56:59]
	v_mfma_f32_16x16x32_bf16 v[52:55], v[170:173], v[188:191], v[52:55]
	v_mfma_f32_16x16x32_bf16 v[40:43], v[162:165], v[192:195], v[40:43]
	v_mfma_f32_16x16x32_bf16 v[36:39], v[170:173], v[192:195], v[36:39]
	v_mfma_f32_16x16x32_bf16 v[22:25], v[162:165], v[204:207], v[22:25]
	v_mfma_f32_16x16x32_bf16 v[18:21], v[170:173], v[204:207], v[18:21]
	v_mfma_f32_16x16x32_bf16 v[6:9], v[162:165], v[208:211], v[6:9]
	v_mfma_f32_16x16x32_bf16 v[2:5], v[170:173], v[208:211], v[2:5]
	s_barrier
	s_add_i32 s25, 0, 0x18000
	s_add_i32 s34, 0, 0x1c000
	ds_read_b128 v[138:141], v1 offset:32768
	ds_read_b128 v[142:145], v150 offset:32768
	ds_read_b128 v[146:149], v1 offset:34816
	ds_read_b128 v[154:157], v150 offset:34816
	ds_read_b128 v[158:161], v1 offset:49152
	ds_read_b128 v[162:165], v150 offset:49152
	ds_read_b128 v[166:169], v1 offset:51200
	ds_read_b128 v[170:173], v150 offset:51200
	s_add_u32 s30, s44, 0x80000
	s_addc_u32 s31, s45, 0
	s_mov_b32 m0, s48
	ds_read_b128 v[174:177], v151 offset:32768
	ds_read_b128 v[184:187], v151 offset:34816
	ds_read_b128 v[188:191], v152 offset:32768
	ds_read_b128 v[192:195], v152 offset:34816
	ds_read_b128 v[196:199], v151 offset:36864
	ds_read_b128 v[200:203], v151 offset:38912
	ds_read_b128 v[204:207], v152 offset:36864
	ds_read_b128 v[208:211], v152 offset:38912
	global_load_lds_dwordx4 v136, s[30:31]
	s_mov_b32 m0, s49
	s_nop 0
	global_load_lds_dwordx4 v134, s[30:31]
	s_waitcnt vmcnt(8)
	s_waitcnt lgkmcnt(0)
	s_barrier
	v_mfma_f32_16x16x32_bf16 v[128:131], v[138:141], v[174:177], v[128:131]
	v_mfma_f32_16x16x32_bf16 v[124:127], v[146:149], v[174:177], v[124:127]
	v_mfma_f32_16x16x32_bf16 v[112:115], v[138:141], v[184:187], v[112:115]
	v_mfma_f32_16x16x32_bf16 v[108:111], v[146:149], v[184:187], v[108:111]
	v_mfma_f32_16x16x32_bf16 v[96:99], v[138:141], v[196:199], v[96:99]
	v_mfma_f32_16x16x32_bf16 v[92:95], v[146:149], v[196:199], v[92:95]
	v_mfma_f32_16x16x32_bf16 v[80:83], v[138:141], v[200:203], v[80:83]
	v_mfma_f32_16x16x32_bf16 v[76:79], v[146:149], v[200:203], v[76:79]
	v_mfma_f32_16x16x32_bf16 v[128:131], v[142:145], v[188:191], v[128:131]
	v_mfma_f32_16x16x32_bf16 v[124:127], v[154:157], v[188:191], v[124:127]
	v_mfma_f32_16x16x32_bf16 v[112:115], v[142:145], v[192:195], v[112:115]
	v_mfma_f32_16x16x32_bf16 v[108:111], v[154:157], v[192:195], v[108:111]
	v_mfma_f32_16x16x32_bf16 v[96:99], v[142:145], v[204:207], v[96:99]
	v_mfma_f32_16x16x32_bf16 v[92:95], v[154:157], v[204:207], v[92:95]
	v_mfma_f32_16x16x32_bf16 v[80:83], v[142:145], v[208:211], v[80:83]
	v_mfma_f32_16x16x32_bf16 v[76:79], v[154:157], v[208:211], v[76:79]
	v_mfma_f32_16x16x32_bf16 v[120:123], v[158:161], v[174:177], v[120:123]
	v_mfma_f32_16x16x32_bf16 v[116:119], v[166:169], v[174:177], v[116:119]
	v_mfma_f32_16x16x32_bf16 v[104:107], v[158:161], v[184:187], v[104:107]
	v_mfma_f32_16x16x32_bf16 v[100:103], v[166:169], v[184:187], v[100:103]
	v_mfma_f32_16x16x32_bf16 v[88:91], v[158:161], v[196:199], v[88:91]
	v_mfma_f32_16x16x32_bf16 v[84:87], v[166:169], v[196:199], v[84:87]
	v_mfma_f32_16x16x32_bf16 v[72:75], v[158:161], v[200:203], v[72:75]
	v_mfma_f32_16x16x32_bf16 v[68:71], v[166:169], v[200:203], v[68:71]
	v_mfma_f32_16x16x32_bf16 v[120:123], v[162:165], v[188:191], v[120:123]
	v_mfma_f32_16x16x32_bf16 v[116:119], v[170:173], v[188:191], v[116:119]
	v_mfma_f32_16x16x32_bf16 v[104:107], v[162:165], v[192:195], v[104:107]
	v_mfma_f32_16x16x32_bf16 v[100:103], v[170:173], v[192:195], v[100:103]
	v_mfma_f32_16x16x32_bf16 v[88:91], v[162:165], v[204:207], v[88:91]
	v_mfma_f32_16x16x32_bf16 v[84:87], v[170:173], v[204:207], v[84:87]
	v_mfma_f32_16x16x32_bf16 v[72:75], v[162:165], v[208:211], v[72:75]
	v_mfma_f32_16x16x32_bf16 v[68:71], v[170:173], v[208:211], v[68:71]
	s_barrier
	s_add_i32 s25, s25, s33
	s_add_i32 m0, s25, 0xffffff80
	ds_read_b128 v[174:177], v151 offset:49152
	ds_read_b128 v[184:187], v151 offset:51200
	ds_read_b128 v[188:191], v152 offset:49152
	ds_read_b128 v[192:195], v152 offset:51200
	ds_read_b128 v[196:199], v151 offset:53248
	ds_read_b128 v[200:203], v151 offset:55296
	ds_read_b128 v[204:207], v152 offset:53248
	ds_read_b128 v[208:211], v152 offset:55296
	global_load_lds_dwordx4 v34, s[28:29] offset:128
	s_add_i32 m0, s25, 0x1f80
	s_mov_b64 s[98:99], s[28:29]
	s_add_u32 s28, s28, 0x80080
	s_addc_u32 s29, s29, 0
	s_add_i32 s25, s34, s33
	global_load_lds_dwordx4 v132, s[98:99] offset:128
	s_mov_b32 m0, s25
	s_nop 0
	global_load_lds_dwordx4 v34, s[28:29]
	s_add_i32 m0, s25, 0x2000
	s_nop 0
	global_load_lds_dwordx4 v132, s[28:29]
	s_add_i32 m0, s52, 0xffffff80
	s_nop 0
	global_load_lds_dwordx4 v136, s[44:45] offset:128
	s_add_i32 m0, s53, 0xffffff80
	s_nop 0
	global_load_lds_dwordx4 v134, s[44:45] offset:128
	s_nop 0
	s_waitcnt vmcnt(8)
	s_waitcnt lgkmcnt(0)
	s_barrier
	v_mfma_f32_16x16x32_bf16 v[64:67], v[138:141], v[174:177], v[64:67]
	v_mfma_f32_16x16x32_bf16 v[60:63], v[146:149], v[174:177], v[60:63]
	v_mfma_f32_16x16x32_bf16 v[48:51], v[138:141], v[184:187], v[48:51]
	v_mfma_f32_16x16x32_bf16 v[44:47], v[146:149], v[184:187], v[44:47]
	v_mfma_f32_16x16x32_bf16 v[30:33], v[138:141], v[196:199], v[30:33]
	v_mfma_f32_16x16x32_bf16 v[26:29], v[146:149], v[196:199], v[26:29]
	v_mfma_f32_16x16x32_bf16 v[14:17], v[138:141], v[200:203], v[14:17]
	v_mfma_f32_16x16x32_bf16 v[10:13], v[146:149], v[200:203], v[10:13]
	v_mfma_f32_16x16x32_bf16 v[64:67], v[142:145], v[188:191], v[64:67]
	v_mfma_f32_16x16x32_bf16 v[60:63], v[154:157], v[188:191], v[60:63]
	v_mfma_f32_16x16x32_bf16 v[48:51], v[142:145], v[192:195], v[48:51]
	v_mfma_f32_16x16x32_bf16 v[44:47], v[154:157], v[192:195], v[44:47]
	v_mfma_f32_16x16x32_bf16 v[30:33], v[142:145], v[204:207], v[30:33]
	v_mfma_f32_16x16x32_bf16 v[26:29], v[154:157], v[204:207], v[26:29]
	v_mfma_f32_16x16x32_bf16 v[14:17], v[142:145], v[208:211], v[14:17]
	v_mfma_f32_16x16x32_bf16 v[10:13], v[154:157], v[208:211], v[10:13]
	v_mfma_f32_16x16x32_bf16 v[56:59], v[158:161], v[174:177], v[56:59]
	v_mfma_f32_16x16x32_bf16 v[52:55], v[166:169], v[174:177], v[52:55]
	v_mfma_f32_16x16x32_bf16 v[40:43], v[158:161], v[184:187], v[40:43]
	v_mfma_f32_16x16x32_bf16 v[36:39], v[166:169], v[184:187], v[36:39]
	v_mfma_f32_16x16x32_bf16 v[22:25], v[158:161], v[196:199], v[22:25]
	v_mfma_f32_16x16x32_bf16 v[18:21], v[166:169], v[196:199], v[18:21]
	v_mfma_f32_16x16x32_bf16 v[6:9], v[158:161], v[200:203], v[6:9]
	v_mfma_f32_16x16x32_bf16 v[2:5], v[166:169], v[200:203], v[2:5]
	v_mfma_f32_16x16x32_bf16 v[56:59], v[162:165], v[188:191], v[56:59]
	v_mfma_f32_16x16x32_bf16 v[52:55], v[170:173], v[188:191], v[52:55]
	v_mfma_f32_16x16x32_bf16 v[40:43], v[162:165], v[192:195], v[40:43]
	v_mfma_f32_16x16x32_bf16 v[36:39], v[170:173], v[192:195], v[36:39]
	v_mfma_f32_16x16x32_bf16 v[22:25], v[162:165], v[204:207], v[22:25]
	v_mfma_f32_16x16x32_bf16 v[18:21], v[170:173], v[204:207], v[18:21]
	v_mfma_f32_16x16x32_bf16 v[6:9], v[162:165], v[208:211], v[6:9]
	v_mfma_f32_16x16x32_bf16 v[2:5], v[170:173], v[208:211], v[2:5]
	s_barrier
	s_add_i32 s24, s24, 2
	s_add_u32 s8, s8, 0x100
	s_addc_u32 s9, s9, 0
	s_add_u32 s21, s21, 0x100
	s_addc_u32 s23, s23, 0
	s_cmp_gt_u32 s24, 29
	s_cbranch_scc0 .LBB0_1023

.LBB0_1113:
	s_ashr_i32 s19, s18, 31
	s_lshl_b64 s[20:21], s[18:19], 20
	v_readlane_b32 s22, v254, 38
	v_readlane_b32 s23, v254, 39
	s_add_u32 s22, s22, s20
	s_addc_u32 s23, s23, s21
	s_and_b64 s[20:21], s[38:39], exec
	s_cselect_b32 s13, s23, s9
	s_cselect_b32 s19, s22, s8
	s_ashr_i32 s11, s10, 31
	s_lshl_b64 s[20:21], s[10:11], 20
	v_readlane_b32 s30, v254, 8
	v_readlane_b32 s31, v254, 9
	s_add_u32 s40, s30, s20
	s_addc_u32 s41, s31, s21
	v_mov_b32_e32 v2, v0
	s_and_b64 s[20:21], s[38:39], exec
	s_cselect_b32 s20, s41, s29
	s_cselect_b32 s21, s40, s28
	s_lshl_b32 s11, s24, 8
	v_and_or_b32 v2, v2, 63, s50
	v_or_b32_e32 v2, s11, v2
	v_ashrrev_i32_e32 v3, 31, v2
	v_readlane_b32 s24, v252, 61
	v_lshlrev_b64 v[2:3], 5, v[2:3]
	v_readlane_b32 s25, v252, 62
	s_add_u32 s8, s8, 0x80080
	s_addc_u32 s9, s9, 0
	v_lshl_add_u64 v[2:3], s[24:25], 0, v[2:3]
	global_load_dwordx4 v[116:119], v[2:3], off offset:16
	global_load_dwordx4 v[120:123], v[2:3], off
	s_add_u32 s24, s28, 0x100
	s_addc_u32 s25, s29, 0
	s_mov_b32 s30, -2
	v_readlane_b32 s57, v255, 20
	v_readlane_b32 s58, v255, 21
	v_readlane_b32 s59, v255, 22
	v_readlane_b32 s60, v255, 23
	s_mov_b64 s[62:63], 0x80
	s_add_u32 s28, s8, 0xfff80080
	s_addc_u32 s29, s9, -1
	s_add_i32 s31, 0, 0x10000
	s_cmp_eq_u32 s30, 28
	s_cselect_b32 s43, s13, s29
	s_cselect_b32 s42, s19, s28
	ds_read_b128 v[150:153], v1
	ds_read_b128 v[154:157], v146
	s_cselect_b32 s29, s20, s25
	s_cselect_b32 s28, s21, s24
	s_add_i32 s56, 0, 0x14000
	ds_read_b128 v[158:161], v1 offset:2048
	ds_read_b128 v[162:165], v146 offset:2048
	ds_read_b128 v[166:169], v1 offset:16384
	ds_read_b128 v[170:173], v146 offset:16384
	ds_read_b128 v[174:177], v1 offset:18432
	ds_read_b128 v[184:187], v146 offset:18432
	s_add_i32 m0, s34, 0xc000
	ds_read_b128 v[188:191], v147
	ds_read_b128 v[192:195], v147 offset:2048
	ds_read_b128 v[196:199], v148
	ds_read_b128 v[200:203], v148 offset:2048
	ds_read_b128 v[204:207], v147 offset:4096
	ds_read_b128 v[208:211], v147 offset:6144
	ds_read_b128 v[224:227], v148 offset:4096
	ds_read_b128 v[228:231], v148 offset:6144
	global_load_lds_dwordx4 v144, s[8:9]
	s_add_i32 m0, s34, 0xe000
	s_nop 0
	global_load_lds_dwordx4 v142, s[8:9]
	s_waitcnt vmcnt(8)
	s_waitcnt lgkmcnt(0)
	s_barrier
	v_mfma_f32_16x16x32_bf16 v[132:135], v[150:153], v[188:191], 0
	v_mfma_f32_16x16x32_bf16 v[124:127], v[158:161], v[188:191], 0
	v_mfma_f32_16x16x32_bf16 v[108:111], v[150:153], v[192:195], 0
	v_mfma_f32_16x16x32_bf16 v[100:103], v[158:161], v[192:195], 0
	v_mfma_f32_16x16x32_bf16 v[92:95], v[150:153], v[204:207], 0
	v_mfma_f32_16x16x32_bf16 v[84:87], v[158:161], v[204:207], 0
	v_mfma_f32_16x16x32_bf16 v[76:79], v[150:153], v[208:211], 0
	v_mfma_f32_16x16x32_bf16 v[68:71], v[158:161], v[208:211], 0
	v_mfma_f32_16x16x32_bf16 v[132:135], v[154:157], v[196:199], v[132:135]
	v_mfma_f32_16x16x32_bf16 v[124:127], v[162:165], v[196:199], v[124:127]
	v_mfma_f32_16x16x32_bf16 v[108:111], v[154:157], v[200:203], v[108:111]
	v_mfma_f32_16x16x32_bf16 v[100:103], v[162:165], v[200:203], v[100:103]
	v_mfma_f32_16x16x32_bf16 v[92:95], v[154:157], v[224:227], v[92:95]
	v_mfma_f32_16x16x32_bf16 v[84:87], v[162:165], v[224:227], v[84:87]
	v_mfma_f32_16x16x32_bf16 v[76:79], v[154:157], v[228:231], v[76:79]
	v_mfma_f32_16x16x32_bf16 v[68:71], v[162:165], v[228:231], v[68:71]
	v_mfma_f32_16x16x32_bf16 v[136:139], v[166:169], v[188:191], 0
	v_mfma_f32_16x16x32_bf16 v[128:131], v[174:177], v[188:191], 0
	v_mfma_f32_16x16x32_bf16 v[112:115], v[166:169], v[192:195], 0
	v_mfma_f32_16x16x32_bf16 v[104:107], v[174:177], v[192:195], 0
	v_mfma_f32_16x16x32_bf16 v[96:99], v[166:169], v[204:207], 0
	v_mfma_f32_16x16x32_bf16 v[88:91], v[174:177], v[204:207], 0
	v_mfma_f32_16x16x32_bf16 v[80:83], v[166:169], v[208:211], 0
	v_mfma_f32_16x16x32_bf16 v[72:75], v[174:177], v[208:211], 0
	v_mfma_f32_16x16x32_bf16 v[136:139], v[170:173], v[196:199], v[136:139]
	v_mfma_f32_16x16x32_bf16 v[128:131], v[184:187], v[196:199], v[128:131]
	v_mfma_f32_16x16x32_bf16 v[112:115], v[170:173], v[200:203], v[112:115]
	v_mfma_f32_16x16x32_bf16 v[104:107], v[184:187], v[200:203], v[104:107]
	v_mfma_f32_16x16x32_bf16 v[96:99], v[170:173], v[224:227], v[96:99]
	v_mfma_f32_16x16x32_bf16 v[88:91], v[184:187], v[224:227], v[88:91]
	v_mfma_f32_16x16x32_bf16 v[80:83], v[170:173], v[228:231], v[80:83]
	v_mfma_f32_16x16x32_bf16 v[72:75], v[184:187], v[228:231], v[72:75]
	s_barrier
	s_add_i32 s31, s31, s33
	s_mov_b32 m0, s31
	ds_read_b128 v[188:191], v147 offset:16384
	ds_read_b128 v[192:195], v147 offset:18432
	ds_read_b128 v[196:199], v148 offset:16384
	ds_read_b128 v[200:203], v148 offset:18432
	ds_read_b128 v[204:207], v147 offset:20480
	ds_read_b128 v[208:211], v147 offset:22528
	ds_read_b128 v[224:227], v148 offset:20480
	ds_read_b128 v[228:231], v148 offset:22528
	global_load_lds_dwordx4 v34, s[28:29]
	s_add_i32 m0, s31, 0x2000
	s_add_u32 s54, s28, 0x80000
	s_addc_u32 s55, s29, 0
	s_add_i32 s31, s56, s33
	global_load_lds_dwordx4 v140, s[28:29]
	s_mov_b32 m0, s31
	s_nop 0
	global_load_lds_dwordx4 v34, s[54:55]
	s_add_i32 m0, s31, 0x2000
	s_nop 0
	global_load_lds_dwordx4 v140, s[54:55]
	s_mov_b32 m0, s34
	s_nop 0
	global_load_lds_dwordx4 v144, s[42:43]
	s_mov_b32 m0, s35
	s_nop 0
	global_load_lds_dwordx4 v142, s[42:43]
	s_nop 0
	s_waitcnt vmcnt(8)
	s_waitcnt lgkmcnt(0)
	s_barrier
	v_mfma_f32_16x16x32_bf16 v[60:63], v[150:153], v[188:191], 0
	v_mfma_f32_16x16x32_bf16 v[52:55], v[158:161], v[188:191], 0
	v_mfma_f32_16x16x32_bf16 v[44:47], v[150:153], v[192:195], 0
	v_mfma_f32_16x16x32_bf16 v[36:39], v[158:161], v[192:195], 0
	v_mfma_f32_16x16x32_bf16 v[26:29], v[150:153], v[204:207], 0
	v_mfma_f32_16x16x32_bf16 v[18:21], v[158:161], v[204:207], 0
	v_mfma_f32_16x16x32_bf16 v[10:13], v[150:153], v[208:211], 0
	v_mfma_f32_16x16x32_bf16 v[6:9], v[158:161], v[208:211], 0
	v_mfma_f32_16x16x32_bf16 v[60:63], v[154:157], v[196:199], v[60:63]
	v_mfma_f32_16x16x32_bf16 v[52:55], v[162:165], v[196:199], v[52:55]
	v_mfma_f32_16x16x32_bf16 v[44:47], v[154:157], v[200:203], v[44:47]
	v_mfma_f32_16x16x32_bf16 v[36:39], v[162:165], v[200:203], v[36:39]
	v_mfma_f32_16x16x32_bf16 v[26:29], v[154:157], v[224:227], v[26:29]
	v_mfma_f32_16x16x32_bf16 v[18:21], v[162:165], v[224:227], v[18:21]
	v_mfma_f32_16x16x32_bf16 v[10:13], v[154:157], v[228:231], v[10:13]
	v_mfma_f32_16x16x32_bf16 v[6:9], v[162:165], v[228:231], v[6:9]
	v_mfma_f32_16x16x32_bf16 v[64:67], v[166:169], v[188:191], 0
	v_mfma_f32_16x16x32_bf16 v[56:59], v[174:177], v[188:191], 0
	v_mfma_f32_16x16x32_bf16 v[48:51], v[166:169], v[192:195], 0
	v_mfma_f32_16x16x32_bf16 v[40:43], v[174:177], v[192:195], 0
	v_mfma_f32_16x16x32_bf16 v[30:33], v[166:169], v[204:207], 0
	v_mfma_f32_16x16x32_bf16 v[22:25], v[174:177], v[204:207], 0
	v_mfma_f32_16x16x32_bf16 v[14:17], v[166:169], v[208:211], 0
	v_mfma_f32_16x16x32_bf16 v[2:5], v[174:177], v[208:211], 0
	v_mfma_f32_16x16x32_bf16 v[64:67], v[170:173], v[196:199], v[64:67]
	v_mfma_f32_16x16x32_bf16 v[56:59], v[184:187], v[196:199], v[56:59]
	v_mfma_f32_16x16x32_bf16 v[48:51], v[170:173], v[200:203], v[48:51]
	v_mfma_f32_16x16x32_bf16 v[40:43], v[184:187], v[200:203], v[40:43]
	v_mfma_f32_16x16x32_bf16 v[30:33], v[170:173], v[224:227], v[30:33]
	v_mfma_f32_16x16x32_bf16 v[22:25], v[184:187], v[224:227], v[22:25]
	v_mfma_f32_16x16x32_bf16 v[14:17], v[170:173], v[228:231], v[14:17]
	v_mfma_f32_16x16x32_bf16 v[2:5], v[184:187], v[228:231], v[2:5]
	s_barrier
	s_add_i32 s31, 0, 0x18000
	ds_read_b128 v[150:153], v1 offset:32768
	ds_read_b128 v[154:157], v146 offset:32768
	s_add_i32 s54, 0, 0x1c000
	ds_read_b128 v[158:161], v1 offset:34816
	ds_read_b128 v[162:165], v146 offset:34816
	ds_read_b128 v[166:169], v1 offset:49152
	ds_read_b128 v[170:173], v146 offset:49152
	ds_read_b128 v[174:177], v1 offset:51200
	ds_read_b128 v[184:187], v146 offset:51200
	s_mov_b64 s[100:101], s[42:43]
	s_add_u32 s42, s42, 0x80000
	s_addc_u32 s43, s43, 0
	s_mov_b32 m0, s44
	ds_read_b128 v[188:191], v147 offset:32768
	ds_read_b128 v[192:195], v147 offset:34816
	ds_read_b128 v[196:199], v148 offset:32768
	ds_read_b128 v[200:203], v148 offset:34816
	ds_read_b128 v[204:207], v147 offset:36864
	ds_read_b128 v[208:211], v147 offset:38912
	ds_read_b128 v[224:227], v148 offset:36864
	ds_read_b128 v[228:231], v148 offset:38912
	global_load_lds_dwordx4 v144, s[42:43]
	s_mov_b32 m0, s45
	s_nop 0
	global_load_lds_dwordx4 v142, s[42:43]
	s_nop 0
	s_waitcnt vmcnt(8)
	s_waitcnt lgkmcnt(0)
	s_barrier
	v_mfma_f32_16x16x32_bf16 v[132:135], v[150:153], v[188:191], v[132:135]
	v_mfma_f32_16x16x32_bf16 v[124:127], v[158:161], v[188:191], v[124:127]
	v_mfma_f32_16x16x32_bf16 v[108:111], v[150:153], v[192:195], v[108:111]
	v_mfma_f32_16x16x32_bf16 v[100:103], v[158:161], v[192:195], v[100:103]
	v_mfma_f32_16x16x32_bf16 v[92:95], v[150:153], v[204:207], v[92:95]
	v_mfma_f32_16x16x32_bf16 v[84:87], v[158:161], v[204:207], v[84:87]
	v_mfma_f32_16x16x32_bf16 v[76:79], v[150:153], v[208:211], v[76:79]
	v_mfma_f32_16x16x32_bf16 v[68:71], v[158:161], v[208:211], v[68:71]
	v_mfma_f32_16x16x32_bf16 v[132:135], v[154:157], v[196:199], v[132:135]
	v_mfma_f32_16x16x32_bf16 v[124:127], v[162:165], v[196:199], v[124:127]
	v_mfma_f32_16x16x32_bf16 v[108:111], v[154:157], v[200:203], v[108:111]
	v_mfma_f32_16x16x32_bf16 v[100:103], v[162:165], v[200:203], v[100:103]
	v_mfma_f32_16x16x32_bf16 v[92:95], v[154:157], v[224:227], v[92:95]
	v_mfma_f32_16x16x32_bf16 v[84:87], v[162:165], v[224:227], v[84:87]
	v_mfma_f32_16x16x32_bf16 v[76:79], v[154:157], v[228:231], v[76:79]
	v_mfma_f32_16x16x32_bf16 v[68:71], v[162:165], v[228:231], v[68:71]
	v_mfma_f32_16x16x32_bf16 v[136:139], v[166:169], v[188:191], v[136:139]
	v_mfma_f32_16x16x32_bf16 v[128:131], v[174:177], v[188:191], v[128:131]
	v_mfma_f32_16x16x32_bf16 v[112:115], v[166:169], v[192:195], v[112:115]
	v_mfma_f32_16x16x32_bf16 v[104:107], v[174:177], v[192:195], v[104:107]
	v_mfma_f32_16x16x32_bf16 v[96:99], v[166:169], v[204:207], v[96:99]
	v_mfma_f32_16x16x32_bf16 v[88:91], v[174:177], v[204:207], v[88:91]
	v_mfma_f32_16x16x32_bf16 v[80:83], v[166:169], v[208:211], v[80:83]
	v_mfma_f32_16x16x32_bf16 v[72:75], v[174:177], v[208:211], v[72:75]
	v_mfma_f32_16x16x32_bf16 v[136:139], v[170:173], v[196:199], v[136:139]
	v_mfma_f32_16x16x32_bf16 v[128:131], v[184:187], v[196:199], v[128:131]
	v_mfma_f32_16x16x32_bf16 v[112:115], v[170:173], v[200:203], v[112:115]
	v_mfma_f32_16x16x32_bf16 v[104:107], v[184:187], v[200:203], v[104:107]
	v_mfma_f32_16x16x32_bf16 v[96:99], v[170:173], v[224:227], v[96:99]
	v_mfma_f32_16x16x32_bf16 v[88:91], v[184:187], v[224:227], v[88:91]
	v_mfma_f32_16x16x32_bf16 v[80:83], v[170:173], v[228:231], v[80:83]
	v_mfma_f32_16x16x32_bf16 v[72:75], v[184:187], v[228:231], v[72:75]
	s_barrier
	s_add_i32 s31, s31, s33
	s_add_i32 m0, s31, 0xffffff80
	ds_read_b128 v[188:191], v147 offset:49152
	ds_read_b128 v[192:195], v147 offset:51200
	ds_read_b128 v[196:199], v148 offset:49152
	ds_read_b128 v[200:203], v148 offset:51200
	ds_read_b128 v[204:207], v147 offset:53248
	ds_read_b128 v[208:211], v147 offset:55296
	ds_read_b128 v[224:227], v148 offset:53248
	ds_read_b128 v[228:231], v148 offset:55296
	global_load_lds_dwordx4 v34, s[28:29] offset:128
	s_add_i32 m0, s31, 0x1f80
	s_mov_b64 s[98:99], s[28:29]
	s_add_u32 s28, s28, 0x80080
	s_addc_u32 s29, s29, 0
	s_add_i32 s31, s54, s33
	global_load_lds_dwordx4 v140, s[98:99] offset:128
	s_mov_b32 m0, s31
	s_nop 0
	global_load_lds_dwordx4 v34, s[28:29]
	s_add_i32 m0, s31, 0x2000
	s_nop 0
	global_load_lds_dwordx4 v140, s[28:29]
	s_add_i32 m0, s48, 0xffffff80
	s_nop 0
	global_load_lds_dwordx4 v144, s[100:101] offset:128
	s_add_i32 m0, s49, 0xffffff80
	s_nop 0
	global_load_lds_dwordx4 v142, s[100:101] offset:128
	s_nop 0
	s_waitcnt vmcnt(8)
	s_waitcnt lgkmcnt(0)
	s_barrier
	v_mfma_f32_16x16x32_bf16 v[60:63], v[150:153], v[188:191], v[60:63]
	v_mfma_f32_16x16x32_bf16 v[52:55], v[158:161], v[188:191], v[52:55]
	v_mfma_f32_16x16x32_bf16 v[44:47], v[150:153], v[192:195], v[44:47]
	v_mfma_f32_16x16x32_bf16 v[36:39], v[158:161], v[192:195], v[36:39]
	v_mfma_f32_16x16x32_bf16 v[26:29], v[150:153], v[204:207], v[26:29]
	v_mfma_f32_16x16x32_bf16 v[18:21], v[158:161], v[204:207], v[18:21]
	v_mfma_f32_16x16x32_bf16 v[10:13], v[150:153], v[208:211], v[10:13]
	v_mfma_f32_16x16x32_bf16 v[6:9], v[158:161], v[208:211], v[6:9]
	v_mfma_f32_16x16x32_bf16 v[60:63], v[154:157], v[196:199], v[60:63]
	v_mfma_f32_16x16x32_bf16 v[52:55], v[162:165], v[196:199], v[52:55]
	v_mfma_f32_16x16x32_bf16 v[44:47], v[154:157], v[200:203], v[44:47]
	v_mfma_f32_16x16x32_bf16 v[36:39], v[162:165], v[200:203], v[36:39]
	v_mfma_f32_16x16x32_bf16 v[26:29], v[154:157], v[224:227], v[26:29]
	v_mfma_f32_16x16x32_bf16 v[18:21], v[162:165], v[224:227], v[18:21]
	v_mfma_f32_16x16x32_bf16 v[10:13], v[154:157], v[228:231], v[10:13]
	v_mfma_f32_16x16x32_bf16 v[6:9], v[162:165], v[228:231], v[6:9]
	v_mfma_f32_16x16x32_bf16 v[64:67], v[166:169], v[188:191], v[64:67]
	v_mfma_f32_16x16x32_bf16 v[56:59], v[174:177], v[188:191], v[56:59]
	v_mfma_f32_16x16x32_bf16 v[48:51], v[166:169], v[192:195], v[48:51]
	v_mfma_f32_16x16x32_bf16 v[40:43], v[174:177], v[192:195], v[40:43]
	v_mfma_f32_16x16x32_bf16 v[30:33], v[166:169], v[204:207], v[30:33]
	v_mfma_f32_16x16x32_bf16 v[22:25], v[174:177], v[204:207], v[22:25]
	v_mfma_f32_16x16x32_bf16 v[14:17], v[166:169], v[208:211], v[14:17]
	v_mfma_f32_16x16x32_bf16 v[2:5], v[174:177], v[208:211], v[2:5]
	v_mfma_f32_16x16x32_bf16 v[64:67], v[170:173], v[196:199], v[64:67]
	v_mfma_f32_16x16x32_bf16 v[56:59], v[184:187], v[196:199], v[56:59]
	v_mfma_f32_16x16x32_bf16 v[48:51], v[170:173], v[200:203], v[48:51]
	v_mfma_f32_16x16x32_bf16 v[40:43], v[184:187], v[200:203], v[40:43]
	v_mfma_f32_16x16x32_bf16 v[30:33], v[170:173], v[224:227], v[30:33]
	v_mfma_f32_16x16x32_bf16 v[22:25], v[184:187], v[224:227], v[22:25]
	v_mfma_f32_16x16x32_bf16 v[14:17], v[170:173], v[228:231], v[14:17]
	v_mfma_f32_16x16x32_bf16 v[2:5], v[184:187], v[228:231], v[2:5]
	s_barrier
	s_add_i32 s30, s30, 2
	s_add_u32 s8, s8, 0x100
	s_addc_u32 s9, s9, 0
	s_add_u32 s24, s24, 0x100
	s_addc_u32 s25, s25, 0
	s_cmp_gt_u32 s30, 29
	s_cbranch_scc1 .Lpeel_done_P6
.LBB0_1114:
	s_add_u32 s28, s8, 0xfff80080
	s_addc_u32 s29, s9, -1
	s_add_i32 s31, 0, 0x10000
	s_cmp_eq_u32 s30, 28
	s_cselect_b32 s43, s13, s29
	s_cselect_b32 s42, s19, s28
	ds_read_b128 v[150:153], v1
	ds_read_b128 v[154:157], v146
	s_cselect_b32 s29, s20, s25
	s_cselect_b32 s28, s21, s24
	s_add_i32 s56, 0, 0x14000
	ds_read_b128 v[158:161], v1 offset:2048
	ds_read_b128 v[162:165], v146 offset:2048
	ds_read_b128 v[166:169], v1 offset:16384
	ds_read_b128 v[170:173], v146 offset:16384
	ds_read_b128 v[174:177], v1 offset:18432
	ds_read_b128 v[184:187], v146 offset:18432
	s_add_i32 m0, s34, 0xc000
	ds_read_b128 v[188:191], v147
	ds_read_b128 v[192:195], v147 offset:2048
	ds_read_b128 v[196:199], v148
	ds_read_b128 v[200:203], v148 offset:2048
	ds_read_b128 v[204:207], v147 offset:4096
	ds_read_b128 v[208:211], v147 offset:6144
	ds_read_b128 v[224:227], v148 offset:4096
	ds_read_b128 v[228:231], v148 offset:6144
	global_load_lds_dwordx4 v144, s[8:9]
	s_add_i32 m0, s34, 0xe000
	s_nop 0
	global_load_lds_dwordx4 v142, s[8:9]
	s_waitcnt vmcnt(8)
	s_waitcnt lgkmcnt(0)
	s_barrier
	v_mfma_f32_16x16x32_bf16 v[132:135], v[150:153], v[188:191], v[132:135]
	v_mfma_f32_16x16x32_bf16 v[124:127], v[158:161], v[188:191], v[124:127]
	v_mfma_f32_16x16x32_bf16 v[108:111], v[150:153], v[192:195], v[108:111]
	v_mfma_f32_16x16x32_bf16 v[100:103], v[158:161], v[192:195], v[100:103]
	v_mfma_f32_16x16x32_bf16 v[92:95], v[150:153], v[204:207], v[92:95]
	v_mfma_f32_16x16x32_bf16 v[84:87], v[158:161], v[204:207], v[84:87]
	v_mfma_f32_16x16x32_bf16 v[76:79], v[150:153], v[208:211], v[76:79]
	v_mfma_f32_16x16x32_bf16 v[68:71], v[158:161], v[208:211], v[68:71]
	v_mfma_f32_16x16x32_bf16 v[132:135], v[154:157], v[196:199], v[132:135]
	v_mfma_f32_16x16x32_bf16 v[124:127], v[162:165], v[196:199], v[124:127]
	v_mfma_f32_16x16x32_bf16 v[108:111], v[154:157], v[200:203], v[108:111]
	v_mfma_f32_16x16x32_bf16 v[100:103], v[162:165], v[200:203], v[100:103]
	v_mfma_f32_16x16x32_bf16 v[92:95], v[154:157], v[224:227], v[92:95]
	v_mfma_f32_16x16x32_bf16 v[84:87], v[162:165], v[224:227], v[84:87]
	v_mfma_f32_16x16x32_bf16 v[76:79], v[154:157], v[228:231], v[76:79]
	v_mfma_f32_16x16x32_bf16 v[68:71], v[162:165], v[228:231], v[68:71]
	v_mfma_f32_16x16x32_bf16 v[136:139], v[166:169], v[188:191], v[136:139]
	v_mfma_f32_16x16x32_bf16 v[128:131], v[174:177], v[188:191], v[128:131]
	v_mfma_f32_16x16x32_bf16 v[112:115], v[166:169], v[192:195], v[112:115]
	v_mfma_f32_16x16x32_bf16 v[104:107], v[174:177], v[192:195], v[104:107]
	v_mfma_f32_16x16x32_bf16 v[96:99], v[166:169], v[204:207], v[96:99]
	v_mfma_f32_16x16x32_bf16 v[88:91], v[174:177], v[204:207], v[88:91]
	v_mfma_f32_16x16x32_bf16 v[80:83], v[166:169], v[208:211], v[80:83]
	v_mfma_f32_16x16x32_bf16 v[72:75], v[174:177], v[208:211], v[72:75]
	v_mfma_f32_16x16x32_bf16 v[136:139], v[170:173], v[196:199], v[136:139]
	v_mfma_f32_16x16x32_bf16 v[128:131], v[184:187], v[196:199], v[128:131]
	v_mfma_f32_16x16x32_bf16 v[112:115], v[170:173], v[200:203], v[112:115]
	v_mfma_f32_16x16x32_bf16 v[104:107], v[184:187], v[200:203], v[104:107]
	v_mfma_f32_16x16x32_bf16 v[96:99], v[170:173], v[224:227], v[96:99]
	v_mfma_f32_16x16x32_bf16 v[88:91], v[184:187], v[224:227], v[88:91]
	v_mfma_f32_16x16x32_bf16 v[80:83], v[170:173], v[228:231], v[80:83]
	v_mfma_f32_16x16x32_bf16 v[72:75], v[184:187], v[228:231], v[72:75]
	s_barrier
	s_add_i32 s31, s31, s33
	s_mov_b32 m0, s31
	ds_read_b128 v[188:191], v147 offset:16384
	ds_read_b128 v[192:195], v147 offset:18432
	ds_read_b128 v[196:199], v148 offset:16384
	ds_read_b128 v[200:203], v148 offset:18432
	ds_read_b128 v[204:207], v147 offset:20480
	ds_read_b128 v[208:211], v147 offset:22528
	ds_read_b128 v[224:227], v148 offset:20480
	ds_read_b128 v[228:231], v148 offset:22528
	global_load_lds_dwordx4 v34, s[28:29]
	s_add_i32 m0, s31, 0x2000
	s_add_u32 s54, s28, 0x80000
	s_addc_u32 s55, s29, 0
	s_add_i32 s31, s56, s33
	global_load_lds_dwordx4 v140, s[28:29]
	s_mov_b32 m0, s31
	s_nop 0
	global_load_lds_dwordx4 v34, s[54:55]
	s_add_i32 m0, s31, 0x2000
	s_nop 0
	global_load_lds_dwordx4 v140, s[54:55]
	s_mov_b32 m0, s34
	s_nop 0
	global_load_lds_dwordx4 v144, s[42:43]
	s_mov_b32 m0, s35
	s_nop 0
	global_load_lds_dwordx4 v142, s[42:43]
	s_nop 0
	s_waitcnt vmcnt(8)
	s_waitcnt lgkmcnt(0)
	s_barrier
	v_mfma_f32_16x16x32_bf16 v[60:63], v[150:153], v[188:191], v[60:63]
	v_mfma_f32_16x16x32_bf16 v[52:55], v[158:161], v[188:191], v[52:55]
	v_mfma_f32_16x16x32_bf16 v[44:47], v[150:153], v[192:195], v[44:47]
	v_mfma_f32_16x16x32_bf16 v[36:39], v[158:161], v[192:195], v[36:39]
	v_mfma_f32_16x16x32_bf16 v[26:29], v[150:153], v[204:207], v[26:29]
	v_mfma_f32_16x16x32_bf16 v[18:21], v[158:161], v[204:207], v[18:21]
	v_mfma_f32_16x16x32_bf16 v[10:13], v[150:153], v[208:211], v[10:13]
	v_mfma_f32_16x16x32_bf16 v[6:9], v[158:161], v[208:211], v[6:9]
	v_mfma_f32_16x16x32_bf16 v[60:63], v[154:157], v[196:199], v[60:63]
	v_mfma_f32_16x16x32_bf16 v[52:55], v[162:165], v[196:199], v[52:55]
	v_mfma_f32_16x16x32_bf16 v[44:47], v[154:157], v[200:203], v[44:47]
	v_mfma_f32_16x16x32_bf16 v[36:39], v[162:165], v[200:203], v[36:39]
	v_mfma_f32_16x16x32_bf16 v[26:29], v[154:157], v[224:227], v[26:29]
	v_mfma_f32_16x16x32_bf16 v[18:21], v[162:165], v[224:227], v[18:21]
	v_mfma_f32_16x16x32_bf16 v[10:13], v[154:157], v[228:231], v[10:13]
	v_mfma_f32_16x16x32_bf16 v[6:9], v[162:165], v[228:231], v[6:9]
	v_mfma_f32_16x16x32_bf16 v[64:67], v[166:169], v[188:191], v[64:67]
	v_mfma_f32_16x16x32_bf16 v[56:59], v[174:177], v[188:191], v[56:59]
	v_mfma_f32_16x16x32_bf16 v[48:51], v[166:169], v[192:195], v[48:51]
	v_mfma_f32_16x16x32_bf16 v[40:43], v[174:177], v[192:195], v[40:43]
	v_mfma_f32_16x16x32_bf16 v[30:33], v[166:169], v[204:207], v[30:33]
	v_mfma_f32_16x16x32_bf16 v[22:25], v[174:177], v[204:207], v[22:25]
	v_mfma_f32_16x16x32_bf16 v[14:17], v[166:169], v[208:211], v[14:17]
	v_mfma_f32_16x16x32_bf16 v[2:5], v[174:177], v[208:211], v[2:5]
	v_mfma_f32_16x16x32_bf16 v[64:67], v[170:173], v[196:199], v[64:67]
	v_mfma_f32_16x16x32_bf16 v[56:59], v[184:187], v[196:199], v[56:59]
	v_mfma_f32_16x16x32_bf16 v[48:51], v[170:173], v[200:203], v[48:51]
	v_mfma_f32_16x16x32_bf16 v[40:43], v[184:187], v[200:203], v[40:43]
	v_mfma_f32_16x16x32_bf16 v[30:33], v[170:173], v[224:227], v[30:33]
	v_mfma_f32_16x16x32_bf16 v[22:25], v[184:187], v[224:227], v[22:25]
	v_mfma_f32_16x16x32_bf16 v[14:17], v[170:173], v[228:231], v[14:17]
	v_mfma_f32_16x16x32_bf16 v[2:5], v[184:187], v[228:231], v[2:5]
	s_barrier
	s_add_i32 s31, 0, 0x18000
	ds_read_b128 v[150:153], v1 offset:32768
	ds_read_b128 v[154:157], v146 offset:32768
	s_add_i32 s54, 0, 0x1c000
	ds_read_b128 v[158:161], v1 offset:34816
	ds_read_b128 v[162:165], v146 offset:34816
	ds_read_b128 v[166:169], v1 offset:49152
	ds_read_b128 v[170:173], v146 offset:49152
	ds_read_b128 v[174:177], v1 offset:51200
	ds_read_b128 v[184:187], v146 offset:51200
	s_mov_b64 s[100:101], s[42:43]
	s_add_u32 s42, s42, 0x80000
	s_addc_u32 s43, s43, 0
	s_mov_b32 m0, s44
	ds_read_b128 v[188:191], v147 offset:32768
	ds_read_b128 v[192:195], v147 offset:34816
	ds_read_b128 v[196:199], v148 offset:32768
	ds_read_b128 v[200:203], v148 offset:34816
	ds_read_b128 v[204:207], v147 offset:36864
	ds_read_b128 v[208:211], v147 offset:38912
	ds_read_b128 v[224:227], v148 offset:36864
	ds_read_b128 v[228:231], v148 offset:38912
	global_load_lds_dwordx4 v144, s[42:43]
	s_mov_b32 m0, s45
	s_nop 0
	global_load_lds_dwordx4 v142, s[42:43]
	s_nop 0
	s_waitcnt vmcnt(8)
	s_waitcnt lgkmcnt(0)
	s_barrier
	v_mfma_f32_16x16x32_bf16 v[132:135], v[150:153], v[188:191], v[132:135]
	v_mfma_f32_16x16x32_bf16 v[124:127], v[158:161], v[188:191], v[124:127]
	v_mfma_f32_16x16x32_bf16 v[108:111], v[150:153], v[192:195], v[108:111]
	v_mfma_f32_16x16x32_bf16 v[100:103], v[158:161], v[192:195], v[100:103]
	v_mfma_f32_16x16x32_bf16 v[92:95], v[150:153], v[204:207], v[92:95]
	v_mfma_f32_16x16x32_bf16 v[84:87], v[158:161], v[204:207], v[84:87]
	v_mfma_f32_16x16x32_bf16 v[76:79], v[150:153], v[208:211], v[76:79]
	v_mfma_f32_16x16x32_bf16 v[68:71], v[158:161], v[208:211], v[68:71]
	v_mfma_f32_16x16x32_bf16 v[132:135], v[154:157], v[196:199], v[132:135]
	v_mfma_f32_16x16x32_bf16 v[124:127], v[162:165], v[196:199], v[124:127]
	v_mfma_f32_16x16x32_bf16 v[108:111], v[154:157], v[200:203], v[108:111]
	v_mfma_f32_16x16x32_bf16 v[100:103], v[162:165], v[200:203], v[100:103]
	v_mfma_f32_16x16x32_bf16 v[92:95], v[154:157], v[224:227], v[92:95]
	v_mfma_f32_16x16x32_bf16 v[84:87], v[162:165], v[224:227], v[84:87]
	v_mfma_f32_16x16x32_bf16 v[76:79], v[154:157], v[228:231], v[76:79]
	v_mfma_f32_16x16x32_bf16 v[68:71], v[162:165], v[228:231], v[68:71]
	v_mfma_f32_16x16x32_bf16 v[136:139], v[166:169], v[188:191], v[136:139]
	v_mfma_f32_16x16x32_bf16 v[128:131], v[174:177], v[188:191], v[128:131]
	v_mfma_f32_16x16x32_bf16 v[112:115], v[166:169], v[192:195], v[112:115]
	v_mfma_f32_16x16x32_bf16 v[104:107], v[174:177], v[192:195], v[104:107]
	v_mfma_f32_16x16x32_bf16 v[96:99], v[166:169], v[204:207], v[96:99]
	v_mfma_f32_16x16x32_bf16 v[88:91], v[174:177], v[204:207], v[88:91]
	v_mfma_f32_16x16x32_bf16 v[80:83], v[166:169], v[208:211], v[80:83]
	v_mfma_f32_16x16x32_bf16 v[72:75], v[174:177], v[208:211], v[72:75]
	v_mfma_f32_16x16x32_bf16 v[136:139], v[170:173], v[196:199], v[136:139]
	v_mfma_f32_16x16x32_bf16 v[128:131], v[184:187], v[196:199], v[128:131]
	v_mfma_f32_16x16x32_bf16 v[112:115], v[170:173], v[200:203], v[112:115]
	v_mfma_f32_16x16x32_bf16 v[104:107], v[184:187], v[200:203], v[104:107]
	v_mfma_f32_16x16x32_bf16 v[96:99], v[170:173], v[224:227], v[96:99]
	v_mfma_f32_16x16x32_bf16 v[88:91], v[184:187], v[224:227], v[88:91]
	v_mfma_f32_16x16x32_bf16 v[80:83], v[170:173], v[228:231], v[80:83]
	v_mfma_f32_16x16x32_bf16 v[72:75], v[184:187], v[228:231], v[72:75]
	s_barrier
	s_add_i32 s31, s31, s33
	s_add_i32 m0, s31, 0xffffff80
	ds_read_b128 v[188:191], v147 offset:49152
	ds_read_b128 v[192:195], v147 offset:51200
	ds_read_b128 v[196:199], v148 offset:49152
	ds_read_b128 v[200:203], v148 offset:51200
	ds_read_b128 v[204:207], v147 offset:53248
	ds_read_b128 v[208:211], v147 offset:55296
	ds_read_b128 v[224:227], v148 offset:53248
	ds_read_b128 v[228:231], v148 offset:55296
	global_load_lds_dwordx4 v34, s[28:29] offset:128
	s_add_i32 m0, s31, 0x1f80
	s_mov_b64 s[98:99], s[28:29]
	s_add_u32 s28, s28, 0x80080
	s_addc_u32 s29, s29, 0
	s_add_i32 s31, s54, s33
	global_load_lds_dwordx4 v140, s[98:99] offset:128
	s_mov_b32 m0, s31
	s_nop 0
	global_load_lds_dwordx4 v34, s[28:29]
	s_add_i32 m0, s31, 0x2000
	s_nop 0
	global_load_lds_dwordx4 v140, s[28:29]
	s_add_i32 m0, s48, 0xffffff80
	s_nop 0
	global_load_lds_dwordx4 v144, s[100:101] offset:128
	s_add_i32 m0, s49, 0xffffff80
	s_nop 0
	global_load_lds_dwordx4 v142, s[100:101] offset:128
	s_nop 0
	s_waitcnt vmcnt(8)
	s_waitcnt lgkmcnt(0)
	s_barrier
	v_mfma_f32_16x16x32_bf16 v[60:63], v[150:153], v[188:191], v[60:63]
	v_mfma_f32_16x16x32_bf16 v[52:55], v[158:161], v[188:191], v[52:55]
	v_mfma_f32_16x16x32_bf16 v[44:47], v[150:153], v[192:195], v[44:47]
	v_mfma_f32_16x16x32_bf16 v[36:39], v[158:161], v[192:195], v[36:39]
	v_mfma_f32_16x16x32_bf16 v[26:29], v[150:153], v[204:207], v[26:29]
	v_mfma_f32_16x16x32_bf16 v[18:21], v[158:161], v[204:207], v[18:21]
	v_mfma_f32_16x16x32_bf16 v[10:13], v[150:153], v[208:211], v[10:13]
	v_mfma_f32_16x16x32_bf16 v[6:9], v[158:161], v[208:211], v[6:9]
	v_mfma_f32_16x16x32_bf16 v[60:63], v[154:157], v[196:199], v[60:63]
	v_mfma_f32_16x16x32_bf16 v[52:55], v[162:165], v[196:199], v[52:55]
	v_mfma_f32_16x16x32_bf16 v[44:47], v[154:157], v[200:203], v[44:47]
	v_mfma_f32_16x16x32_bf16 v[36:39], v[162:165], v[200:203], v[36:39]
	v_mfma_f32_16x16x32_bf16 v[26:29], v[154:157], v[224:227], v[26:29]
	v_mfma_f32_16x16x32_bf16 v[18:21], v[162:165], v[224:227], v[18:21]
	v_mfma_f32_16x16x32_bf16 v[10:13], v[154:157], v[228:231], v[10:13]
	v_mfma_f32_16x16x32_bf16 v[6:9], v[162:165], v[228:231], v[6:9]
	v_mfma_f32_16x16x32_bf16 v[64:67], v[166:169], v[188:191], v[64:67]
	v_mfma_f32_16x16x32_bf16 v[56:59], v[174:177], v[188:191], v[56:59]
	v_mfma_f32_16x16x32_bf16 v[48:51], v[166:169], v[192:195], v[48:51]
	v_mfma_f32_16x16x32_bf16 v[40:43], v[174:177], v[192:195], v[40:43]
	v_mfma_f32_16x16x32_bf16 v[30:33], v[166:169], v[204:207], v[30:33]
	v_mfma_f32_16x16x32_bf16 v[22:25], v[174:177], v[204:207], v[22:25]
	v_mfma_f32_16x16x32_bf16 v[14:17], v[166:169], v[208:211], v[14:17]
	v_mfma_f32_16x16x32_bf16 v[2:5], v[174:177], v[208:211], v[2:5]
	v_mfma_f32_16x16x32_bf16 v[64:67], v[170:173], v[196:199], v[64:67]
	v_mfma_f32_16x16x32_bf16 v[56:59], v[184:187], v[196:199], v[56:59]
	v_mfma_f32_16x16x32_bf16 v[48:51], v[170:173], v[200:203], v[48:51]
	v_mfma_f32_16x16x32_bf16 v[40:43], v[184:187], v[200:203], v[40:43]
	v_mfma_f32_16x16x32_bf16 v[30:33], v[170:173], v[224:227], v[30:33]
	v_mfma_f32_16x16x32_bf16 v[22:25], v[184:187], v[224:227], v[22:25]
	v_mfma_f32_16x16x32_bf16 v[14:17], v[170:173], v[228:231], v[14:17]
	v_mfma_f32_16x16x32_bf16 v[2:5], v[184:187], v[228:231], v[2:5]
	s_barrier
	s_add_i32 s30, s30, 2
	s_add_u32 s8, s8, 0x100
	s_addc_u32 s9, s9, 0
	s_add_u32 s24, s24, 0x100
	s_addc_u32 s25, s25, 0
	s_cmp_gt_u32 s30, 29
	s_cbranch_scc0 .LBB0_1114

.LBB0_1194:
	s_add_u32 s8, s8, 0x160080
	s_addc_u32 s9, s9, 0
	s_add_u32 s20, s18, 0x100
	s_addc_u32 s21, s19, 0
	s_mov_b32 s24, -2
	v_readlane_b32 s35, v255, 20
	v_readlane_b32 s40, v255, 21
	v_readlane_b32 s41, v255, 22
	v_readlane_b32 s57, v255, 23
	s_mov_b64 s[58:59], 0x80
	s_add_u32 s18, s8, 0xffea0080
	s_addc_u32 s19, s9, -1
	s_add_i32 s25, 0, 0x10000
	s_cmpk_eq_i32 s24, 0x54
	s_cselect_b32 s23, s45, s19
	s_cselect_b32 s22, s44, s18
	s_cselect_b32 s19, s47, s21
	s_cselect_b32 s18, s46, s20
	s_add_i32 s34, 0, 0x14000
	ds_read_b128 v[138:141], v1
	ds_read_b128 v[142:145], v160
	ds_read_b128 v[146:149], v1 offset:2048
	ds_read_b128 v[150:153], v160 offset:2048
	ds_read_b128 v[154:157], v1 offset:16384
	ds_read_b128 v[164:167], v160 offset:16384
	ds_read_b128 v[168:171], v1 offset:18432
	ds_read_b128 v[172:175], v160 offset:18432
	s_add_i32 m0, s29, 0xc000
	ds_read_b128 v[176:179], v161
	ds_read_b128 v[184:187], v161 offset:2048
	ds_read_b128 v[188:191], v162
	ds_read_b128 v[192:195], v162 offset:2048
	ds_read_b128 v[196:199], v161 offset:4096
	ds_read_b128 v[200:203], v161 offset:6144
	ds_read_b128 v[204:207], v162 offset:4096
	ds_read_b128 v[208:211], v162 offset:6144
	global_load_lds_dwordx4 v136, s[8:9]
	s_add_i32 m0, s29, 0xe000
	s_nop 0
	global_load_lds_dwordx4 v134, s[8:9]
	s_nop 0
	s_waitcnt vmcnt(8)
	s_waitcnt lgkmcnt(0)
	s_barrier
	v_mfma_f32_16x16x32_bf16 v[128:131], v[138:141], v[176:179], 0
	v_mfma_f32_16x16x32_bf16 v[124:127], v[146:149], v[176:179], 0
	v_mfma_f32_16x16x32_bf16 v[112:115], v[138:141], v[184:187], 0
	v_mfma_f32_16x16x32_bf16 v[108:111], v[146:149], v[184:187], 0
	v_mfma_f32_16x16x32_bf16 v[96:99], v[138:141], v[196:199], 0
	v_mfma_f32_16x16x32_bf16 v[92:95], v[146:149], v[196:199], 0
	v_mfma_f32_16x16x32_bf16 v[80:83], v[138:141], v[200:203], 0
	v_mfma_f32_16x16x32_bf16 v[76:79], v[146:149], v[200:203], 0
	v_mfma_f32_16x16x32_bf16 v[128:131], v[142:145], v[188:191], v[128:131]
	v_mfma_f32_16x16x32_bf16 v[124:127], v[150:153], v[188:191], v[124:127]
	v_mfma_f32_16x16x32_bf16 v[112:115], v[142:145], v[192:195], v[112:115]
	v_mfma_f32_16x16x32_bf16 v[108:111], v[150:153], v[192:195], v[108:111]
	v_mfma_f32_16x16x32_bf16 v[96:99], v[142:145], v[204:207], v[96:99]
	v_mfma_f32_16x16x32_bf16 v[92:95], v[150:153], v[204:207], v[92:95]
	v_mfma_f32_16x16x32_bf16 v[80:83], v[142:145], v[208:211], v[80:83]
	v_mfma_f32_16x16x32_bf16 v[76:79], v[150:153], v[208:211], v[76:79]
	v_mfma_f32_16x16x32_bf16 v[120:123], v[154:157], v[176:179], 0
	v_mfma_f32_16x16x32_bf16 v[116:119], v[168:171], v[176:179], 0
	v_mfma_f32_16x16x32_bf16 v[104:107], v[154:157], v[184:187], 0
	v_mfma_f32_16x16x32_bf16 v[100:103], v[168:171], v[184:187], 0
	v_mfma_f32_16x16x32_bf16 v[88:91], v[154:157], v[196:199], 0
	v_mfma_f32_16x16x32_bf16 v[84:87], v[168:171], v[196:199], 0
	v_mfma_f32_16x16x32_bf16 v[72:75], v[154:157], v[200:203], 0
	v_mfma_f32_16x16x32_bf16 v[68:71], v[168:171], v[200:203], 0
	v_mfma_f32_16x16x32_bf16 v[120:123], v[164:167], v[188:191], v[120:123]
	v_mfma_f32_16x16x32_bf16 v[116:119], v[172:175], v[188:191], v[116:119]
	v_mfma_f32_16x16x32_bf16 v[104:107], v[164:167], v[192:195], v[104:107]
	v_mfma_f32_16x16x32_bf16 v[100:103], v[172:175], v[192:195], v[100:103]
	v_mfma_f32_16x16x32_bf16 v[88:91], v[164:167], v[204:207], v[88:91]
	v_mfma_f32_16x16x32_bf16 v[84:87], v[172:175], v[204:207], v[84:87]
	v_mfma_f32_16x16x32_bf16 v[72:75], v[164:167], v[208:211], v[72:75]
	v_mfma_f32_16x16x32_bf16 v[68:71], v[172:175], v[208:211], v[68:71]
	s_barrier
	s_add_i32 s25, s25, s28
	s_mov_b32 m0, s25
	ds_read_b128 v[176:179], v161 offset:16384
	ds_read_b128 v[184:187], v161 offset:18432
	ds_read_b128 v[188:191], v162 offset:16384
	ds_read_b128 v[192:195], v162 offset:18432
	ds_read_b128 v[196:199], v161 offset:20480
	ds_read_b128 v[200:203], v161 offset:22528
	ds_read_b128 v[204:207], v162 offset:20480
	ds_read_b128 v[208:211], v162 offset:22528
	global_load_lds_dwordx4 v34, s[18:19]
	s_add_i32 m0, s25, 0x2000
	s_add_u32 s30, s18, 0x160000
	s_addc_u32 s31, s19, 0
	s_add_i32 s25, s34, s28
	global_load_lds_dwordx4 v132, s[18:19]
	s_mov_b32 m0, s25
	s_nop 0
	global_load_lds_dwordx4 v34, s[30:31]
	s_add_i32 m0, s25, 0x2000
	s_nop 0
	global_load_lds_dwordx4 v132, s[30:31]
	s_mov_b32 m0, s29
	s_nop 0
	global_load_lds_dwordx4 v136, s[22:23]
	s_mov_b32 m0, s33
	s_nop 0
	global_load_lds_dwordx4 v134, s[22:23]
	s_nop 0
	s_waitcnt vmcnt(8)
	s_waitcnt lgkmcnt(0)
	s_barrier
	v_mfma_f32_16x16x32_bf16 v[64:67], v[138:141], v[176:179], 0
	v_mfma_f32_16x16x32_bf16 v[60:63], v[146:149], v[176:179], 0
	v_mfma_f32_16x16x32_bf16 v[48:51], v[138:141], v[184:187], 0
	v_mfma_f32_16x16x32_bf16 v[44:47], v[146:149], v[184:187], 0
	v_mfma_f32_16x16x32_bf16 v[30:33], v[138:141], v[196:199], 0
	v_mfma_f32_16x16x32_bf16 v[26:29], v[146:149], v[196:199], 0
	v_mfma_f32_16x16x32_bf16 v[14:17], v[138:141], v[200:203], 0
	v_mfma_f32_16x16x32_bf16 v[10:13], v[146:149], v[200:203], 0
	v_mfma_f32_16x16x32_bf16 v[64:67], v[142:145], v[188:191], v[64:67]
	v_mfma_f32_16x16x32_bf16 v[60:63], v[150:153], v[188:191], v[60:63]
	v_mfma_f32_16x16x32_bf16 v[48:51], v[142:145], v[192:195], v[48:51]
	v_mfma_f32_16x16x32_bf16 v[44:47], v[150:153], v[192:195], v[44:47]
	v_mfma_f32_16x16x32_bf16 v[30:33], v[142:145], v[204:207], v[30:33]
	v_mfma_f32_16x16x32_bf16 v[26:29], v[150:153], v[204:207], v[26:29]
	v_mfma_f32_16x16x32_bf16 v[14:17], v[142:145], v[208:211], v[14:17]
	v_mfma_f32_16x16x32_bf16 v[10:13], v[150:153], v[208:211], v[10:13]
	v_mfma_f32_16x16x32_bf16 v[56:59], v[154:157], v[176:179], 0
	v_mfma_f32_16x16x32_bf16 v[52:55], v[168:171], v[176:179], 0
	v_mfma_f32_16x16x32_bf16 v[40:43], v[154:157], v[184:187], 0
	v_mfma_f32_16x16x32_bf16 v[36:39], v[168:171], v[184:187], 0
	v_mfma_f32_16x16x32_bf16 v[22:25], v[154:157], v[196:199], 0
	v_mfma_f32_16x16x32_bf16 v[18:21], v[168:171], v[196:199], 0
	v_mfma_f32_16x16x32_bf16 v[6:9], v[154:157], v[200:203], 0
	v_mfma_f32_16x16x32_bf16 v[2:5], v[168:171], v[200:203], 0
	v_mfma_f32_16x16x32_bf16 v[56:59], v[164:167], v[188:191], v[56:59]
	v_mfma_f32_16x16x32_bf16 v[52:55], v[172:175], v[188:191], v[52:55]
	v_mfma_f32_16x16x32_bf16 v[40:43], v[164:167], v[192:195], v[40:43]
	v_mfma_f32_16x16x32_bf16 v[36:39], v[172:175], v[192:195], v[36:39]
	v_mfma_f32_16x16x32_bf16 v[22:25], v[164:167], v[204:207], v[22:25]
	v_mfma_f32_16x16x32_bf16 v[18:21], v[172:175], v[204:207], v[18:21]
	v_mfma_f32_16x16x32_bf16 v[6:9], v[164:167], v[208:211], v[6:9]
	v_mfma_f32_16x16x32_bf16 v[2:5], v[172:175], v[208:211], v[2:5]
	s_barrier
	s_add_i32 s25, 0, 0x18000
	s_add_i32 s30, 0, 0x1c000
	ds_read_b128 v[138:141], v1 offset:32768
	ds_read_b128 v[142:145], v160 offset:32768
	ds_read_b128 v[146:149], v1 offset:34816
	ds_read_b128 v[150:153], v160 offset:34816
	ds_read_b128 v[154:157], v1 offset:49152
	ds_read_b128 v[164:167], v160 offset:49152
	ds_read_b128 v[168:171], v1 offset:51200
	ds_read_b128 v[172:175], v160 offset:51200
	s_mov_b64 s[100:101], s[22:23]
	s_add_u32 s22, s22, 0x160000
	s_addc_u32 s23, s23, 0
	s_mov_b32 m0, s48
	ds_read_b128 v[176:179], v161 offset:32768
	ds_read_b128 v[184:187], v161 offset:34816
	ds_read_b128 v[188:191], v162 offset:32768
	ds_read_b128 v[192:195], v162 offset:34816
	ds_read_b128 v[196:199], v161 offset:36864
	ds_read_b128 v[200:203], v161 offset:38912
	ds_read_b128 v[204:207], v162 offset:36864
	ds_read_b128 v[208:211], v162 offset:38912
	global_load_lds_dwordx4 v136, s[22:23]
	s_mov_b32 m0, s49
	s_nop 0
	global_load_lds_dwordx4 v134, s[22:23]
	s_nop 0
	s_waitcnt vmcnt(8)
	s_waitcnt lgkmcnt(0)
	s_barrier
	v_mfma_f32_16x16x32_bf16 v[128:131], v[138:141], v[176:179], v[128:131]
	v_mfma_f32_16x16x32_bf16 v[124:127], v[146:149], v[176:179], v[124:127]
	v_mfma_f32_16x16x32_bf16 v[112:115], v[138:141], v[184:187], v[112:115]
	v_mfma_f32_16x16x32_bf16 v[108:111], v[146:149], v[184:187], v[108:111]
	v_mfma_f32_16x16x32_bf16 v[96:99], v[138:141], v[196:199], v[96:99]
	v_mfma_f32_16x16x32_bf16 v[92:95], v[146:149], v[196:199], v[92:95]
	v_mfma_f32_16x16x32_bf16 v[80:83], v[138:141], v[200:203], v[80:83]
	v_mfma_f32_16x16x32_bf16 v[76:79], v[146:149], v[200:203], v[76:79]
	v_mfma_f32_16x16x32_bf16 v[128:131], v[142:145], v[188:191], v[128:131]
	v_mfma_f32_16x16x32_bf16 v[124:127], v[150:153], v[188:191], v[124:127]
	v_mfma_f32_16x16x32_bf16 v[112:115], v[142:145], v[192:195], v[112:115]
	v_mfma_f32_16x16x32_bf16 v[108:111], v[150:153], v[192:195], v[108:111]
	v_mfma_f32_16x16x32_bf16 v[96:99], v[142:145], v[204:207], v[96:99]
	v_mfma_f32_16x16x32_bf16 v[92:95], v[150:153], v[204:207], v[92:95]
	v_mfma_f32_16x16x32_bf16 v[80:83], v[142:145], v[208:211], v[80:83]
	v_mfma_f32_16x16x32_bf16 v[76:79], v[150:153], v[208:211], v[76:79]
	v_mfma_f32_16x16x32_bf16 v[120:123], v[154:157], v[176:179], v[120:123]
	v_mfma_f32_16x16x32_bf16 v[116:119], v[168:171], v[176:179], v[116:119]
	v_mfma_f32_16x16x32_bf16 v[104:107], v[154:157], v[184:187], v[104:107]
	v_mfma_f32_16x16x32_bf16 v[100:103], v[168:171], v[184:187], v[100:103]
	v_mfma_f32_16x16x32_bf16 v[88:91], v[154:157], v[196:199], v[88:91]
	v_mfma_f32_16x16x32_bf16 v[84:87], v[168:171], v[196:199], v[84:87]
	v_mfma_f32_16x16x32_bf16 v[72:75], v[154:157], v[200:203], v[72:75]
	v_mfma_f32_16x16x32_bf16 v[68:71], v[168:171], v[200:203], v[68:71]
	v_mfma_f32_16x16x32_bf16 v[120:123], v[164:167], v[188:191], v[120:123]
	v_mfma_f32_16x16x32_bf16 v[116:119], v[172:175], v[188:191], v[116:119]
	v_mfma_f32_16x16x32_bf16 v[104:107], v[164:167], v[192:195], v[104:107]
	v_mfma_f32_16x16x32_bf16 v[100:103], v[172:175], v[192:195], v[100:103]
	v_mfma_f32_16x16x32_bf16 v[88:91], v[164:167], v[204:207], v[88:91]
	v_mfma_f32_16x16x32_bf16 v[84:87], v[172:175], v[204:207], v[84:87]
	v_mfma_f32_16x16x32_bf16 v[72:75], v[164:167], v[208:211], v[72:75]
	v_mfma_f32_16x16x32_bf16 v[68:71], v[172:175], v[208:211], v[68:71]
	s_barrier
	s_add_i32 s22, s25, s28
	s_add_i32 m0, s22, 0xffffff80
	ds_read_b128 v[176:179], v161 offset:49152
	ds_read_b128 v[184:187], v161 offset:51200
	ds_read_b128 v[188:191], v162 offset:49152
	ds_read_b128 v[192:195], v162 offset:51200
	ds_read_b128 v[196:199], v161 offset:53248
	ds_read_b128 v[200:203], v161 offset:55296
	ds_read_b128 v[204:207], v162 offset:53248
	ds_read_b128 v[208:211], v162 offset:55296
	global_load_lds_dwordx4 v34, s[18:19] offset:128
	s_add_i32 m0, s22, 0x1f80
	s_mov_b64 s[98:99], s[18:19]
	s_add_u32 s18, s18, 0x160080
	s_addc_u32 s19, s19, 0
	s_add_i32 s22, s30, s28
	global_load_lds_dwordx4 v132, s[98:99] offset:128
	s_mov_b32 m0, s22
	s_nop 0
	global_load_lds_dwordx4 v34, s[18:19]
	s_add_i32 m0, s22, 0x2000
	s_nop 0
	global_load_lds_dwordx4 v132, s[18:19]
	s_add_i32 m0, s53, 0xffffff80
	s_nop 0
	global_load_lds_dwordx4 v136, s[100:101] offset:128
	s_add_i32 m0, s54, 0xffffff80
	s_nop 0
	global_load_lds_dwordx4 v134, s[100:101] offset:128
	s_nop 0
	s_waitcnt vmcnt(8)
	s_waitcnt lgkmcnt(0)
	s_barrier
	v_mfma_f32_16x16x32_bf16 v[64:67], v[138:141], v[176:179], v[64:67]
	v_mfma_f32_16x16x32_bf16 v[60:63], v[146:149], v[176:179], v[60:63]
	v_mfma_f32_16x16x32_bf16 v[48:51], v[138:141], v[184:187], v[48:51]
	v_mfma_f32_16x16x32_bf16 v[44:47], v[146:149], v[184:187], v[44:47]
	v_mfma_f32_16x16x32_bf16 v[30:33], v[138:141], v[196:199], v[30:33]
	v_mfma_f32_16x16x32_bf16 v[26:29], v[146:149], v[196:199], v[26:29]
	v_mfma_f32_16x16x32_bf16 v[14:17], v[138:141], v[200:203], v[14:17]
	v_mfma_f32_16x16x32_bf16 v[10:13], v[146:149], v[200:203], v[10:13]
	v_mfma_f32_16x16x32_bf16 v[64:67], v[142:145], v[188:191], v[64:67]
	v_mfma_f32_16x16x32_bf16 v[60:63], v[150:153], v[188:191], v[60:63]
	v_mfma_f32_16x16x32_bf16 v[48:51], v[142:145], v[192:195], v[48:51]
	v_mfma_f32_16x16x32_bf16 v[44:47], v[150:153], v[192:195], v[44:47]
	v_mfma_f32_16x16x32_bf16 v[30:33], v[142:145], v[204:207], v[30:33]
	v_mfma_f32_16x16x32_bf16 v[26:29], v[150:153], v[204:207], v[26:29]
	v_mfma_f32_16x16x32_bf16 v[14:17], v[142:145], v[208:211], v[14:17]
	v_mfma_f32_16x16x32_bf16 v[10:13], v[150:153], v[208:211], v[10:13]
	v_mfma_f32_16x16x32_bf16 v[56:59], v[154:157], v[176:179], v[56:59]
	v_mfma_f32_16x16x32_bf16 v[52:55], v[168:171], v[176:179], v[52:55]
	v_mfma_f32_16x16x32_bf16 v[40:43], v[154:157], v[184:187], v[40:43]
	v_mfma_f32_16x16x32_bf16 v[36:39], v[168:171], v[184:187], v[36:39]
	v_mfma_f32_16x16x32_bf16 v[22:25], v[154:157], v[196:199], v[22:25]
	v_mfma_f32_16x16x32_bf16 v[18:21], v[168:171], v[196:199], v[18:21]
	v_mfma_f32_16x16x32_bf16 v[6:9], v[154:157], v[200:203], v[6:9]
	v_mfma_f32_16x16x32_bf16 v[2:5], v[168:171], v[200:203], v[2:5]
	v_mfma_f32_16x16x32_bf16 v[56:59], v[164:167], v[188:191], v[56:59]
	v_mfma_f32_16x16x32_bf16 v[52:55], v[172:175], v[188:191], v[52:55]
	v_mfma_f32_16x16x32_bf16 v[40:43], v[164:167], v[192:195], v[40:43]
	v_mfma_f32_16x16x32_bf16 v[36:39], v[172:175], v[192:195], v[36:39]
	v_mfma_f32_16x16x32_bf16 v[22:25], v[164:167], v[204:207], v[22:25]
	v_mfma_f32_16x16x32_bf16 v[18:21], v[172:175], v[204:207], v[18:21]
	v_mfma_f32_16x16x32_bf16 v[6:9], v[164:167], v[208:211], v[6:9]
	v_mfma_f32_16x16x32_bf16 v[2:5], v[172:175], v[208:211], v[2:5]
	s_barrier
	s_add_i32 s24, s24, 2
	s_add_u32 s8, s8, 0x100
	s_addc_u32 s9, s9, 0
	s_add_u32 s20, s20, 0x100
	s_addc_u32 s21, s21, 0
	s_cmpk_gt_u32 s24, 0x55
	s_cbranch_scc1 .Lpeel_done_P7
.LBB0_1195:
	s_add_u32 s18, s8, 0xffea0080
	s_addc_u32 s19, s9, -1
	s_add_i32 s25, 0, 0x10000
	s_cmpk_eq_i32 s24, 0x54
	s_cselect_b32 s23, s45, s19
	s_cselect_b32 s22, s44, s18
	s_cselect_b32 s19, s47, s21
	s_cselect_b32 s18, s46, s20
	s_add_i32 s34, 0, 0x14000
	ds_read_b128 v[138:141], v1
	ds_read_b128 v[142:145], v160
	ds_read_b128 v[146:149], v1 offset:2048
	ds_read_b128 v[150:153], v160 offset:2048
	ds_read_b128 v[154:157], v1 offset:16384
	ds_read_b128 v[164:167], v160 offset:16384
	ds_read_b128 v[168:171], v1 offset:18432
	ds_read_b128 v[172:175], v160 offset:18432
	s_add_i32 m0, s29, 0xc000
	ds_read_b128 v[176:179], v161
	ds_read_b128 v[184:187], v161 offset:2048
	ds_read_b128 v[188:191], v162
	ds_read_b128 v[192:195], v162 offset:2048
	ds_read_b128 v[196:199], v161 offset:4096
	ds_read_b128 v[200:203], v161 offset:6144
	ds_read_b128 v[204:207], v162 offset:4096
	ds_read_b128 v[208:211], v162 offset:6144
	global_load_lds_dwordx4 v136, s[8:9]
	s_add_i32 m0, s29, 0xe000
	s_nop 0
	global_load_lds_dwordx4 v134, s[8:9]
	s_waitcnt vmcnt(8)
	s_waitcnt lgkmcnt(0)
	s_barrier
	v_mfma_f32_16x16x32_bf16 v[128:131], v[138:141], v[176:179], v[128:131]
	v_mfma_f32_16x16x32_bf16 v[124:127], v[146:149], v[176:179], v[124:127]
	v_mfma_f32_16x16x32_bf16 v[112:115], v[138:141], v[184:187], v[112:115]
	v_mfma_f32_16x16x32_bf16 v[108:111], v[146:149], v[184:187], v[108:111]
	v_mfma_f32_16x16x32_bf16 v[96:99], v[138:141], v[196:199], v[96:99]
	v_mfma_f32_16x16x32_bf16 v[92:95], v[146:149], v[196:199], v[92:95]
	v_mfma_f32_16x16x32_bf16 v[80:83], v[138:141], v[200:203], v[80:83]
	v_mfma_f32_16x16x32_bf16 v[76:79], v[146:149], v[200:203], v[76:79]
	v_mfma_f32_16x16x32_bf16 v[128:131], v[142:145], v[188:191], v[128:131]
	v_mfma_f32_16x16x32_bf16 v[124:127], v[150:153], v[188:191], v[124:127]
	v_mfma_f32_16x16x32_bf16 v[112:115], v[142:145], v[192:195], v[112:115]
	v_mfma_f32_16x16x32_bf16 v[108:111], v[150:153], v[192:195], v[108:111]
	v_mfma_f32_16x16x32_bf16 v[96:99], v[142:145], v[204:207], v[96:99]
	v_mfma_f32_16x16x32_bf16 v[92:95], v[150:153], v[204:207], v[92:95]
	v_mfma_f32_16x16x32_bf16 v[80:83], v[142:145], v[208:211], v[80:83]
	v_mfma_f32_16x16x32_bf16 v[76:79], v[150:153], v[208:211], v[76:79]
	v_mfma_f32_16x16x32_bf16 v[120:123], v[154:157], v[176:179], v[120:123]
	v_mfma_f32_16x16x32_bf16 v[116:119], v[168:171], v[176:179], v[116:119]
	v_mfma_f32_16x16x32_bf16 v[104:107], v[154:157], v[184:187], v[104:107]
	v_mfma_f32_16x16x32_bf16 v[100:103], v[168:171], v[184:187], v[100:103]
	v_mfma_f32_16x16x32_bf16 v[88:91], v[154:157], v[196:199], v[88:91]
	v_mfma_f32_16x16x32_bf16 v[84:87], v[168:171], v[196:199], v[84:87]
	v_mfma_f32_16x16x32_bf16 v[72:75], v[154:157], v[200:203], v[72:75]
	v_mfma_f32_16x16x32_bf16 v[68:71], v[168:171], v[200:203], v[68:71]
	v_mfma_f32_16x16x32_bf16 v[120:123], v[164:167], v[188:191], v[120:123]
	v_mfma_f32_16x16x32_bf16 v[116:119], v[172:175], v[188:191], v[116:119]
	v_mfma_f32_16x16x32_bf16 v[104:107], v[164:167], v[192:195], v[104:107]
	v_mfma_f32_16x16x32_bf16 v[100:103], v[172:175], v[192:195], v[100:103]
	v_mfma_f32_16x16x32_bf16 v[88:91], v[164:167], v[204:207], v[88:91]
	v_mfma_f32_16x16x32_bf16 v[84:87], v[172:175], v[204:207], v[84:87]
	v_mfma_f32_16x16x32_bf16 v[72:75], v[164:167], v[208:211], v[72:75]
	v_mfma_f32_16x16x32_bf16 v[68:71], v[172:175], v[208:211], v[68:71]
	s_barrier
	s_add_i32 s25, s25, s28
	s_mov_b32 m0, s25
	ds_read_b128 v[176:179], v161 offset:16384
	ds_read_b128 v[184:187], v161 offset:18432
	ds_read_b128 v[188:191], v162 offset:16384
	ds_read_b128 v[192:195], v162 offset:18432
	ds_read_b128 v[196:199], v161 offset:20480
	ds_read_b128 v[200:203], v161 offset:22528
	ds_read_b128 v[204:207], v162 offset:20480
	ds_read_b128 v[208:211], v162 offset:22528
	global_load_lds_dwordx4 v34, s[18:19]
	s_add_i32 m0, s25, 0x2000
	s_add_u32 s30, s18, 0x160000
	s_addc_u32 s31, s19, 0
	s_add_i32 s25, s34, s28
	global_load_lds_dwordx4 v132, s[18:19]
	s_mov_b32 m0, s25
	s_nop 0
	global_load_lds_dwordx4 v34, s[30:31]
	s_add_i32 m0, s25, 0x2000
	s_nop 0
	global_load_lds_dwordx4 v132, s[30:31]
	s_mov_b32 m0, s29
	s_nop 0
	global_load_lds_dwordx4 v136, s[22:23]
	s_mov_b32 m0, s33
	s_nop 0
	global_load_lds_dwordx4 v134, s[22:23]
	s_nop 0
	s_waitcnt vmcnt(8)
	s_waitcnt lgkmcnt(0)
	s_barrier
	v_mfma_f32_16x16x32_bf16 v[64:67], v[138:141], v[176:179], v[64:67]
	v_mfma_f32_16x16x32_bf16 v[60:63], v[146:149], v[176:179], v[60:63]
	v_mfma_f32_16x16x32_bf16 v[48:51], v[138:141], v[184:187], v[48:51]
	v_mfma_f32_16x16x32_bf16 v[44:47], v[146:149], v[184:187], v[44:47]
	v_mfma_f32_16x16x32_bf16 v[30:33], v[138:141], v[196:199], v[30:33]
	v_mfma_f32_16x16x32_bf16 v[26:29], v[146:149], v[196:199], v[26:29]
	v_mfma_f32_16x16x32_bf16 v[14:17], v[138:141], v[200:203], v[14:17]
	v_mfma_f32_16x16x32_bf16 v[10:13], v[146:149], v[200:203], v[10:13]
	v_mfma_f32_16x16x32_bf16 v[64:67], v[142:145], v[188:191], v[64:67]
	v_mfma_f32_16x16x32_bf16 v[60:63], v[150:153], v[188:191], v[60:63]
	v_mfma_f32_16x16x32_bf16 v[48:51], v[142:145], v[192:195], v[48:51]
	v_mfma_f32_16x16x32_bf16 v[44:47], v[150:153], v[192:195], v[44:47]
	v_mfma_f32_16x16x32_bf16 v[30:33], v[142:145], v[204:207], v[30:33]
	v_mfma_f32_16x16x32_bf16 v[26:29], v[150:153], v[204:207], v[26:29]
	v_mfma_f32_16x16x32_bf16 v[14:17], v[142:145], v[208:211], v[14:17]
	v_mfma_f32_16x16x32_bf16 v[10:13], v[150:153], v[208:211], v[10:13]
	v_mfma_f32_16x16x32_bf16 v[56:59], v[154:157], v[176:179], v[56:59]
	v_mfma_f32_16x16x32_bf16 v[52:55], v[168:171], v[176:179], v[52:55]
	v_mfma_f32_16x16x32_bf16 v[40:43], v[154:157], v[184:187], v[40:43]
	v_mfma_f32_16x16x32_bf16 v[36:39], v[168:171], v[184:187], v[36:39]
	v_mfma_f32_16x16x32_bf16 v[22:25], v[154:157], v[196:199], v[22:25]
	v_mfma_f32_16x16x32_bf16 v[18:21], v[168:171], v[196:199], v[18:21]
	v_mfma_f32_16x16x32_bf16 v[6:9], v[154:157], v[200:203], v[6:9]
	v_mfma_f32_16x16x32_bf16 v[2:5], v[168:171], v[200:203], v[2:5]
	v_mfma_f32_16x16x32_bf16 v[56:59], v[164:167], v[188:191], v[56:59]
	v_mfma_f32_16x16x32_bf16 v[52:55], v[172:175], v[188:191], v[52:55]
	v_mfma_f32_16x16x32_bf16 v[40:43], v[164:167], v[192:195], v[40:43]
	v_mfma_f32_16x16x32_bf16 v[36:39], v[172:175], v[192:195], v[36:39]
	v_mfma_f32_16x16x32_bf16 v[22:25], v[164:167], v[204:207], v[22:25]
	v_mfma_f32_16x16x32_bf16 v[18:21], v[172:175], v[204:207], v[18:21]
	v_mfma_f32_16x16x32_bf16 v[6:9], v[164:167], v[208:211], v[6:9]
	v_mfma_f32_16x16x32_bf16 v[2:5], v[172:175], v[208:211], v[2:5]
	s_barrier
	s_add_i32 s25, 0, 0x18000
	s_add_i32 s30, 0, 0x1c000
	ds_read_b128 v[138:141], v1 offset:32768
	ds_read_b128 v[142:145], v160 offset:32768
	ds_read_b128 v[146:149], v1 offset:34816
	ds_read_b128 v[150:153], v160 offset:34816
	ds_read_b128 v[154:157], v1 offset:49152
	ds_read_b128 v[164:167], v160 offset:49152
	ds_read_b128 v[168:171], v1 offset:51200
	ds_read_b128 v[172:175], v160 offset:51200
	s_mov_b64 s[100:101], s[22:23]
	s_add_u32 s22, s22, 0x160000
	s_addc_u32 s23, s23, 0
	s_mov_b32 m0, s48
	ds_read_b128 v[176:179], v161 offset:32768
	ds_read_b128 v[184:187], v161 offset:34816
	ds_read_b128 v[188:191], v162 offset:32768
	ds_read_b128 v[192:195], v162 offset:34816
	ds_read_b128 v[196:199], v161 offset:36864
	ds_read_b128 v[200:203], v161 offset:38912
	ds_read_b128 v[204:207], v162 offset:36864
	ds_read_b128 v[208:211], v162 offset:38912
	global_load_lds_dwordx4 v136, s[22:23]
	s_mov_b32 m0, s49
	s_nop 0
	global_load_lds_dwordx4 v134, s[22:23]
	s_nop 0
	s_waitcnt vmcnt(8)
	s_waitcnt lgkmcnt(0)
	s_barrier
	v_mfma_f32_16x16x32_bf16 v[128:131], v[138:141], v[176:179], v[128:131]
	v_mfma_f32_16x16x32_bf16 v[124:127], v[146:149], v[176:179], v[124:127]
	v_mfma_f32_16x16x32_bf16 v[112:115], v[138:141], v[184:187], v[112:115]
	v_mfma_f32_16x16x32_bf16 v[108:111], v[146:149], v[184:187], v[108:111]
	v_mfma_f32_16x16x32_bf16 v[96:99], v[138:141], v[196:199], v[96:99]
	v_mfma_f32_16x16x32_bf16 v[92:95], v[146:149], v[196:199], v[92:95]
	v_mfma_f32_16x16x32_bf16 v[80:83], v[138:141], v[200:203], v[80:83]
	v_mfma_f32_16x16x32_bf16 v[76:79], v[146:149], v[200:203], v[76:79]
	v_mfma_f32_16x16x32_bf16 v[128:131], v[142:145], v[188:191], v[128:131]
	v_mfma_f32_16x16x32_bf16 v[124:127], v[150:153], v[188:191], v[124:127]
	v_mfma_f32_16x16x32_bf16 v[112:115], v[142:145], v[192:195], v[112:115]
	v_mfma_f32_16x16x32_bf16 v[108:111], v[150:153], v[192:195], v[108:111]
	v_mfma_f32_16x16x32_bf16 v[96:99], v[142:145], v[204:207], v[96:99]
	v_mfma_f32_16x16x32_bf16 v[92:95], v[150:153], v[204:207], v[92:95]
	v_mfma_f32_16x16x32_bf16 v[80:83], v[142:145], v[208:211], v[80:83]
	v_mfma_f32_16x16x32_bf16 v[76:79], v[150:153], v[208:211], v[76:79]
	v_mfma_f32_16x16x32_bf16 v[120:123], v[154:157], v[176:179], v[120:123]
	v_mfma_f32_16x16x32_bf16 v[116:119], v[168:171], v[176:179], v[116:119]
	v_mfma_f32_16x16x32_bf16 v[104:107], v[154:157], v[184:187], v[104:107]
	v_mfma_f32_16x16x32_bf16 v[100:103], v[168:171], v[184:187], v[100:103]
	v_mfma_f32_16x16x32_bf16 v[88:91], v[154:157], v[196:199], v[88:91]
	v_mfma_f32_16x16x32_bf16 v[84:87], v[168:171], v[196:199], v[84:87]
	v_mfma_f32_16x16x32_bf16 v[72:75], v[154:157], v[200:203], v[72:75]
	v_mfma_f32_16x16x32_bf16 v[68:71], v[168:171], v[200:203], v[68:71]
	v_mfma_f32_16x16x32_bf16 v[120:123], v[164:167], v[188:191], v[120:123]
	v_mfma_f32_16x16x32_bf16 v[116:119], v[172:175], v[188:191], v[116:119]
	v_mfma_f32_16x16x32_bf16 v[104:107], v[164:167], v[192:195], v[104:107]
	v_mfma_f32_16x16x32_bf16 v[100:103], v[172:175], v[192:195], v[100:103]
	v_mfma_f32_16x16x32_bf16 v[88:91], v[164:167], v[204:207], v[88:91]
	v_mfma_f32_16x16x32_bf16 v[84:87], v[172:175], v[204:207], v[84:87]
	v_mfma_f32_16x16x32_bf16 v[72:75], v[164:167], v[208:211], v[72:75]
	v_mfma_f32_16x16x32_bf16 v[68:71], v[172:175], v[208:211], v[68:71]
	s_barrier
	s_add_i32 s22, s25, s28
	s_add_i32 m0, s22, 0xffffff80
	ds_read_b128 v[176:179], v161 offset:49152
	ds_read_b128 v[184:187], v161 offset:51200
	ds_read_b128 v[188:191], v162 offset:49152
	ds_read_b128 v[192:195], v162 offset:51200
	ds_read_b128 v[196:199], v161 offset:53248
	ds_read_b128 v[200:203], v161 offset:55296
	ds_read_b128 v[204:207], v162 offset:53248
	ds_read_b128 v[208:211], v162 offset:55296
	global_load_lds_dwordx4 v34, s[18:19] offset:128
	s_add_i32 m0, s22, 0x1f80
	s_mov_b64 s[98:99], s[18:19]
	s_add_u32 s18, s18, 0x160080
	s_addc_u32 s19, s19, 0
	s_add_i32 s22, s30, s28
	global_load_lds_dwordx4 v132, s[98:99] offset:128
	s_mov_b32 m0, s22
	s_nop 0
	global_load_lds_dwordx4 v34, s[18:19]
	s_add_i32 m0, s22, 0x2000
	s_nop 0
	global_load_lds_dwordx4 v132, s[18:19]
	s_add_i32 m0, s53, 0xffffff80
	s_nop 0
	global_load_lds_dwordx4 v136, s[100:101] offset:128
	s_add_i32 m0, s54, 0xffffff80
	s_nop 0
	global_load_lds_dwordx4 v134, s[100:101] offset:128
	s_nop 0
	s_waitcnt vmcnt(8)
	s_waitcnt lgkmcnt(0)
	s_barrier
	v_mfma_f32_16x16x32_bf16 v[64:67], v[138:141], v[176:179], v[64:67]
	v_mfma_f32_16x16x32_bf16 v[60:63], v[146:149], v[176:179], v[60:63]
	v_mfma_f32_16x16x32_bf16 v[48:51], v[138:141], v[184:187], v[48:51]
	v_mfma_f32_16x16x32_bf16 v[44:47], v[146:149], v[184:187], v[44:47]
	v_mfma_f32_16x16x32_bf16 v[30:33], v[138:141], v[196:199], v[30:33]
	v_mfma_f32_16x16x32_bf16 v[26:29], v[146:149], v[196:199], v[26:29]
	v_mfma_f32_16x16x32_bf16 v[14:17], v[138:141], v[200:203], v[14:17]
	v_mfma_f32_16x16x32_bf16 v[10:13], v[146:149], v[200:203], v[10:13]
	v_mfma_f32_16x16x32_bf16 v[64:67], v[142:145], v[188:191], v[64:67]
	v_mfma_f32_16x16x32_bf16 v[60:63], v[150:153], v[188:191], v[60:63]
	v_mfma_f32_16x16x32_bf16 v[48:51], v[142:145], v[192:195], v[48:51]
	v_mfma_f32_16x16x32_bf16 v[44:47], v[150:153], v[192:195], v[44:47]
	v_mfma_f32_16x16x32_bf16 v[30:33], v[142:145], v[204:207], v[30:33]
	v_mfma_f32_16x16x32_bf16 v[26:29], v[150:153], v[204:207], v[26:29]
	v_mfma_f32_16x16x32_bf16 v[14:17], v[142:145], v[208:211], v[14:17]
	v_mfma_f32_16x16x32_bf16 v[10:13], v[150:153], v[208:211], v[10:13]
	v_mfma_f32_16x16x32_bf16 v[56:59], v[154:157], v[176:179], v[56:59]
	v_mfma_f32_16x16x32_bf16 v[52:55], v[168:171], v[176:179], v[52:55]
	v_mfma_f32_16x16x32_bf16 v[40:43], v[154:157], v[184:187], v[40:43]
	v_mfma_f32_16x16x32_bf16 v[36:39], v[168:171], v[184:187], v[36:39]
	v_mfma_f32_16x16x32_bf16 v[22:25], v[154:157], v[196:199], v[22:25]
	v_mfma_f32_16x16x32_bf16 v[18:21], v[168:171], v[196:199], v[18:21]
	v_mfma_f32_16x16x32_bf16 v[6:9], v[154:157], v[200:203], v[6:9]
	v_mfma_f32_16x16x32_bf16 v[2:5], v[168:171], v[200:203], v[2:5]
	v_mfma_f32_16x16x32_bf16 v[56:59], v[164:167], v[188:191], v[56:59]
	v_mfma_f32_16x16x32_bf16 v[52:55], v[172:175], v[188:191], v[52:55]
	v_mfma_f32_16x16x32_bf16 v[40:43], v[164:167], v[192:195], v[40:43]
	v_mfma_f32_16x16x32_bf16 v[36:39], v[172:175], v[192:195], v[36:39]
	v_mfma_f32_16x16x32_bf16 v[22:25], v[164:167], v[204:207], v[22:25]
	v_mfma_f32_16x16x32_bf16 v[18:21], v[172:175], v[204:207], v[18:21]
	v_mfma_f32_16x16x32_bf16 v[6:9], v[164:167], v[208:211], v[6:9]
	v_mfma_f32_16x16x32_bf16 v[2:5], v[172:175], v[208:211], v[2:5]
	s_barrier
	s_add_i32 s24, s24, 2
	s_add_u32 s8, s8, 0x100
	s_addc_u32 s9, s9, 0
	s_add_u32 s20, s20, 0x100
	s_addc_u32 s21, s21, 0
	s_cmpk_gt_u32 s24, 0x55
	s_cbranch_scc0 .LBB0_1195
